# odd in-proj GEMM epilogue rewritten by hand as four straight-line activation paths selected once per tile (same arithmetic), on top of previous
# speedup vs baseline: 1.0112x; 1.0093x over previous
.LBB0_1875:
	s_ashr_i32 s31, s40, 4
	v_lshl_add_u32 v164, s34, 8, v140
	v_mov_b32_e32 v165, 0
	v_mov_b32_e32 v163, 0
	v_lshlrev_b64 v[166:167], 15, v[164:165]
	v_lshl_add_u64 v[166:167], s[14:15], 0, v[166:167]
	v_lshl_add_u64 v[166:167], v[162:163], 1, v[166:167]
	s_mov_b64 s[8:9], 0x80000
	s_cmp_lt_i32 s31, 1
	s_cbranch_scc1 .Lodd_t0
	s_cmp_eq_u32 s31, 1
	s_cbranch_scc1 .Lodd_t1
	s_cmp_eq_u32 s31, 2
	s_cbranch_scc1 .Lodd_t2
.Lodd_t3:
	v_mov_b32_e32 v164, v166
	v_mov_b32_e32 v165, v167
	v_mul_f32_e32 v244, 0xbfb8aa3b, v66
	v_mul_f32_e32 v245, 0xbfb8aa3b, v67
	v_mul_f32_e32 v246, 0xbfb8aa3b, v68
	v_mul_f32_e32 v247, 0xbfb8aa3b, v69
	v_mul_f32_e32 v248, 0xbfb8aa3b, v62
	v_mul_f32_e32 v249, 0xbfb8aa3b, v63
	v_mul_f32_e32 v250, 0xbfb8aa3b, v64
	v_mul_f32_e32 v251, 0xbfb8aa3b, v65
	v_exp_f32_e32 v244, v244
	v_exp_f32_e32 v245, v245
	v_exp_f32_e32 v246, v246
	v_exp_f32_e32 v247, v247
	v_exp_f32_e32 v248, v248
	v_exp_f32_e32 v249, v249
	v_exp_f32_e32 v250, v250
	v_exp_f32_e32 v251, v251
	v_add_f32_e32 v244, 1.0, v244
	v_add_f32_e32 v245, 1.0, v245
	v_add_f32_e32 v246, 1.0, v246
	v_add_f32_e32 v247, 1.0, v247
	v_add_f32_e32 v248, 1.0, v248
	v_add_f32_e32 v249, 1.0, v249
	v_add_f32_e32 v250, 1.0, v250
	v_add_f32_e32 v251, 1.0, v251
	v_rcp_f32_e32 v66, v244
	v_rcp_f32_e32 v67, v245
	v_rcp_f32_e32 v68, v246
	v_rcp_f32_e32 v69, v247
	v_rcp_f32_e32 v62, v248
	v_rcp_f32_e32 v63, v249
	v_rcp_f32_e32 v64, v250
	v_rcp_f32_e32 v65, v251
	s_nop 0
	v_cvt_pk_bf16_f32 v66, v66, v67
	v_cvt_pk_bf16_f32 v67, v68, v69
	v_cvt_pk_bf16_f32 v68, v62, v63
	v_cvt_pk_bf16_f32 v69, v64, v65
	global_store_dwordx4 v[164:165], v[66:69], off
	v_mul_f32_e32 v244, 0xbfb8aa3b, v42
	v_mul_f32_e32 v245, 0xbfb8aa3b, v43
	v_mul_f32_e32 v246, 0xbfb8aa3b, v44
	v_mul_f32_e32 v247, 0xbfb8aa3b, v45
	v_mul_f32_e32 v248, 0xbfb8aa3b, v34
	v_mul_f32_e32 v249, 0xbfb8aa3b, v35
	v_mul_f32_e32 v250, 0xbfb8aa3b, v36
	v_mul_f32_e32 v251, 0xbfb8aa3b, v37
	v_exp_f32_e32 v244, v244
	v_exp_f32_e32 v245, v245
	v_exp_f32_e32 v246, v246
	v_exp_f32_e32 v247, v247
	v_exp_f32_e32 v248, v248
	v_exp_f32_e32 v249, v249
	v_exp_f32_e32 v250, v250
	v_exp_f32_e32 v251, v251
	v_add_f32_e32 v244, 1.0, v244
	v_add_f32_e32 v245, 1.0, v245
	v_add_f32_e32 v246, 1.0, v246
	v_add_f32_e32 v247, 1.0, v247
	v_add_f32_e32 v248, 1.0, v248
	v_add_f32_e32 v249, 1.0, v249
	v_add_f32_e32 v250, 1.0, v250
	v_add_f32_e32 v251, 1.0, v251
	v_rcp_f32_e32 v42, v244
	v_rcp_f32_e32 v43, v245
	v_rcp_f32_e32 v44, v246
	v_rcp_f32_e32 v45, v247
	v_rcp_f32_e32 v34, v248
	v_rcp_f32_e32 v35, v249
	v_rcp_f32_e32 v36, v250
	v_rcp_f32_e32 v37, v251
	s_nop 0
	v_cvt_pk_bf16_f32 v42, v42, v43
	v_cvt_pk_bf16_f32 v43, v44, v45
	v_cvt_pk_bf16_f32 v44, v34, v35
	v_cvt_pk_bf16_f32 v45, v36, v37
	global_store_dwordx4 v[164:165], v[42:45], off offset:256
	v_lshl_add_u64 v[164:165], v[164:165], 0, s[8:9]
	v_mul_f32_e32 v244, 0xbfb8aa3b, v58
	v_mul_f32_e32 v245, 0xbfb8aa3b, v59
	v_mul_f32_e32 v246, 0xbfb8aa3b, v60
	v_mul_f32_e32 v247, 0xbfb8aa3b, v61
	v_mul_f32_e32 v248, 0xbfb8aa3b, v54
	v_mul_f32_e32 v249, 0xbfb8aa3b, v55
	v_mul_f32_e32 v250, 0xbfb8aa3b, v56
	v_mul_f32_e32 v251, 0xbfb8aa3b, v57
	v_exp_f32_e32 v244, v244
	v_exp_f32_e32 v245, v245
	v_exp_f32_e32 v246, v246
	v_exp_f32_e32 v247, v247
	v_exp_f32_e32 v248, v248
	v_exp_f32_e32 v249, v249
	v_exp_f32_e32 v250, v250
	v_exp_f32_e32 v251, v251
	v_add_f32_e32 v244, 1.0, v244
	v_add_f32_e32 v245, 1.0, v245
	v_add_f32_e32 v246, 1.0, v246
	v_add_f32_e32 v247, 1.0, v247
	v_add_f32_e32 v248, 1.0, v248
	v_add_f32_e32 v249, 1.0, v249
	v_add_f32_e32 v250, 1.0, v250
	v_add_f32_e32 v251, 1.0, v251
	v_rcp_f32_e32 v58, v244
	v_rcp_f32_e32 v59, v245
	v_rcp_f32_e32 v60, v246
	v_rcp_f32_e32 v61, v247
	v_rcp_f32_e32 v54, v248
	v_rcp_f32_e32 v55, v249
	v_rcp_f32_e32 v56, v250
	v_rcp_f32_e32 v57, v251
	s_nop 0
	v_cvt_pk_bf16_f32 v58, v58, v59
	v_cvt_pk_bf16_f32 v59, v60, v61
	v_cvt_pk_bf16_f32 v60, v54, v55
	v_cvt_pk_bf16_f32 v61, v56, v57
	global_store_dwordx4 v[164:165], v[58:61], off
	v_mul_f32_e32 v244, 0xbfb8aa3b, v26
	v_mul_f32_e32 v245, 0xbfb8aa3b, v27
	v_mul_f32_e32 v246, 0xbfb8aa3b, v28
	v_mul_f32_e32 v247, 0xbfb8aa3b, v29
	v_mul_f32_e32 v248, 0xbfb8aa3b, v22
	v_mul_f32_e32 v249, 0xbfb8aa3b, v23
	v_mul_f32_e32 v250, 0xbfb8aa3b, v24
	v_mul_f32_e32 v251, 0xbfb8aa3b, v25
	v_exp_f32_e32 v244, v244
	v_exp_f32_e32 v245, v245
	v_exp_f32_e32 v246, v246
	v_exp_f32_e32 v247, v247
	v_exp_f32_e32 v248, v248
	v_exp_f32_e32 v249, v249
	v_exp_f32_e32 v250, v250
	v_exp_f32_e32 v251, v251
	v_add_f32_e32 v244, 1.0, v244
	v_add_f32_e32 v245, 1.0, v245
	v_add_f32_e32 v246, 1.0, v246
	v_add_f32_e32 v247, 1.0, v247
	v_add_f32_e32 v248, 1.0, v248
	v_add_f32_e32 v249, 1.0, v249
	v_add_f32_e32 v250, 1.0, v250
	v_add_f32_e32 v251, 1.0, v251
	v_rcp_f32_e32 v26, v244
	v_rcp_f32_e32 v27, v245
	v_rcp_f32_e32 v28, v246
	v_rcp_f32_e32 v29, v247
	v_rcp_f32_e32 v22, v248
	v_rcp_f32_e32 v23, v249
	v_rcp_f32_e32 v24, v250
	v_rcp_f32_e32 v25, v251
	s_nop 0
	v_cvt_pk_bf16_f32 v26, v26, v27
	v_cvt_pk_bf16_f32 v27, v28, v29
	v_cvt_pk_bf16_f32 v28, v22, v23
	v_cvt_pk_bf16_f32 v29, v24, v25
	global_store_dwordx4 v[164:165], v[26:29], off offset:256
	v_lshl_add_u64 v[164:165], v[164:165], 0, s[8:9]
	v_mul_f32_e32 v244, 0xbfb8aa3b, v50
	v_mul_f32_e32 v245, 0xbfb8aa3b, v51
	v_mul_f32_e32 v246, 0xbfb8aa3b, v52
	v_mul_f32_e32 v247, 0xbfb8aa3b, v53
	v_mul_f32_e32 v248, 0xbfb8aa3b, v46
	v_mul_f32_e32 v249, 0xbfb8aa3b, v47
	v_mul_f32_e32 v250, 0xbfb8aa3b, v48
	v_mul_f32_e32 v251, 0xbfb8aa3b, v49
	v_exp_f32_e32 v244, v244
	v_exp_f32_e32 v245, v245
	v_exp_f32_e32 v246, v246
	v_exp_f32_e32 v247, v247
	v_exp_f32_e32 v248, v248
	v_exp_f32_e32 v249, v249
	v_exp_f32_e32 v250, v250
	v_exp_f32_e32 v251, v251
	v_add_f32_e32 v244, 1.0, v244
	v_add_f32_e32 v245, 1.0, v245
	v_add_f32_e32 v246, 1.0, v246
	v_add_f32_e32 v247, 1.0, v247
	v_add_f32_e32 v248, 1.0, v248
	v_add_f32_e32 v249, 1.0, v249
	v_add_f32_e32 v250, 1.0, v250
	v_add_f32_e32 v251, 1.0, v251
	v_rcp_f32_e32 v50, v244
	v_rcp_f32_e32 v51, v245
	v_rcp_f32_e32 v52, v246
	v_rcp_f32_e32 v53, v247
	v_rcp_f32_e32 v46, v248
	v_rcp_f32_e32 v47, v249
	v_rcp_f32_e32 v48, v250
	v_rcp_f32_e32 v49, v251
	s_nop 0
	v_cvt_pk_bf16_f32 v50, v50, v51
	v_cvt_pk_bf16_f32 v51, v52, v53
	v_cvt_pk_bf16_f32 v52, v46, v47
	v_cvt_pk_bf16_f32 v53, v48, v49
	global_store_dwordx4 v[164:165], v[50:53], off
	v_mul_f32_e32 v244, 0xbfb8aa3b, v18
	v_mul_f32_e32 v245, 0xbfb8aa3b, v19
	v_mul_f32_e32 v246, 0xbfb8aa3b, v20
	v_mul_f32_e32 v247, 0xbfb8aa3b, v21
	v_mul_f32_e32 v248, 0xbfb8aa3b, v14
	v_mul_f32_e32 v249, 0xbfb8aa3b, v15
	v_mul_f32_e32 v250, 0xbfb8aa3b, v16
	v_mul_f32_e32 v251, 0xbfb8aa3b, v17
	v_exp_f32_e32 v244, v244
	v_exp_f32_e32 v245, v245
	v_exp_f32_e32 v246, v246
	v_exp_f32_e32 v247, v247
	v_exp_f32_e32 v248, v248
	v_exp_f32_e32 v249, v249
	v_exp_f32_e32 v250, v250
	v_exp_f32_e32 v251, v251
	v_add_f32_e32 v244, 1.0, v244
	v_add_f32_e32 v245, 1.0, v245
	v_add_f32_e32 v246, 1.0, v246
	v_add_f32_e32 v247, 1.0, v247
	v_add_f32_e32 v248, 1.0, v248
	v_add_f32_e32 v249, 1.0, v249
	v_add_f32_e32 v250, 1.0, v250
	v_add_f32_e32 v251, 1.0, v251
	v_rcp_f32_e32 v18, v244
	v_rcp_f32_e32 v19, v245
	v_rcp_f32_e32 v20, v246
	v_rcp_f32_e32 v21, v247
	v_rcp_f32_e32 v14, v248
	v_rcp_f32_e32 v15, v249
	v_rcp_f32_e32 v16, v250
	v_rcp_f32_e32 v17, v251
	s_nop 0
	v_cvt_pk_bf16_f32 v18, v18, v19
	v_cvt_pk_bf16_f32 v19, v20, v21
	v_cvt_pk_bf16_f32 v20, v14, v15
	v_cvt_pk_bf16_f32 v21, v16, v17
	global_store_dwordx4 v[164:165], v[18:21], off offset:256
	v_lshl_add_u64 v[164:165], v[164:165], 0, s[8:9]
	v_mul_f32_e32 v244, 0xbfb8aa3b, v38
	v_mul_f32_e32 v245, 0xbfb8aa3b, v39
	v_mul_f32_e32 v246, 0xbfb8aa3b, v40
	v_mul_f32_e32 v247, 0xbfb8aa3b, v41
	v_mul_f32_e32 v248, 0xbfb8aa3b, v30
	v_mul_f32_e32 v249, 0xbfb8aa3b, v31
	v_mul_f32_e32 v250, 0xbfb8aa3b, v32
	v_mul_f32_e32 v251, 0xbfb8aa3b, v33
	v_exp_f32_e32 v244, v244
	v_exp_f32_e32 v245, v245
	v_exp_f32_e32 v246, v246
	v_exp_f32_e32 v247, v247
	v_exp_f32_e32 v248, v248
	v_exp_f32_e32 v249, v249
	v_exp_f32_e32 v250, v250
	v_exp_f32_e32 v251, v251
	v_add_f32_e32 v244, 1.0, v244
	v_add_f32_e32 v245, 1.0, v245
	v_add_f32_e32 v246, 1.0, v246
	v_add_f32_e32 v247, 1.0, v247
	v_add_f32_e32 v248, 1.0, v248
	v_add_f32_e32 v249, 1.0, v249
	v_add_f32_e32 v250, 1.0, v250
	v_add_f32_e32 v251, 1.0, v251
	v_rcp_f32_e32 v38, v244
	v_rcp_f32_e32 v39, v245
	v_rcp_f32_e32 v40, v246
	v_rcp_f32_e32 v41, v247
	v_rcp_f32_e32 v30, v248
	v_rcp_f32_e32 v31, v249
	v_rcp_f32_e32 v32, v250
	v_rcp_f32_e32 v33, v251
	s_nop 0
	v_cvt_pk_bf16_f32 v38, v38, v39
	v_cvt_pk_bf16_f32 v39, v40, v41
	v_cvt_pk_bf16_f32 v40, v30, v31
	v_cvt_pk_bf16_f32 v41, v32, v33
	global_store_dwordx4 v[164:165], v[38:41], off
	v_mul_f32_e32 v244, 0xbfb8aa3b, v10
	v_mul_f32_e32 v245, 0xbfb8aa3b, v11
	v_mul_f32_e32 v246, 0xbfb8aa3b, v12
	v_mul_f32_e32 v247, 0xbfb8aa3b, v13
	v_mul_f32_e32 v248, 0xbfb8aa3b, v6
	v_mul_f32_e32 v249, 0xbfb8aa3b, v7
	v_mul_f32_e32 v250, 0xbfb8aa3b, v8
	v_mul_f32_e32 v251, 0xbfb8aa3b, v9
	v_exp_f32_e32 v244, v244
	v_exp_f32_e32 v245, v245
	v_exp_f32_e32 v246, v246
	v_exp_f32_e32 v247, v247
	v_exp_f32_e32 v248, v248
	v_exp_f32_e32 v249, v249
	v_exp_f32_e32 v250, v250
	v_exp_f32_e32 v251, v251
	v_add_f32_e32 v244, 1.0, v244
	v_add_f32_e32 v245, 1.0, v245
	v_add_f32_e32 v246, 1.0, v246
	v_add_f32_e32 v247, 1.0, v247
	v_add_f32_e32 v248, 1.0, v248
	v_add_f32_e32 v249, 1.0, v249
	v_add_f32_e32 v250, 1.0, v250
	v_add_f32_e32 v251, 1.0, v251
	v_rcp_f32_e32 v10, v244
	v_rcp_f32_e32 v11, v245
	v_rcp_f32_e32 v12, v246
	v_rcp_f32_e32 v13, v247
	v_rcp_f32_e32 v6, v248
	v_rcp_f32_e32 v7, v249
	v_rcp_f32_e32 v8, v250
	v_rcp_f32_e32 v9, v251
	s_nop 0
	v_cvt_pk_bf16_f32 v10, v10, v11
	v_cvt_pk_bf16_f32 v11, v12, v13
	v_cvt_pk_bf16_f32 v12, v6, v7
	v_cvt_pk_bf16_f32 v13, v8, v9
	global_store_dwordx4 v[164:165], v[10:13], off offset:256
	v_lshl_add_u64 v[164:165], v[166:167], 0, s[22:23]
	v_mul_f32_e32 v244, 0xbfb8aa3b, v126
	v_mul_f32_e32 v245, 0xbfb8aa3b, v127
	v_mul_f32_e32 v246, 0xbfb8aa3b, v128
	v_mul_f32_e32 v247, 0xbfb8aa3b, v129
	v_mul_f32_e32 v248, 0xbfb8aa3b, v122
	v_mul_f32_e32 v249, 0xbfb8aa3b, v123
	v_mul_f32_e32 v250, 0xbfb8aa3b, v124
	v_mul_f32_e32 v251, 0xbfb8aa3b, v125
	v_exp_f32_e32 v244, v244
	v_exp_f32_e32 v245, v245
	v_exp_f32_e32 v246, v246
	v_exp_f32_e32 v247, v247
	v_exp_f32_e32 v248, v248
	v_exp_f32_e32 v249, v249
	v_exp_f32_e32 v250, v250
	v_exp_f32_e32 v251, v251
	v_add_f32_e32 v244, 1.0, v244
	v_add_f32_e32 v245, 1.0, v245
	v_add_f32_e32 v246, 1.0, v246
	v_add_f32_e32 v247, 1.0, v247
	v_add_f32_e32 v248, 1.0, v248
	v_add_f32_e32 v249, 1.0, v249
	v_add_f32_e32 v250, 1.0, v250
	v_add_f32_e32 v251, 1.0, v251
	v_rcp_f32_e32 v126, v244
	v_rcp_f32_e32 v127, v245
	v_rcp_f32_e32 v128, v246
	v_rcp_f32_e32 v129, v247
	v_rcp_f32_e32 v122, v248
	v_rcp_f32_e32 v123, v249
	v_rcp_f32_e32 v124, v250
	v_rcp_f32_e32 v125, v251
	s_nop 0
	v_cvt_pk_bf16_f32 v126, v126, v127
	v_cvt_pk_bf16_f32 v127, v128, v129
	v_cvt_pk_bf16_f32 v128, v122, v123
	v_cvt_pk_bf16_f32 v129, v124, v125
	global_store_dwordx4 v[164:165], v[126:129], off
	v_mul_f32_e32 v244, 0xbfb8aa3b, v118
	v_mul_f32_e32 v245, 0xbfb8aa3b, v119
	v_mul_f32_e32 v246, 0xbfb8aa3b, v120
	v_mul_f32_e32 v247, 0xbfb8aa3b, v121
	v_mul_f32_e32 v248, 0xbfb8aa3b, v114
	v_mul_f32_e32 v249, 0xbfb8aa3b, v115
	v_mul_f32_e32 v250, 0xbfb8aa3b, v116
	v_mul_f32_e32 v251, 0xbfb8aa3b, v117
	v_exp_f32_e32 v244, v244
	v_exp_f32_e32 v245, v245
	v_exp_f32_e32 v246, v246
	v_exp_f32_e32 v247, v247
	v_exp_f32_e32 v248, v248
	v_exp_f32_e32 v249, v249
	v_exp_f32_e32 v250, v250
	v_exp_f32_e32 v251, v251
	v_add_f32_e32 v244, 1.0, v244
	v_add_f32_e32 v245, 1.0, v245
	v_add_f32_e32 v246, 1.0, v246
	v_add_f32_e32 v247, 1.0, v247
	v_add_f32_e32 v248, 1.0, v248
	v_add_f32_e32 v249, 1.0, v249
	v_add_f32_e32 v250, 1.0, v250
	v_add_f32_e32 v251, 1.0, v251
	v_rcp_f32_e32 v118, v244
	v_rcp_f32_e32 v119, v245
	v_rcp_f32_e32 v120, v246
	v_rcp_f32_e32 v121, v247
	v_rcp_f32_e32 v114, v248
	v_rcp_f32_e32 v115, v249
	v_rcp_f32_e32 v116, v250
	v_rcp_f32_e32 v117, v251
	s_nop 0
	v_cvt_pk_bf16_f32 v118, v118, v119
	v_cvt_pk_bf16_f32 v119, v120, v121
	v_cvt_pk_bf16_f32 v120, v114, v115
	v_cvt_pk_bf16_f32 v121, v116, v117
	global_store_dwordx4 v[164:165], v[118:121], off offset:256
	v_lshl_add_u64 v[164:165], v[164:165], 0, s[8:9]
	v_mul_f32_e32 v244, 0xbfb8aa3b, v110
	v_mul_f32_e32 v245, 0xbfb8aa3b, v111
	v_mul_f32_e32 v246, 0xbfb8aa3b, v112
	v_mul_f32_e32 v247, 0xbfb8aa3b, v113
	v_mul_f32_e32 v248, 0xbfb8aa3b, v106
	v_mul_f32_e32 v249, 0xbfb8aa3b, v107
	v_mul_f32_e32 v250, 0xbfb8aa3b, v108
	v_mul_f32_e32 v251, 0xbfb8aa3b, v109
	v_exp_f32_e32 v244, v244
	v_exp_f32_e32 v245, v245
	v_exp_f32_e32 v246, v246
	v_exp_f32_e32 v247, v247
	v_exp_f32_e32 v248, v248
	v_exp_f32_e32 v249, v249
	v_exp_f32_e32 v250, v250
	v_exp_f32_e32 v251, v251
	v_add_f32_e32 v244, 1.0, v244
	v_add_f32_e32 v245, 1.0, v245
	v_add_f32_e32 v246, 1.0, v246
	v_add_f32_e32 v247, 1.0, v247
	v_add_f32_e32 v248, 1.0, v248
	v_add_f32_e32 v249, 1.0, v249
	v_add_f32_e32 v250, 1.0, v250
	v_add_f32_e32 v251, 1.0, v251
	v_rcp_f32_e32 v110, v244
	v_rcp_f32_e32 v111, v245
	v_rcp_f32_e32 v112, v246
	v_rcp_f32_e32 v113, v247
	v_rcp_f32_e32 v106, v248
	v_rcp_f32_e32 v107, v249
	v_rcp_f32_e32 v108, v250
	v_rcp_f32_e32 v109, v251
	s_nop 0
	v_cvt_pk_bf16_f32 v110, v110, v111
	v_cvt_pk_bf16_f32 v111, v112, v113
	v_cvt_pk_bf16_f32 v112, v106, v107
	v_cvt_pk_bf16_f32 v113, v108, v109
	global_store_dwordx4 v[164:165], v[110:113], off
	v_mul_f32_e32 v244, 0xbfb8aa3b, v102
	v_mul_f32_e32 v245, 0xbfb8aa3b, v103
	v_mul_f32_e32 v246, 0xbfb8aa3b, v104
	v_mul_f32_e32 v247, 0xbfb8aa3b, v105
	v_mul_f32_e32 v248, 0xbfb8aa3b, v98
	v_mul_f32_e32 v249, 0xbfb8aa3b, v99
	v_mul_f32_e32 v250, 0xbfb8aa3b, v100
	v_mul_f32_e32 v251, 0xbfb8aa3b, v101
	v_exp_f32_e32 v244, v244
	v_exp_f32_e32 v245, v245
	v_exp_f32_e32 v246, v246
	v_exp_f32_e32 v247, v247
	v_exp_f32_e32 v248, v248
	v_exp_f32_e32 v249, v249
	v_exp_f32_e32 v250, v250
	v_exp_f32_e32 v251, v251
	v_add_f32_e32 v244, 1.0, v244
	v_add_f32_e32 v245, 1.0, v245
	v_add_f32_e32 v246, 1.0, v246
	v_add_f32_e32 v247, 1.0, v247
	v_add_f32_e32 v248, 1.0, v248
	v_add_f32_e32 v249, 1.0, v249
	v_add_f32_e32 v250, 1.0, v250
	v_add_f32_e32 v251, 1.0, v251
	v_rcp_f32_e32 v102, v244
	v_rcp_f32_e32 v103, v245
	v_rcp_f32_e32 v104, v246
	v_rcp_f32_e32 v105, v247
	v_rcp_f32_e32 v98, v248
	v_rcp_f32_e32 v99, v249
	v_rcp_f32_e32 v100, v250
	v_rcp_f32_e32 v101, v251
	s_nop 0
	v_cvt_pk_bf16_f32 v102, v102, v103
	v_cvt_pk_bf16_f32 v103, v104, v105
	v_cvt_pk_bf16_f32 v104, v98, v99
	v_cvt_pk_bf16_f32 v105, v100, v101
	global_store_dwordx4 v[164:165], v[102:105], off offset:256
	v_lshl_add_u64 v[164:165], v[164:165], 0, s[8:9]
	v_mul_f32_e32 v244, 0xbfb8aa3b, v94
	v_mul_f32_e32 v245, 0xbfb8aa3b, v95
	v_mul_f32_e32 v246, 0xbfb8aa3b, v96
	v_mul_f32_e32 v247, 0xbfb8aa3b, v97
	v_mul_f32_e32 v248, 0xbfb8aa3b, v90
	v_mul_f32_e32 v249, 0xbfb8aa3b, v91
	v_mul_f32_e32 v250, 0xbfb8aa3b, v92
	v_mul_f32_e32 v251, 0xbfb8aa3b, v93
	v_exp_f32_e32 v244, v244
	v_exp_f32_e32 v245, v245
	v_exp_f32_e32 v246, v246
	v_exp_f32_e32 v247, v247
	v_exp_f32_e32 v248, v248
	v_exp_f32_e32 v249, v249
	v_exp_f32_e32 v250, v250
	v_exp_f32_e32 v251, v251
	v_add_f32_e32 v244, 1.0, v244
	v_add_f32_e32 v245, 1.0, v245
	v_add_f32_e32 v246, 1.0, v246
	v_add_f32_e32 v247, 1.0, v247
	v_add_f32_e32 v248, 1.0, v248
	v_add_f32_e32 v249, 1.0, v249
	v_add_f32_e32 v250, 1.0, v250
	v_add_f32_e32 v251, 1.0, v251
	v_rcp_f32_e32 v94, v244
	v_rcp_f32_e32 v95, v245
	v_rcp_f32_e32 v96, v246
	v_rcp_f32_e32 v97, v247
	v_rcp_f32_e32 v90, v248
	v_rcp_f32_e32 v91, v249
	v_rcp_f32_e32 v92, v250
	v_rcp_f32_e32 v93, v251
	s_nop 0
	v_cvt_pk_bf16_f32 v94, v94, v95
	v_cvt_pk_bf16_f32 v95, v96, v97
	v_cvt_pk_bf16_f32 v96, v90, v91
	v_cvt_pk_bf16_f32 v97, v92, v93
	global_store_dwordx4 v[164:165], v[94:97], off
	v_mul_f32_e32 v244, 0xbfb8aa3b, v86
	v_mul_f32_e32 v245, 0xbfb8aa3b, v87
	v_mul_f32_e32 v246, 0xbfb8aa3b, v88
	v_mul_f32_e32 v247, 0xbfb8aa3b, v89
	v_mul_f32_e32 v248, 0xbfb8aa3b, v82
	v_mul_f32_e32 v249, 0xbfb8aa3b, v83
	v_mul_f32_e32 v250, 0xbfb8aa3b, v84
	v_mul_f32_e32 v251, 0xbfb8aa3b, v85
	v_exp_f32_e32 v244, v244
	v_exp_f32_e32 v245, v245
	v_exp_f32_e32 v246, v246
	v_exp_f32_e32 v247, v247
	v_exp_f32_e32 v248, v248
	v_exp_f32_e32 v249, v249
	v_exp_f32_e32 v250, v250
	v_exp_f32_e32 v251, v251
	v_add_f32_e32 v244, 1.0, v244
	v_add_f32_e32 v245, 1.0, v245
	v_add_f32_e32 v246, 1.0, v246
	v_add_f32_e32 v247, 1.0, v247
	v_add_f32_e32 v248, 1.0, v248
	v_add_f32_e32 v249, 1.0, v249
	v_add_f32_e32 v250, 1.0, v250
	v_add_f32_e32 v251, 1.0, v251
	v_rcp_f32_e32 v86, v244
	v_rcp_f32_e32 v87, v245
	v_rcp_f32_e32 v88, v246
	v_rcp_f32_e32 v89, v247
	v_rcp_f32_e32 v82, v248
	v_rcp_f32_e32 v83, v249
	v_rcp_f32_e32 v84, v250
	v_rcp_f32_e32 v85, v251
	s_nop 0
	v_cvt_pk_bf16_f32 v86, v86, v87
	v_cvt_pk_bf16_f32 v87, v88, v89
	v_cvt_pk_bf16_f32 v88, v82, v83
	v_cvt_pk_bf16_f32 v89, v84, v85
	global_store_dwordx4 v[164:165], v[86:89], off offset:256
	v_lshl_add_u64 v[164:165], v[164:165], 0, s[8:9]
	v_mul_f32_e32 v244, 0xbfb8aa3b, v78
	v_mul_f32_e32 v245, 0xbfb8aa3b, v79
	v_mul_f32_e32 v246, 0xbfb8aa3b, v80
	v_mul_f32_e32 v247, 0xbfb8aa3b, v81
	v_mul_f32_e32 v248, 0xbfb8aa3b, v74
	v_mul_f32_e32 v249, 0xbfb8aa3b, v75
	v_mul_f32_e32 v250, 0xbfb8aa3b, v76
	v_mul_f32_e32 v251, 0xbfb8aa3b, v77
	v_exp_f32_e32 v244, v244
	v_exp_f32_e32 v245, v245
	v_exp_f32_e32 v246, v246
	v_exp_f32_e32 v247, v247
	v_exp_f32_e32 v248, v248
	v_exp_f32_e32 v249, v249
	v_exp_f32_e32 v250, v250
	v_exp_f32_e32 v251, v251
	v_add_f32_e32 v244, 1.0, v244
	v_add_f32_e32 v245, 1.0, v245
	v_add_f32_e32 v246, 1.0, v246
	v_add_f32_e32 v247, 1.0, v247
	v_add_f32_e32 v248, 1.0, v248
	v_add_f32_e32 v249, 1.0, v249
	v_add_f32_e32 v250, 1.0, v250
	v_add_f32_e32 v251, 1.0, v251
	v_rcp_f32_e32 v78, v244
	v_rcp_f32_e32 v79, v245
	v_rcp_f32_e32 v80, v246
	v_rcp_f32_e32 v81, v247
	v_rcp_f32_e32 v74, v248
	v_rcp_f32_e32 v75, v249
	v_rcp_f32_e32 v76, v250
	v_rcp_f32_e32 v77, v251
	s_nop 0
	v_cvt_pk_bf16_f32 v78, v78, v79
	v_cvt_pk_bf16_f32 v79, v80, v81
	v_cvt_pk_bf16_f32 v80, v74, v75
	v_cvt_pk_bf16_f32 v81, v76, v77
	global_store_dwordx4 v[164:165], v[78:81], off
	v_mul_f32_e32 v244, 0xbfb8aa3b, v70
	v_mul_f32_e32 v245, 0xbfb8aa3b, v71
	v_mul_f32_e32 v246, 0xbfb8aa3b, v72
	v_mul_f32_e32 v247, 0xbfb8aa3b, v73
	v_mul_f32_e32 v248, 0xbfb8aa3b, v2
	v_mul_f32_e32 v249, 0xbfb8aa3b, v3
	v_mul_f32_e32 v250, 0xbfb8aa3b, v4
	v_mul_f32_e32 v251, 0xbfb8aa3b, v5
	v_exp_f32_e32 v244, v244
	v_exp_f32_e32 v245, v245
	v_exp_f32_e32 v246, v246
	v_exp_f32_e32 v247, v247
	v_exp_f32_e32 v248, v248
	v_exp_f32_e32 v249, v249
	v_exp_f32_e32 v250, v250
	v_exp_f32_e32 v251, v251
	v_add_f32_e32 v244, 1.0, v244
	v_add_f32_e32 v245, 1.0, v245
	v_add_f32_e32 v246, 1.0, v246
	v_add_f32_e32 v247, 1.0, v247
	v_add_f32_e32 v248, 1.0, v248
	v_add_f32_e32 v249, 1.0, v249
	v_add_f32_e32 v250, 1.0, v250
	v_add_f32_e32 v251, 1.0, v251
	v_rcp_f32_e32 v70, v244
	v_rcp_f32_e32 v71, v245
	v_rcp_f32_e32 v72, v246
	v_rcp_f32_e32 v73, v247
	v_rcp_f32_e32 v2, v248
	v_rcp_f32_e32 v3, v249
	v_rcp_f32_e32 v4, v250
	v_rcp_f32_e32 v5, v251
	s_nop 0
	v_cvt_pk_bf16_f32 v70, v70, v71
	v_cvt_pk_bf16_f32 v71, v72, v73
	v_cvt_pk_bf16_f32 v72, v2, v3
	v_cvt_pk_bf16_f32 v73, v4, v5
	global_store_dwordx4 v[164:165], v[70:73], off offset:256
	s_branch .Lodd_done
.Lodd_t0:
	v_mov_b32_e32 v164, v166
	v_mov_b32_e32 v165, v167
	v_mul_f32_e32 v244, 0xbfb8aa3b, v66
	v_mul_f32_e32 v245, 0xbfb8aa3b, v67
	v_mul_f32_e32 v246, 0xbfb8aa3b, v68
	v_mul_f32_e32 v247, 0xbfb8aa3b, v69
	v_mul_f32_e32 v248, 0xbfb8aa3b, v62
	v_mul_f32_e32 v249, 0xbfb8aa3b, v63
	v_mul_f32_e32 v250, 0xbfb8aa3b, v64
	v_mul_f32_e32 v251, 0xbfb8aa3b, v65
	v_exp_f32_e32 v244, v244
	v_exp_f32_e32 v245, v245
	v_exp_f32_e32 v246, v246
	v_exp_f32_e32 v247, v247
	v_exp_f32_e32 v248, v248
	v_exp_f32_e32 v249, v249
	v_exp_f32_e32 v250, v250
	v_exp_f32_e32 v251, v251
	v_add_f32_e32 v244, 1.0, v244
	v_add_f32_e32 v245, 1.0, v245
	v_add_f32_e32 v246, 1.0, v246
	v_add_f32_e32 v247, 1.0, v247
	v_add_f32_e32 v248, 1.0, v248
	v_add_f32_e32 v249, 1.0, v249
	v_add_f32_e32 v250, 1.0, v250
	v_add_f32_e32 v251, 1.0, v251
	v_rcp_f32_e32 v244, v244
	v_rcp_f32_e32 v245, v245
	v_rcp_f32_e32 v246, v246
	v_rcp_f32_e32 v247, v247
	v_rcp_f32_e32 v248, v248
	v_rcp_f32_e32 v249, v249
	v_rcp_f32_e32 v250, v250
	v_rcp_f32_e32 v251, v251
	v_mul_f32_e32 v66, v66, v244
	v_mul_f32_e32 v67, v67, v245
	v_mul_f32_e32 v68, v68, v246
	v_mul_f32_e32 v69, v69, v247
	v_mul_f32_e32 v62, v62, v248
	v_mul_f32_e32 v63, v63, v249
	v_mul_f32_e32 v64, v64, v250
	v_mul_f32_e32 v65, v65, v251
	v_cvt_pk_bf16_f32 v66, v66, v67
	v_cvt_pk_bf16_f32 v67, v68, v69
	v_cvt_pk_bf16_f32 v68, v62, v63
	v_cvt_pk_bf16_f32 v69, v64, v65
	global_store_dwordx4 v[164:165], v[66:69], off
	v_mul_f32_e32 v244, 0xbfb8aa3b, v42
	v_mul_f32_e32 v245, 0xbfb8aa3b, v43
	v_mul_f32_e32 v246, 0xbfb8aa3b, v44
	v_mul_f32_e32 v247, 0xbfb8aa3b, v45
	v_mul_f32_e32 v248, 0xbfb8aa3b, v34
	v_mul_f32_e32 v249, 0xbfb8aa3b, v35
	v_mul_f32_e32 v250, 0xbfb8aa3b, v36
	v_mul_f32_e32 v251, 0xbfb8aa3b, v37
	v_exp_f32_e32 v244, v244
	v_exp_f32_e32 v245, v245
	v_exp_f32_e32 v246, v246
	v_exp_f32_e32 v247, v247
	v_exp_f32_e32 v248, v248
	v_exp_f32_e32 v249, v249
	v_exp_f32_e32 v250, v250
	v_exp_f32_e32 v251, v251
	v_add_f32_e32 v244, 1.0, v244
	v_add_f32_e32 v245, 1.0, v245
	v_add_f32_e32 v246, 1.0, v246
	v_add_f32_e32 v247, 1.0, v247
	v_add_f32_e32 v248, 1.0, v248
	v_add_f32_e32 v249, 1.0, v249
	v_add_f32_e32 v250, 1.0, v250
	v_add_f32_e32 v251, 1.0, v251
	v_rcp_f32_e32 v244, v244
	v_rcp_f32_e32 v245, v245
	v_rcp_f32_e32 v246, v246
	v_rcp_f32_e32 v247, v247
	v_rcp_f32_e32 v248, v248
	v_rcp_f32_e32 v249, v249
	v_rcp_f32_e32 v250, v250
	v_rcp_f32_e32 v251, v251
	v_mul_f32_e32 v42, v42, v244
	v_mul_f32_e32 v43, v43, v245
	v_mul_f32_e32 v44, v44, v246
	v_mul_f32_e32 v45, v45, v247
	v_mul_f32_e32 v34, v34, v248
	v_mul_f32_e32 v35, v35, v249
	v_mul_f32_e32 v36, v36, v250
	v_mul_f32_e32 v37, v37, v251
	v_cvt_pk_bf16_f32 v42, v42, v43
	v_cvt_pk_bf16_f32 v43, v44, v45
	v_cvt_pk_bf16_f32 v44, v34, v35
	v_cvt_pk_bf16_f32 v45, v36, v37
	global_store_dwordx4 v[164:165], v[42:45], off offset:256
	v_lshl_add_u64 v[164:165], v[164:165], 0, s[8:9]
	v_mul_f32_e32 v244, 0xbfb8aa3b, v58
	v_mul_f32_e32 v245, 0xbfb8aa3b, v59
	v_mul_f32_e32 v246, 0xbfb8aa3b, v60
	v_mul_f32_e32 v247, 0xbfb8aa3b, v61
	v_mul_f32_e32 v248, 0xbfb8aa3b, v54
	v_mul_f32_e32 v249, 0xbfb8aa3b, v55
	v_mul_f32_e32 v250, 0xbfb8aa3b, v56
	v_mul_f32_e32 v251, 0xbfb8aa3b, v57
	v_exp_f32_e32 v244, v244
	v_exp_f32_e32 v245, v245
	v_exp_f32_e32 v246, v246
	v_exp_f32_e32 v247, v247
	v_exp_f32_e32 v248, v248
	v_exp_f32_e32 v249, v249
	v_exp_f32_e32 v250, v250
	v_exp_f32_e32 v251, v251
	v_add_f32_e32 v244, 1.0, v244
	v_add_f32_e32 v245, 1.0, v245
	v_add_f32_e32 v246, 1.0, v246
	v_add_f32_e32 v247, 1.0, v247
	v_add_f32_e32 v248, 1.0, v248
	v_add_f32_e32 v249, 1.0, v249
	v_add_f32_e32 v250, 1.0, v250
	v_add_f32_e32 v251, 1.0, v251
	v_rcp_f32_e32 v244, v244
	v_rcp_f32_e32 v245, v245
	v_rcp_f32_e32 v246, v246
	v_rcp_f32_e32 v247, v247
	v_rcp_f32_e32 v248, v248
	v_rcp_f32_e32 v249, v249
	v_rcp_f32_e32 v250, v250
	v_rcp_f32_e32 v251, v251
	v_mul_f32_e32 v58, v58, v244
	v_mul_f32_e32 v59, v59, v245
	v_mul_f32_e32 v60, v60, v246
	v_mul_f32_e32 v61, v61, v247
	v_mul_f32_e32 v54, v54, v248
	v_mul_f32_e32 v55, v55, v249
	v_mul_f32_e32 v56, v56, v250
	v_mul_f32_e32 v57, v57, v251
	v_cvt_pk_bf16_f32 v58, v58, v59
	v_cvt_pk_bf16_f32 v59, v60, v61
	v_cvt_pk_bf16_f32 v60, v54, v55
	v_cvt_pk_bf16_f32 v61, v56, v57
	global_store_dwordx4 v[164:165], v[58:61], off
	v_mul_f32_e32 v244, 0xbfb8aa3b, v26
	v_mul_f32_e32 v245, 0xbfb8aa3b, v27
	v_mul_f32_e32 v246, 0xbfb8aa3b, v28
	v_mul_f32_e32 v247, 0xbfb8aa3b, v29
	v_mul_f32_e32 v248, 0xbfb8aa3b, v22
	v_mul_f32_e32 v249, 0xbfb8aa3b, v23
	v_mul_f32_e32 v250, 0xbfb8aa3b, v24
	v_mul_f32_e32 v251, 0xbfb8aa3b, v25
	v_exp_f32_e32 v244, v244
	v_exp_f32_e32 v245, v245
	v_exp_f32_e32 v246, v246
	v_exp_f32_e32 v247, v247
	v_exp_f32_e32 v248, v248
	v_exp_f32_e32 v249, v249
	v_exp_f32_e32 v250, v250
	v_exp_f32_e32 v251, v251
	v_add_f32_e32 v244, 1.0, v244
	v_add_f32_e32 v245, 1.0, v245
	v_add_f32_e32 v246, 1.0, v246
	v_add_f32_e32 v247, 1.0, v247
	v_add_f32_e32 v248, 1.0, v248
	v_add_f32_e32 v249, 1.0, v249
	v_add_f32_e32 v250, 1.0, v250
	v_add_f32_e32 v251, 1.0, v251
	v_rcp_f32_e32 v244, v244
	v_rcp_f32_e32 v245, v245
	v_rcp_f32_e32 v246, v246
	v_rcp_f32_e32 v247, v247
	v_rcp_f32_e32 v248, v248
	v_rcp_f32_e32 v249, v249
	v_rcp_f32_e32 v250, v250
	v_rcp_f32_e32 v251, v251
	v_mul_f32_e32 v26, v26, v244
	v_mul_f32_e32 v27, v27, v245
	v_mul_f32_e32 v28, v28, v246
	v_mul_f32_e32 v29, v29, v247
	v_mul_f32_e32 v22, v22, v248
	v_mul_f32_e32 v23, v23, v249
	v_mul_f32_e32 v24, v24, v250
	v_mul_f32_e32 v25, v25, v251
	v_cvt_pk_bf16_f32 v26, v26, v27
	v_cvt_pk_bf16_f32 v27, v28, v29
	v_cvt_pk_bf16_f32 v28, v22, v23
	v_cvt_pk_bf16_f32 v29, v24, v25
	global_store_dwordx4 v[164:165], v[26:29], off offset:256
	v_lshl_add_u64 v[164:165], v[164:165], 0, s[8:9]
	v_mul_f32_e32 v244, 0xbfb8aa3b, v50
	v_mul_f32_e32 v245, 0xbfb8aa3b, v51
	v_mul_f32_e32 v246, 0xbfb8aa3b, v52
	v_mul_f32_e32 v247, 0xbfb8aa3b, v53
	v_mul_f32_e32 v248, 0xbfb8aa3b, v46
	v_mul_f32_e32 v249, 0xbfb8aa3b, v47
	v_mul_f32_e32 v250, 0xbfb8aa3b, v48
	v_mul_f32_e32 v251, 0xbfb8aa3b, v49
	v_exp_f32_e32 v244, v244
	v_exp_f32_e32 v245, v245
	v_exp_f32_e32 v246, v246
	v_exp_f32_e32 v247, v247
	v_exp_f32_e32 v248, v248
	v_exp_f32_e32 v249, v249
	v_exp_f32_e32 v250, v250
	v_exp_f32_e32 v251, v251
	v_add_f32_e32 v244, 1.0, v244
	v_add_f32_e32 v245, 1.0, v245
	v_add_f32_e32 v246, 1.0, v246
	v_add_f32_e32 v247, 1.0, v247
	v_add_f32_e32 v248, 1.0, v248
	v_add_f32_e32 v249, 1.0, v249
	v_add_f32_e32 v250, 1.0, v250
	v_add_f32_e32 v251, 1.0, v251
	v_rcp_f32_e32 v244, v244
	v_rcp_f32_e32 v245, v245
	v_rcp_f32_e32 v246, v246
	v_rcp_f32_e32 v247, v247
	v_rcp_f32_e32 v248, v248
	v_rcp_f32_e32 v249, v249
	v_rcp_f32_e32 v250, v250
	v_rcp_f32_e32 v251, v251
	v_mul_f32_e32 v50, v50, v244
	v_mul_f32_e32 v51, v51, v245
	v_mul_f32_e32 v52, v52, v246
	v_mul_f32_e32 v53, v53, v247
	v_mul_f32_e32 v46, v46, v248
	v_mul_f32_e32 v47, v47, v249
	v_mul_f32_e32 v48, v48, v250
	v_mul_f32_e32 v49, v49, v251
	v_cvt_pk_bf16_f32 v50, v50, v51
	v_cvt_pk_bf16_f32 v51, v52, v53
	v_cvt_pk_bf16_f32 v52, v46, v47
	v_cvt_pk_bf16_f32 v53, v48, v49
	global_store_dwordx4 v[164:165], v[50:53], off
	v_mul_f32_e32 v244, 0xbfb8aa3b, v18
	v_mul_f32_e32 v245, 0xbfb8aa3b, v19
	v_mul_f32_e32 v246, 0xbfb8aa3b, v20
	v_mul_f32_e32 v247, 0xbfb8aa3b, v21
	v_mul_f32_e32 v248, 0xbfb8aa3b, v14
	v_mul_f32_e32 v249, 0xbfb8aa3b, v15
	v_mul_f32_e32 v250, 0xbfb8aa3b, v16
	v_mul_f32_e32 v251, 0xbfb8aa3b, v17
	v_exp_f32_e32 v244, v244
	v_exp_f32_e32 v245, v245
	v_exp_f32_e32 v246, v246
	v_exp_f32_e32 v247, v247
	v_exp_f32_e32 v248, v248
	v_exp_f32_e32 v249, v249
	v_exp_f32_e32 v250, v250
	v_exp_f32_e32 v251, v251
	v_add_f32_e32 v244, 1.0, v244
	v_add_f32_e32 v245, 1.0, v245
	v_add_f32_e32 v246, 1.0, v246
	v_add_f32_e32 v247, 1.0, v247
	v_add_f32_e32 v248, 1.0, v248
	v_add_f32_e32 v249, 1.0, v249
	v_add_f32_e32 v250, 1.0, v250
	v_add_f32_e32 v251, 1.0, v251
	v_rcp_f32_e32 v244, v244
	v_rcp_f32_e32 v245, v245
	v_rcp_f32_e32 v246, v246
	v_rcp_f32_e32 v247, v247
	v_rcp_f32_e32 v248, v248
	v_rcp_f32_e32 v249, v249
	v_rcp_f32_e32 v250, v250
	v_rcp_f32_e32 v251, v251
	v_mul_f32_e32 v18, v18, v244
	v_mul_f32_e32 v19, v19, v245
	v_mul_f32_e32 v20, v20, v246
	v_mul_f32_e32 v21, v21, v247
	v_mul_f32_e32 v14, v14, v248
	v_mul_f32_e32 v15, v15, v249
	v_mul_f32_e32 v16, v16, v250
	v_mul_f32_e32 v17, v17, v251
	v_cvt_pk_bf16_f32 v18, v18, v19
	v_cvt_pk_bf16_f32 v19, v20, v21
	v_cvt_pk_bf16_f32 v20, v14, v15
	v_cvt_pk_bf16_f32 v21, v16, v17
	global_store_dwordx4 v[164:165], v[18:21], off offset:256
	v_lshl_add_u64 v[164:165], v[164:165], 0, s[8:9]
	v_mul_f32_e32 v244, 0xbfb8aa3b, v38
	v_mul_f32_e32 v245, 0xbfb8aa3b, v39
	v_mul_f32_e32 v246, 0xbfb8aa3b, v40
	v_mul_f32_e32 v247, 0xbfb8aa3b, v41
	v_mul_f32_e32 v248, 0xbfb8aa3b, v30
	v_mul_f32_e32 v249, 0xbfb8aa3b, v31
	v_mul_f32_e32 v250, 0xbfb8aa3b, v32
	v_mul_f32_e32 v251, 0xbfb8aa3b, v33
	v_exp_f32_e32 v244, v244
	v_exp_f32_e32 v245, v245
	v_exp_f32_e32 v246, v246
	v_exp_f32_e32 v247, v247
	v_exp_f32_e32 v248, v248
	v_exp_f32_e32 v249, v249
	v_exp_f32_e32 v250, v250
	v_exp_f32_e32 v251, v251
	v_add_f32_e32 v244, 1.0, v244
	v_add_f32_e32 v245, 1.0, v245
	v_add_f32_e32 v246, 1.0, v246
	v_add_f32_e32 v247, 1.0, v247
	v_add_f32_e32 v248, 1.0, v248
	v_add_f32_e32 v249, 1.0, v249
	v_add_f32_e32 v250, 1.0, v250
	v_add_f32_e32 v251, 1.0, v251
	v_rcp_f32_e32 v244, v244
	v_rcp_f32_e32 v245, v245
	v_rcp_f32_e32 v246, v246
	v_rcp_f32_e32 v247, v247
	v_rcp_f32_e32 v248, v248
	v_rcp_f32_e32 v249, v249
	v_rcp_f32_e32 v250, v250
	v_rcp_f32_e32 v251, v251
	v_mul_f32_e32 v38, v38, v244
	v_mul_f32_e32 v39, v39, v245
	v_mul_f32_e32 v40, v40, v246
	v_mul_f32_e32 v41, v41, v247
	v_mul_f32_e32 v30, v30, v248
	v_mul_f32_e32 v31, v31, v249
	v_mul_f32_e32 v32, v32, v250
	v_mul_f32_e32 v33, v33, v251
	v_cvt_pk_bf16_f32 v38, v38, v39
	v_cvt_pk_bf16_f32 v39, v40, v41
	v_cvt_pk_bf16_f32 v40, v30, v31
	v_cvt_pk_bf16_f32 v41, v32, v33
	global_store_dwordx4 v[164:165], v[38:41], off
	v_mul_f32_e32 v244, 0xbfb8aa3b, v10
	v_mul_f32_e32 v245, 0xbfb8aa3b, v11
	v_mul_f32_e32 v246, 0xbfb8aa3b, v12
	v_mul_f32_e32 v247, 0xbfb8aa3b, v13
	v_mul_f32_e32 v248, 0xbfb8aa3b, v6
	v_mul_f32_e32 v249, 0xbfb8aa3b, v7
	v_mul_f32_e32 v250, 0xbfb8aa3b, v8
	v_mul_f32_e32 v251, 0xbfb8aa3b, v9
	v_exp_f32_e32 v244, v244
	v_exp_f32_e32 v245, v245
	v_exp_f32_e32 v246, v246
	v_exp_f32_e32 v247, v247
	v_exp_f32_e32 v248, v248
	v_exp_f32_e32 v249, v249
	v_exp_f32_e32 v250, v250
	v_exp_f32_e32 v251, v251
	v_add_f32_e32 v244, 1.0, v244
	v_add_f32_e32 v245, 1.0, v245
	v_add_f32_e32 v246, 1.0, v246
	v_add_f32_e32 v247, 1.0, v247
	v_add_f32_e32 v248, 1.0, v248
	v_add_f32_e32 v249, 1.0, v249
	v_add_f32_e32 v250, 1.0, v250
	v_add_f32_e32 v251, 1.0, v251
	v_rcp_f32_e32 v244, v244
	v_rcp_f32_e32 v245, v245
	v_rcp_f32_e32 v246, v246
	v_rcp_f32_e32 v247, v247
	v_rcp_f32_e32 v248, v248
	v_rcp_f32_e32 v249, v249
	v_rcp_f32_e32 v250, v250
	v_rcp_f32_e32 v251, v251
	v_mul_f32_e32 v10, v10, v244
	v_mul_f32_e32 v11, v11, v245
	v_mul_f32_e32 v12, v12, v246
	v_mul_f32_e32 v13, v13, v247
	v_mul_f32_e32 v6, v6, v248
	v_mul_f32_e32 v7, v7, v249
	v_mul_f32_e32 v8, v8, v250
	v_mul_f32_e32 v9, v9, v251
	v_cvt_pk_bf16_f32 v10, v10, v11
	v_cvt_pk_bf16_f32 v11, v12, v13
	v_cvt_pk_bf16_f32 v12, v6, v7
	v_cvt_pk_bf16_f32 v13, v8, v9
	global_store_dwordx4 v[164:165], v[10:13], off offset:256
	v_lshl_add_u64 v[164:165], v[166:167], 0, s[22:23]
	v_mul_f32_e32 v244, 0xbfb8aa3b, v126
	v_mul_f32_e32 v245, 0xbfb8aa3b, v127
	v_mul_f32_e32 v246, 0xbfb8aa3b, v128
	v_mul_f32_e32 v247, 0xbfb8aa3b, v129
	v_mul_f32_e32 v248, 0xbfb8aa3b, v122
	v_mul_f32_e32 v249, 0xbfb8aa3b, v123
	v_mul_f32_e32 v250, 0xbfb8aa3b, v124
	v_mul_f32_e32 v251, 0xbfb8aa3b, v125
	v_exp_f32_e32 v244, v244
	v_exp_f32_e32 v245, v245
	v_exp_f32_e32 v246, v246
	v_exp_f32_e32 v247, v247
	v_exp_f32_e32 v248, v248
	v_exp_f32_e32 v249, v249
	v_exp_f32_e32 v250, v250
	v_exp_f32_e32 v251, v251
	v_add_f32_e32 v244, 1.0, v244
	v_add_f32_e32 v245, 1.0, v245
	v_add_f32_e32 v246, 1.0, v246
	v_add_f32_e32 v247, 1.0, v247
	v_add_f32_e32 v248, 1.0, v248
	v_add_f32_e32 v249, 1.0, v249
	v_add_f32_e32 v250, 1.0, v250
	v_add_f32_e32 v251, 1.0, v251
	v_rcp_f32_e32 v244, v244
	v_rcp_f32_e32 v245, v245
	v_rcp_f32_e32 v246, v246
	v_rcp_f32_e32 v247, v247
	v_rcp_f32_e32 v248, v248
	v_rcp_f32_e32 v249, v249
	v_rcp_f32_e32 v250, v250
	v_rcp_f32_e32 v251, v251
	v_mul_f32_e32 v126, v126, v244
	v_mul_f32_e32 v127, v127, v245
	v_mul_f32_e32 v128, v128, v246
	v_mul_f32_e32 v129, v129, v247
	v_mul_f32_e32 v122, v122, v248
	v_mul_f32_e32 v123, v123, v249
	v_mul_f32_e32 v124, v124, v250
	v_mul_f32_e32 v125, v125, v251
	v_cvt_pk_bf16_f32 v126, v126, v127
	v_cvt_pk_bf16_f32 v127, v128, v129
	v_cvt_pk_bf16_f32 v128, v122, v123
	v_cvt_pk_bf16_f32 v129, v124, v125
	global_store_dwordx4 v[164:165], v[126:129], off
	v_mul_f32_e32 v244, 0xbfb8aa3b, v118
	v_mul_f32_e32 v245, 0xbfb8aa3b, v119
	v_mul_f32_e32 v246, 0xbfb8aa3b, v120
	v_mul_f32_e32 v247, 0xbfb8aa3b, v121
	v_mul_f32_e32 v248, 0xbfb8aa3b, v114
	v_mul_f32_e32 v249, 0xbfb8aa3b, v115
	v_mul_f32_e32 v250, 0xbfb8aa3b, v116
	v_mul_f32_e32 v251, 0xbfb8aa3b, v117
	v_exp_f32_e32 v244, v244
	v_exp_f32_e32 v245, v245
	v_exp_f32_e32 v246, v246
	v_exp_f32_e32 v247, v247
	v_exp_f32_e32 v248, v248
	v_exp_f32_e32 v249, v249
	v_exp_f32_e32 v250, v250
	v_exp_f32_e32 v251, v251
	v_add_f32_e32 v244, 1.0, v244
	v_add_f32_e32 v245, 1.0, v245
	v_add_f32_e32 v246, 1.0, v246
	v_add_f32_e32 v247, 1.0, v247
	v_add_f32_e32 v248, 1.0, v248
	v_add_f32_e32 v249, 1.0, v249
	v_add_f32_e32 v250, 1.0, v250
	v_add_f32_e32 v251, 1.0, v251
	v_rcp_f32_e32 v244, v244
	v_rcp_f32_e32 v245, v245
	v_rcp_f32_e32 v246, v246
	v_rcp_f32_e32 v247, v247
	v_rcp_f32_e32 v248, v248
	v_rcp_f32_e32 v249, v249
	v_rcp_f32_e32 v250, v250
	v_rcp_f32_e32 v251, v251
	v_mul_f32_e32 v118, v118, v244
	v_mul_f32_e32 v119, v119, v245
	v_mul_f32_e32 v120, v120, v246
	v_mul_f32_e32 v121, v121, v247
	v_mul_f32_e32 v114, v114, v248
	v_mul_f32_e32 v115, v115, v249
	v_mul_f32_e32 v116, v116, v250
	v_mul_f32_e32 v117, v117, v251
	v_cvt_pk_bf16_f32 v118, v118, v119
	v_cvt_pk_bf16_f32 v119, v120, v121
	v_cvt_pk_bf16_f32 v120, v114, v115
	v_cvt_pk_bf16_f32 v121, v116, v117
	global_store_dwordx4 v[164:165], v[118:121], off offset:256
	v_lshl_add_u64 v[164:165], v[164:165], 0, s[8:9]
	v_mul_f32_e32 v244, 0xbfb8aa3b, v110
	v_mul_f32_e32 v245, 0xbfb8aa3b, v111
	v_mul_f32_e32 v246, 0xbfb8aa3b, v112
	v_mul_f32_e32 v247, 0xbfb8aa3b, v113
	v_mul_f32_e32 v248, 0xbfb8aa3b, v106
	v_mul_f32_e32 v249, 0xbfb8aa3b, v107
	v_mul_f32_e32 v250, 0xbfb8aa3b, v108
	v_mul_f32_e32 v251, 0xbfb8aa3b, v109
	v_exp_f32_e32 v244, v244
	v_exp_f32_e32 v245, v245
	v_exp_f32_e32 v246, v246
	v_exp_f32_e32 v247, v247
	v_exp_f32_e32 v248, v248
	v_exp_f32_e32 v249, v249
	v_exp_f32_e32 v250, v250
	v_exp_f32_e32 v251, v251
	v_add_f32_e32 v244, 1.0, v244
	v_add_f32_e32 v245, 1.0, v245
	v_add_f32_e32 v246, 1.0, v246
	v_add_f32_e32 v247, 1.0, v247
	v_add_f32_e32 v248, 1.0, v248
	v_add_f32_e32 v249, 1.0, v249
	v_add_f32_e32 v250, 1.0, v250
	v_add_f32_e32 v251, 1.0, v251
	v_rcp_f32_e32 v244, v244
	v_rcp_f32_e32 v245, v245
	v_rcp_f32_e32 v246, v246
	v_rcp_f32_e32 v247, v247
	v_rcp_f32_e32 v248, v248
	v_rcp_f32_e32 v249, v249
	v_rcp_f32_e32 v250, v250
	v_rcp_f32_e32 v251, v251
	v_mul_f32_e32 v110, v110, v244
	v_mul_f32_e32 v111, v111, v245
	v_mul_f32_e32 v112, v112, v246
	v_mul_f32_e32 v113, v113, v247
	v_mul_f32_e32 v106, v106, v248
	v_mul_f32_e32 v107, v107, v249
	v_mul_f32_e32 v108, v108, v250
	v_mul_f32_e32 v109, v109, v251
	v_cvt_pk_bf16_f32 v110, v110, v111
	v_cvt_pk_bf16_f32 v111, v112, v113
	v_cvt_pk_bf16_f32 v112, v106, v107
	v_cvt_pk_bf16_f32 v113, v108, v109
	global_store_dwordx4 v[164:165], v[110:113], off
	v_mul_f32_e32 v244, 0xbfb8aa3b, v102
	v_mul_f32_e32 v245, 0xbfb8aa3b, v103
	v_mul_f32_e32 v246, 0xbfb8aa3b, v104
	v_mul_f32_e32 v247, 0xbfb8aa3b, v105
	v_mul_f32_e32 v248, 0xbfb8aa3b, v98
	v_mul_f32_e32 v249, 0xbfb8aa3b, v99
	v_mul_f32_e32 v250, 0xbfb8aa3b, v100
	v_mul_f32_e32 v251, 0xbfb8aa3b, v101
	v_exp_f32_e32 v244, v244
	v_exp_f32_e32 v245, v245
	v_exp_f32_e32 v246, v246
	v_exp_f32_e32 v247, v247
	v_exp_f32_e32 v248, v248
	v_exp_f32_e32 v249, v249
	v_exp_f32_e32 v250, v250
	v_exp_f32_e32 v251, v251
	v_add_f32_e32 v244, 1.0, v244
	v_add_f32_e32 v245, 1.0, v245
	v_add_f32_e32 v246, 1.0, v246
	v_add_f32_e32 v247, 1.0, v247
	v_add_f32_e32 v248, 1.0, v248
	v_add_f32_e32 v249, 1.0, v249
	v_add_f32_e32 v250, 1.0, v250
	v_add_f32_e32 v251, 1.0, v251
	v_rcp_f32_e32 v244, v244
	v_rcp_f32_e32 v245, v245
	v_rcp_f32_e32 v246, v246
	v_rcp_f32_e32 v247, v247
	v_rcp_f32_e32 v248, v248
	v_rcp_f32_e32 v249, v249
	v_rcp_f32_e32 v250, v250
	v_rcp_f32_e32 v251, v251
	v_mul_f32_e32 v102, v102, v244
	v_mul_f32_e32 v103, v103, v245
	v_mul_f32_e32 v104, v104, v246
	v_mul_f32_e32 v105, v105, v247
	v_mul_f32_e32 v98, v98, v248
	v_mul_f32_e32 v99, v99, v249
	v_mul_f32_e32 v100, v100, v250
	v_mul_f32_e32 v101, v101, v251
	v_cvt_pk_bf16_f32 v102, v102, v103
	v_cvt_pk_bf16_f32 v103, v104, v105
	v_cvt_pk_bf16_f32 v104, v98, v99
	v_cvt_pk_bf16_f32 v105, v100, v101
	global_store_dwordx4 v[164:165], v[102:105], off offset:256
	v_lshl_add_u64 v[164:165], v[164:165], 0, s[8:9]
	v_mul_f32_e32 v244, 0xbfb8aa3b, v94
	v_mul_f32_e32 v245, 0xbfb8aa3b, v95
	v_mul_f32_e32 v246, 0xbfb8aa3b, v96
	v_mul_f32_e32 v247, 0xbfb8aa3b, v97
	v_mul_f32_e32 v248, 0xbfb8aa3b, v90
	v_mul_f32_e32 v249, 0xbfb8aa3b, v91
	v_mul_f32_e32 v250, 0xbfb8aa3b, v92
	v_mul_f32_e32 v251, 0xbfb8aa3b, v93
	v_exp_f32_e32 v244, v244
	v_exp_f32_e32 v245, v245
	v_exp_f32_e32 v246, v246
	v_exp_f32_e32 v247, v247
	v_exp_f32_e32 v248, v248
	v_exp_f32_e32 v249, v249
	v_exp_f32_e32 v250, v250
	v_exp_f32_e32 v251, v251
	v_add_f32_e32 v244, 1.0, v244
	v_add_f32_e32 v245, 1.0, v245
	v_add_f32_e32 v246, 1.0, v246
	v_add_f32_e32 v247, 1.0, v247
	v_add_f32_e32 v248, 1.0, v248
	v_add_f32_e32 v249, 1.0, v249
	v_add_f32_e32 v250, 1.0, v250
	v_add_f32_e32 v251, 1.0, v251
	v_rcp_f32_e32 v244, v244
	v_rcp_f32_e32 v245, v245
	v_rcp_f32_e32 v246, v246
	v_rcp_f32_e32 v247, v247
	v_rcp_f32_e32 v248, v248
	v_rcp_f32_e32 v249, v249
	v_rcp_f32_e32 v250, v250
	v_rcp_f32_e32 v251, v251
	v_mul_f32_e32 v94, v94, v244
	v_mul_f32_e32 v95, v95, v245
	v_mul_f32_e32 v96, v96, v246
	v_mul_f32_e32 v97, v97, v247
	v_mul_f32_e32 v90, v90, v248
	v_mul_f32_e32 v91, v91, v249
	v_mul_f32_e32 v92, v92, v250
	v_mul_f32_e32 v93, v93, v251
	v_cvt_pk_bf16_f32 v94, v94, v95
	v_cvt_pk_bf16_f32 v95, v96, v97
	v_cvt_pk_bf16_f32 v96, v90, v91
	v_cvt_pk_bf16_f32 v97, v92, v93
	global_store_dwordx4 v[164:165], v[94:97], off
	v_mul_f32_e32 v244, 0xbfb8aa3b, v86
	v_mul_f32_e32 v245, 0xbfb8aa3b, v87
	v_mul_f32_e32 v246, 0xbfb8aa3b, v88
	v_mul_f32_e32 v247, 0xbfb8aa3b, v89
	v_mul_f32_e32 v248, 0xbfb8aa3b, v82
	v_mul_f32_e32 v249, 0xbfb8aa3b, v83
	v_mul_f32_e32 v250, 0xbfb8aa3b, v84
	v_mul_f32_e32 v251, 0xbfb8aa3b, v85
	v_exp_f32_e32 v244, v244
	v_exp_f32_e32 v245, v245
	v_exp_f32_e32 v246, v246
	v_exp_f32_e32 v247, v247
	v_exp_f32_e32 v248, v248
	v_exp_f32_e32 v249, v249
	v_exp_f32_e32 v250, v250
	v_exp_f32_e32 v251, v251
	v_add_f32_e32 v244, 1.0, v244
	v_add_f32_e32 v245, 1.0, v245
	v_add_f32_e32 v246, 1.0, v246
	v_add_f32_e32 v247, 1.0, v247
	v_add_f32_e32 v248, 1.0, v248
	v_add_f32_e32 v249, 1.0, v249
	v_add_f32_e32 v250, 1.0, v250
	v_add_f32_e32 v251, 1.0, v251
	v_rcp_f32_e32 v244, v244
	v_rcp_f32_e32 v245, v245
	v_rcp_f32_e32 v246, v246
	v_rcp_f32_e32 v247, v247
	v_rcp_f32_e32 v248, v248
	v_rcp_f32_e32 v249, v249
	v_rcp_f32_e32 v250, v250
	v_rcp_f32_e32 v251, v251
	v_mul_f32_e32 v86, v86, v244
	v_mul_f32_e32 v87, v87, v245
	v_mul_f32_e32 v88, v88, v246
	v_mul_f32_e32 v89, v89, v247
	v_mul_f32_e32 v82, v82, v248
	v_mul_f32_e32 v83, v83, v249
	v_mul_f32_e32 v84, v84, v250
	v_mul_f32_e32 v85, v85, v251
	v_cvt_pk_bf16_f32 v86, v86, v87
	v_cvt_pk_bf16_f32 v87, v88, v89
	v_cvt_pk_bf16_f32 v88, v82, v83
	v_cvt_pk_bf16_f32 v89, v84, v85
	global_store_dwordx4 v[164:165], v[86:89], off offset:256
	v_lshl_add_u64 v[164:165], v[164:165], 0, s[8:9]
	v_mul_f32_e32 v244, 0xbfb8aa3b, v78
	v_mul_f32_e32 v245, 0xbfb8aa3b, v79
	v_mul_f32_e32 v246, 0xbfb8aa3b, v80
	v_mul_f32_e32 v247, 0xbfb8aa3b, v81
	v_mul_f32_e32 v248, 0xbfb8aa3b, v74
	v_mul_f32_e32 v249, 0xbfb8aa3b, v75
	v_mul_f32_e32 v250, 0xbfb8aa3b, v76
	v_mul_f32_e32 v251, 0xbfb8aa3b, v77
	v_exp_f32_e32 v244, v244
	v_exp_f32_e32 v245, v245
	v_exp_f32_e32 v246, v246
	v_exp_f32_e32 v247, v247
	v_exp_f32_e32 v248, v248
	v_exp_f32_e32 v249, v249
	v_exp_f32_e32 v250, v250
	v_exp_f32_e32 v251, v251
	v_add_f32_e32 v244, 1.0, v244
	v_add_f32_e32 v245, 1.0, v245
	v_add_f32_e32 v246, 1.0, v246
	v_add_f32_e32 v247, 1.0, v247
	v_add_f32_e32 v248, 1.0, v248
	v_add_f32_e32 v249, 1.0, v249
	v_add_f32_e32 v250, 1.0, v250
	v_add_f32_e32 v251, 1.0, v251
	v_rcp_f32_e32 v244, v244
	v_rcp_f32_e32 v245, v245
	v_rcp_f32_e32 v246, v246
	v_rcp_f32_e32 v247, v247
	v_rcp_f32_e32 v248, v248
	v_rcp_f32_e32 v249, v249
	v_rcp_f32_e32 v250, v250
	v_rcp_f32_e32 v251, v251
	v_mul_f32_e32 v78, v78, v244
	v_mul_f32_e32 v79, v79, v245
	v_mul_f32_e32 v80, v80, v246
	v_mul_f32_e32 v81, v81, v247
	v_mul_f32_e32 v74, v74, v248
	v_mul_f32_e32 v75, v75, v249
	v_mul_f32_e32 v76, v76, v250
	v_mul_f32_e32 v77, v77, v251
	v_cvt_pk_bf16_f32 v78, v78, v79
	v_cvt_pk_bf16_f32 v79, v80, v81
	v_cvt_pk_bf16_f32 v80, v74, v75
	v_cvt_pk_bf16_f32 v81, v76, v77
	global_store_dwordx4 v[164:165], v[78:81], off
	v_mul_f32_e32 v244, 0xbfb8aa3b, v70
	v_mul_f32_e32 v245, 0xbfb8aa3b, v71
	v_mul_f32_e32 v246, 0xbfb8aa3b, v72
	v_mul_f32_e32 v247, 0xbfb8aa3b, v73
	v_mul_f32_e32 v248, 0xbfb8aa3b, v2
	v_mul_f32_e32 v249, 0xbfb8aa3b, v3
	v_mul_f32_e32 v250, 0xbfb8aa3b, v4
	v_mul_f32_e32 v251, 0xbfb8aa3b, v5
	v_exp_f32_e32 v244, v244
	v_exp_f32_e32 v245, v245
	v_exp_f32_e32 v246, v246
	v_exp_f32_e32 v247, v247
	v_exp_f32_e32 v248, v248
	v_exp_f32_e32 v249, v249
	v_exp_f32_e32 v250, v250
	v_exp_f32_e32 v251, v251
	v_add_f32_e32 v244, 1.0, v244
	v_add_f32_e32 v245, 1.0, v245
	v_add_f32_e32 v246, 1.0, v246
	v_add_f32_e32 v247, 1.0, v247
	v_add_f32_e32 v248, 1.0, v248
	v_add_f32_e32 v249, 1.0, v249
	v_add_f32_e32 v250, 1.0, v250
	v_add_f32_e32 v251, 1.0, v251
	v_rcp_f32_e32 v244, v244
	v_rcp_f32_e32 v245, v245
	v_rcp_f32_e32 v246, v246
	v_rcp_f32_e32 v247, v247
	v_rcp_f32_e32 v248, v248
	v_rcp_f32_e32 v249, v249
	v_rcp_f32_e32 v250, v250
	v_rcp_f32_e32 v251, v251
	v_mul_f32_e32 v70, v70, v244
	v_mul_f32_e32 v71, v71, v245
	v_mul_f32_e32 v72, v72, v246
	v_mul_f32_e32 v73, v73, v247
	v_mul_f32_e32 v2, v2, v248
	v_mul_f32_e32 v3, v3, v249
	v_mul_f32_e32 v4, v4, v250
	v_mul_f32_e32 v5, v5, v251
	v_cvt_pk_bf16_f32 v70, v70, v71
	v_cvt_pk_bf16_f32 v71, v72, v73
	v_cvt_pk_bf16_f32 v72, v2, v3
	v_cvt_pk_bf16_f32 v73, v4, v5
	global_store_dwordx4 v[164:165], v[70:73], off offset:256
	s_branch .Lodd_done
.Lodd_t2:
	v_mov_b32_e32 v164, v166
	v_mov_b32_e32 v165, v167
	v_cvt_pk_bf16_f32 v66, v66, v67
	v_cvt_pk_bf16_f32 v67, v68, v69
	v_cvt_pk_bf16_f32 v68, v62, v63
	v_cvt_pk_bf16_f32 v69, v64, v65
	global_store_dwordx4 v[164:165], v[66:69], off
	v_cvt_pk_bf16_f32 v42, v42, v43
	v_cvt_pk_bf16_f32 v43, v44, v45
	v_cvt_pk_bf16_f32 v44, v34, v35
	v_cvt_pk_bf16_f32 v45, v36, v37
	global_store_dwordx4 v[164:165], v[42:45], off offset:256
	v_lshl_add_u64 v[164:165], v[164:165], 0, s[8:9]
	v_cvt_pk_bf16_f32 v58, v58, v59
	v_cvt_pk_bf16_f32 v59, v60, v61
	v_cvt_pk_bf16_f32 v60, v54, v55
	v_cvt_pk_bf16_f32 v61, v56, v57
	global_store_dwordx4 v[164:165], v[58:61], off
	v_cvt_pk_bf16_f32 v26, v26, v27
	v_cvt_pk_bf16_f32 v27, v28, v29
	v_cvt_pk_bf16_f32 v28, v22, v23
	v_cvt_pk_bf16_f32 v29, v24, v25
	global_store_dwordx4 v[164:165], v[26:29], off offset:256
	v_lshl_add_u64 v[164:165], v[164:165], 0, s[8:9]
	v_cvt_pk_bf16_f32 v50, v50, v51
	v_cvt_pk_bf16_f32 v51, v52, v53
	v_cvt_pk_bf16_f32 v52, v46, v47
	v_cvt_pk_bf16_f32 v53, v48, v49
	global_store_dwordx4 v[164:165], v[50:53], off
	v_cvt_pk_bf16_f32 v18, v18, v19
	v_cvt_pk_bf16_f32 v19, v20, v21
	v_cvt_pk_bf16_f32 v20, v14, v15
	v_cvt_pk_bf16_f32 v21, v16, v17
	global_store_dwordx4 v[164:165], v[18:21], off offset:256
	v_lshl_add_u64 v[164:165], v[164:165], 0, s[8:9]
	v_cvt_pk_bf16_f32 v38, v38, v39
	v_cvt_pk_bf16_f32 v39, v40, v41
	v_cvt_pk_bf16_f32 v40, v30, v31
	v_cvt_pk_bf16_f32 v41, v32, v33
	global_store_dwordx4 v[164:165], v[38:41], off
	v_cvt_pk_bf16_f32 v10, v10, v11
	v_cvt_pk_bf16_f32 v11, v12, v13
	v_cvt_pk_bf16_f32 v12, v6, v7
	v_cvt_pk_bf16_f32 v13, v8, v9
	global_store_dwordx4 v[164:165], v[10:13], off offset:256
	v_lshl_add_u64 v[164:165], v[166:167], 0, s[22:23]
	v_cvt_pk_bf16_f32 v126, v126, v127
	v_cvt_pk_bf16_f32 v127, v128, v129
	v_cvt_pk_bf16_f32 v128, v122, v123
	v_cvt_pk_bf16_f32 v129, v124, v125
	global_store_dwordx4 v[164:165], v[126:129], off
	v_cvt_pk_bf16_f32 v118, v118, v119
	v_cvt_pk_bf16_f32 v119, v120, v121
	v_cvt_pk_bf16_f32 v120, v114, v115
	v_cvt_pk_bf16_f32 v121, v116, v117
	global_store_dwordx4 v[164:165], v[118:121], off offset:256
	v_lshl_add_u64 v[164:165], v[164:165], 0, s[8:9]
	v_cvt_pk_bf16_f32 v110, v110, v111
	v_cvt_pk_bf16_f32 v111, v112, v113
	v_cvt_pk_bf16_f32 v112, v106, v107
	v_cvt_pk_bf16_f32 v113, v108, v109
	global_store_dwordx4 v[164:165], v[110:113], off
	v_cvt_pk_bf16_f32 v102, v102, v103
	v_cvt_pk_bf16_f32 v103, v104, v105
	v_cvt_pk_bf16_f32 v104, v98, v99
	v_cvt_pk_bf16_f32 v105, v100, v101
	global_store_dwordx4 v[164:165], v[102:105], off offset:256
	v_lshl_add_u64 v[164:165], v[164:165], 0, s[8:9]
	v_cvt_pk_bf16_f32 v94, v94, v95
	v_cvt_pk_bf16_f32 v95, v96, v97
	v_cvt_pk_bf16_f32 v96, v90, v91
	v_cvt_pk_bf16_f32 v97, v92, v93
	global_store_dwordx4 v[164:165], v[94:97], off
	v_cvt_pk_bf16_f32 v86, v86, v87
	v_cvt_pk_bf16_f32 v87, v88, v89
	v_cvt_pk_bf16_f32 v88, v82, v83
	v_cvt_pk_bf16_f32 v89, v84, v85
	global_store_dwordx4 v[164:165], v[86:89], off offset:256
	v_lshl_add_u64 v[164:165], v[164:165], 0, s[8:9]
	v_cvt_pk_bf16_f32 v78, v78, v79
	v_cvt_pk_bf16_f32 v79, v80, v81
	v_cvt_pk_bf16_f32 v80, v74, v75
	v_cvt_pk_bf16_f32 v81, v76, v77
	global_store_dwordx4 v[164:165], v[78:81], off
	v_cvt_pk_bf16_f32 v70, v70, v71
	v_cvt_pk_bf16_f32 v71, v72, v73
	v_cvt_pk_bf16_f32 v72, v2, v3
	v_cvt_pk_bf16_f32 v73, v4, v5
	global_store_dwordx4 v[164:165], v[70:73], off offset:256
	s_branch .Lodd_done
.Lodd_t1:
	v_and_b32_e32 v163, 0xf78, v162
	v_lshlrev_b32_e32 v163, 2, v163
	global_load_dwordx4 v[172:175], v163, s[16:17]
	global_load_dwordx4 v[176:179], v163, s[16:17] offset:16
	global_load_dwordx4 v[180:183], v163, s[16:17] offset:512
	global_load_dwordx4 v[184:187], v163, s[16:17] offset:528
	s_waitcnt vmcnt(0)
	v_mov_b32_e32 v164, v166
	v_mov_b32_e32 v165, v167
	v_mul_f32_e32 v244, 0xbfb8aa3b, v66
	v_mul_f32_e32 v245, 0xbfb8aa3b, v67
	v_mul_f32_e32 v246, 0xbfb8aa3b, v68
	v_mul_f32_e32 v247, 0xbfb8aa3b, v69
	v_exp_f32_e32 v244, v244
	v_exp_f32_e32 v245, v245
	v_exp_f32_e32 v246, v246
	v_exp_f32_e32 v247, v247
	v_sub_f32_e32 v248, 1.0, v172
	v_sub_f32_e32 v249, 1.0, v173
	v_sub_f32_e32 v250, 1.0, v174
	v_sub_f32_e32 v251, 1.0, v175
	v_add_f32_e32 v244, 1.0, v244
	v_add_f32_e32 v245, 1.0, v245
	v_add_f32_e32 v246, 1.0, v246
	v_add_f32_e32 v247, 1.0, v247
	v_rcp_f32_e32 v244, v244
	v_rcp_f32_e32 v245, v245
	v_rcp_f32_e32 v246, v246
	v_rcp_f32_e32 v247, v247
	v_fma_f32 v244, v244, v248, v172
	v_fma_f32 v245, v245, v249, v173
	v_fma_f32 v246, v246, v250, v174
	v_fma_f32 v247, v247, v251, v175
	v_cmp_gt_f32_e64 vcc, s74, v244
	v_cmp_gt_f32_e64 s[34:35], s74, v245
	v_cmp_gt_f32_e64 s[40:41], s74, v246
	v_cmp_gt_f32_e64 s[42:43], s74, v247
	v_cndmask_b32_e64 v192, 0, 32, vcc
	v_cndmask_b32_e64 v193, 0, 32, s[34:35]
	v_cndmask_b32_e64 v196, 0, 32, s[40:41]
	v_cndmask_b32_e64 v197, 0, 32, s[42:43]
	v_cndmask_b32_e64 v188, 0, v171, vcc
	v_cndmask_b32_e64 v189, 0, v171, s[34:35]
	v_cndmask_b32_e64 v190, 0, v171, s[40:41]
	v_cndmask_b32_e64 v191, 0, v171, s[42:43]
	v_ldexp_f32 v244, v244, v192
	v_ldexp_f32 v245, v245, v193
	v_ldexp_f32 v246, v246, v196
	v_ldexp_f32 v247, v247, v197
	v_log_f32_e32 v244, v244
	v_log_f32_e32 v245, v245
	v_log_f32_e32 v246, v246
	v_log_f32_e32 v247, v247
	v_mul_f32_e32 v248, 0x3f317217, v244
	v_mul_f32_e32 v249, 0x3f317217, v245
	v_mul_f32_e32 v250, 0x3f317217, v246
	v_mul_f32_e32 v251, 0x3f317217, v247
	v_fma_f32 v192, v244, s75, -v248
	v_fma_f32 v193, v245, s75, -v249
	v_fma_f32 v196, v246, s75, -v250
	v_fma_f32 v197, v247, s75, -v251
	v_fmac_f32_e32 v192, 0x3377d1cf, v244
	v_fmac_f32_e32 v193, 0x3377d1cf, v245
	v_fmac_f32_e32 v196, 0x3377d1cf, v246
	v_fmac_f32_e32 v197, 0x3377d1cf, v247
	v_fmac_f32_e32 v192, 0x3f317217, v244
	v_fmac_f32_e32 v193, 0x3f317217, v245
	v_fmac_f32_e32 v196, 0x3f317217, v246
	v_fmac_f32_e32 v197, 0x3f317217, v247
	v_cmp_lt_f32_e64 vcc, |v244|, s76
	v_cmp_lt_f32_e64 s[34:35], |v245|, s76
	v_cmp_lt_f32_e64 s[40:41], |v246|, s76
	v_cmp_lt_f32_e64 s[42:43], |v247|, s76
	v_cndmask_b32_e64 v244, v244, v192, vcc
	v_cndmask_b32_e64 v245, v245, v193, s[34:35]
	v_cndmask_b32_e64 v246, v246, v196, s[40:41]
	v_cndmask_b32_e64 v247, v247, v197, s[42:43]
	v_sub_f32_e32 v66, v244, v188
	v_sub_f32_e32 v67, v245, v189
	v_sub_f32_e32 v68, v246, v190
	v_sub_f32_e32 v69, v247, v191
	v_mul_f32_e32 v244, 0xbfb8aa3b, v62
	v_mul_f32_e32 v245, 0xbfb8aa3b, v63
	v_mul_f32_e32 v246, 0xbfb8aa3b, v64
	v_mul_f32_e32 v247, 0xbfb8aa3b, v65
	v_exp_f32_e32 v244, v244
	v_exp_f32_e32 v245, v245
	v_exp_f32_e32 v246, v246
	v_exp_f32_e32 v247, v247
	v_sub_f32_e32 v248, 1.0, v176
	v_sub_f32_e32 v249, 1.0, v177
	v_sub_f32_e32 v250, 1.0, v178
	v_sub_f32_e32 v251, 1.0, v179
	v_add_f32_e32 v244, 1.0, v244
	v_add_f32_e32 v245, 1.0, v245
	v_add_f32_e32 v246, 1.0, v246
	v_add_f32_e32 v247, 1.0, v247
	v_rcp_f32_e32 v244, v244
	v_rcp_f32_e32 v245, v245
	v_rcp_f32_e32 v246, v246
	v_rcp_f32_e32 v247, v247
	v_fma_f32 v244, v244, v248, v176
	v_fma_f32 v245, v245, v249, v177
	v_fma_f32 v246, v246, v250, v178
	v_fma_f32 v247, v247, v251, v179
	v_cmp_gt_f32_e64 vcc, s74, v244
	v_cmp_gt_f32_e64 s[34:35], s74, v245
	v_cmp_gt_f32_e64 s[40:41], s74, v246
	v_cmp_gt_f32_e64 s[42:43], s74, v247
	v_cndmask_b32_e64 v192, 0, 32, vcc
	v_cndmask_b32_e64 v193, 0, 32, s[34:35]
	v_cndmask_b32_e64 v196, 0, 32, s[40:41]
	v_cndmask_b32_e64 v197, 0, 32, s[42:43]
	v_cndmask_b32_e64 v188, 0, v171, vcc
	v_cndmask_b32_e64 v189, 0, v171, s[34:35]
	v_cndmask_b32_e64 v190, 0, v171, s[40:41]
	v_cndmask_b32_e64 v191, 0, v171, s[42:43]
	v_ldexp_f32 v244, v244, v192
	v_ldexp_f32 v245, v245, v193
	v_ldexp_f32 v246, v246, v196
	v_ldexp_f32 v247, v247, v197
	v_log_f32_e32 v244, v244
	v_log_f32_e32 v245, v245
	v_log_f32_e32 v246, v246
	v_log_f32_e32 v247, v247
	v_mul_f32_e32 v248, 0x3f317217, v244
	v_mul_f32_e32 v249, 0x3f317217, v245
	v_mul_f32_e32 v250, 0x3f317217, v246
	v_mul_f32_e32 v251, 0x3f317217, v247
	v_fma_f32 v192, v244, s75, -v248
	v_fma_f32 v193, v245, s75, -v249
	v_fma_f32 v196, v246, s75, -v250
	v_fma_f32 v197, v247, s75, -v251
	v_fmac_f32_e32 v192, 0x3377d1cf, v244
	v_fmac_f32_e32 v193, 0x3377d1cf, v245
	v_fmac_f32_e32 v196, 0x3377d1cf, v246
	v_fmac_f32_e32 v197, 0x3377d1cf, v247
	v_fmac_f32_e32 v192, 0x3f317217, v244
	v_fmac_f32_e32 v193, 0x3f317217, v245
	v_fmac_f32_e32 v196, 0x3f317217, v246
	v_fmac_f32_e32 v197, 0x3f317217, v247
	v_cmp_lt_f32_e64 vcc, |v244|, s76
	v_cmp_lt_f32_e64 s[34:35], |v245|, s76
	v_cmp_lt_f32_e64 s[40:41], |v246|, s76
	v_cmp_lt_f32_e64 s[42:43], |v247|, s76
	v_cndmask_b32_e64 v244, v244, v192, vcc
	v_cndmask_b32_e64 v245, v245, v193, s[34:35]
	v_cndmask_b32_e64 v246, v246, v196, s[40:41]
	v_cndmask_b32_e64 v247, v247, v197, s[42:43]
	v_sub_f32_e32 v62, v244, v188
	v_sub_f32_e32 v63, v245, v189
	v_sub_f32_e32 v64, v246, v190
	v_sub_f32_e32 v65, v247, v191
	v_cvt_pk_bf16_f32 v66, v66, v67
	v_cvt_pk_bf16_f32 v67, v68, v69
	v_cvt_pk_bf16_f32 v68, v62, v63
	v_cvt_pk_bf16_f32 v69, v64, v65
	global_store_dwordx4 v[164:165], v[66:69], off
	v_mul_f32_e32 v244, 0xbfb8aa3b, v42
	v_mul_f32_e32 v245, 0xbfb8aa3b, v43
	v_mul_f32_e32 v246, 0xbfb8aa3b, v44
	v_mul_f32_e32 v247, 0xbfb8aa3b, v45
	v_exp_f32_e32 v244, v244
	v_exp_f32_e32 v245, v245
	v_exp_f32_e32 v246, v246
	v_exp_f32_e32 v247, v247
	v_sub_f32_e32 v248, 1.0, v180
	v_sub_f32_e32 v249, 1.0, v181
	v_sub_f32_e32 v250, 1.0, v182
	v_sub_f32_e32 v251, 1.0, v183
	v_add_f32_e32 v244, 1.0, v244
	v_add_f32_e32 v245, 1.0, v245
	v_add_f32_e32 v246, 1.0, v246
	v_add_f32_e32 v247, 1.0, v247
	v_rcp_f32_e32 v244, v244
	v_rcp_f32_e32 v245, v245
	v_rcp_f32_e32 v246, v246
	v_rcp_f32_e32 v247, v247
	v_fma_f32 v244, v244, v248, v180
	v_fma_f32 v245, v245, v249, v181
	v_fma_f32 v246, v246, v250, v182
	v_fma_f32 v247, v247, v251, v183
	v_cmp_gt_f32_e64 vcc, s74, v244
	v_cmp_gt_f32_e64 s[34:35], s74, v245
	v_cmp_gt_f32_e64 s[40:41], s74, v246
	v_cmp_gt_f32_e64 s[42:43], s74, v247
	v_cndmask_b32_e64 v192, 0, 32, vcc
	v_cndmask_b32_e64 v193, 0, 32, s[34:35]
	v_cndmask_b32_e64 v196, 0, 32, s[40:41]
	v_cndmask_b32_e64 v197, 0, 32, s[42:43]
	v_cndmask_b32_e64 v188, 0, v171, vcc
	v_cndmask_b32_e64 v189, 0, v171, s[34:35]
	v_cndmask_b32_e64 v190, 0, v171, s[40:41]
	v_cndmask_b32_e64 v191, 0, v171, s[42:43]
	v_ldexp_f32 v244, v244, v192
	v_ldexp_f32 v245, v245, v193
	v_ldexp_f32 v246, v246, v196
	v_ldexp_f32 v247, v247, v197
	v_log_f32_e32 v244, v244
	v_log_f32_e32 v245, v245
	v_log_f32_e32 v246, v246
	v_log_f32_e32 v247, v247
	v_mul_f32_e32 v248, 0x3f317217, v244
	v_mul_f32_e32 v249, 0x3f317217, v245
	v_mul_f32_e32 v250, 0x3f317217, v246
	v_mul_f32_e32 v251, 0x3f317217, v247
	v_fma_f32 v192, v244, s75, -v248
	v_fma_f32 v193, v245, s75, -v249
	v_fma_f32 v196, v246, s75, -v250
	v_fma_f32 v197, v247, s75, -v251
	v_fmac_f32_e32 v192, 0x3377d1cf, v244
	v_fmac_f32_e32 v193, 0x3377d1cf, v245
	v_fmac_f32_e32 v196, 0x3377d1cf, v246
	v_fmac_f32_e32 v197, 0x3377d1cf, v247
	v_fmac_f32_e32 v192, 0x3f317217, v244
	v_fmac_f32_e32 v193, 0x3f317217, v245
	v_fmac_f32_e32 v196, 0x3f317217, v246
	v_fmac_f32_e32 v197, 0x3f317217, v247
	v_cmp_lt_f32_e64 vcc, |v244|, s76
	v_cmp_lt_f32_e64 s[34:35], |v245|, s76
	v_cmp_lt_f32_e64 s[40:41], |v246|, s76
	v_cmp_lt_f32_e64 s[42:43], |v247|, s76
	v_cndmask_b32_e64 v244, v244, v192, vcc
	v_cndmask_b32_e64 v245, v245, v193, s[34:35]
	v_cndmask_b32_e64 v246, v246, v196, s[40:41]
	v_cndmask_b32_e64 v247, v247, v197, s[42:43]
	v_sub_f32_e32 v42, v244, v188
	v_sub_f32_e32 v43, v245, v189
	v_sub_f32_e32 v44, v246, v190
	v_sub_f32_e32 v45, v247, v191
	v_mul_f32_e32 v244, 0xbfb8aa3b, v34
	v_mul_f32_e32 v245, 0xbfb8aa3b, v35
	v_mul_f32_e32 v246, 0xbfb8aa3b, v36
	v_mul_f32_e32 v247, 0xbfb8aa3b, v37
	v_exp_f32_e32 v244, v244
	v_exp_f32_e32 v245, v245
	v_exp_f32_e32 v246, v246
	v_exp_f32_e32 v247, v247
	v_sub_f32_e32 v248, 1.0, v184
	v_sub_f32_e32 v249, 1.0, v185
	v_sub_f32_e32 v250, 1.0, v186
	v_sub_f32_e32 v251, 1.0, v187
	v_add_f32_e32 v244, 1.0, v244
	v_add_f32_e32 v245, 1.0, v245
	v_add_f32_e32 v246, 1.0, v246
	v_add_f32_e32 v247, 1.0, v247
	v_rcp_f32_e32 v244, v244
	v_rcp_f32_e32 v245, v245
	v_rcp_f32_e32 v246, v246
	v_rcp_f32_e32 v247, v247
	v_fma_f32 v244, v244, v248, v184
	v_fma_f32 v245, v245, v249, v185
	v_fma_f32 v246, v246, v250, v186
	v_fma_f32 v247, v247, v251, v187
	v_cmp_gt_f32_e64 vcc, s74, v244
	v_cmp_gt_f32_e64 s[34:35], s74, v245
	v_cmp_gt_f32_e64 s[40:41], s74, v246
	v_cmp_gt_f32_e64 s[42:43], s74, v247
	v_cndmask_b32_e64 v192, 0, 32, vcc
	v_cndmask_b32_e64 v193, 0, 32, s[34:35]
	v_cndmask_b32_e64 v196, 0, 32, s[40:41]
	v_cndmask_b32_e64 v197, 0, 32, s[42:43]
	v_cndmask_b32_e64 v188, 0, v171, vcc
	v_cndmask_b32_e64 v189, 0, v171, s[34:35]
	v_cndmask_b32_e64 v190, 0, v171, s[40:41]
	v_cndmask_b32_e64 v191, 0, v171, s[42:43]
	v_ldexp_f32 v244, v244, v192
	v_ldexp_f32 v245, v245, v193
	v_ldexp_f32 v246, v246, v196
	v_ldexp_f32 v247, v247, v197
	v_log_f32_e32 v244, v244
	v_log_f32_e32 v245, v245
	v_log_f32_e32 v246, v246
	v_log_f32_e32 v247, v247
	v_mul_f32_e32 v248, 0x3f317217, v244
	v_mul_f32_e32 v249, 0x3f317217, v245
	v_mul_f32_e32 v250, 0x3f317217, v246
	v_mul_f32_e32 v251, 0x3f317217, v247
	v_fma_f32 v192, v244, s75, -v248
	v_fma_f32 v193, v245, s75, -v249
	v_fma_f32 v196, v246, s75, -v250
	v_fma_f32 v197, v247, s75, -v251
	v_fmac_f32_e32 v192, 0x3377d1cf, v244
	v_fmac_f32_e32 v193, 0x3377d1cf, v245
	v_fmac_f32_e32 v196, 0x3377d1cf, v246
	v_fmac_f32_e32 v197, 0x3377d1cf, v247
	v_fmac_f32_e32 v192, 0x3f317217, v244
	v_fmac_f32_e32 v193, 0x3f317217, v245
	v_fmac_f32_e32 v196, 0x3f317217, v246
	v_fmac_f32_e32 v197, 0x3f317217, v247
	v_cmp_lt_f32_e64 vcc, |v244|, s76
	v_cmp_lt_f32_e64 s[34:35], |v245|, s76
	v_cmp_lt_f32_e64 s[40:41], |v246|, s76
	v_cmp_lt_f32_e64 s[42:43], |v247|, s76
	v_cndmask_b32_e64 v244, v244, v192, vcc
	v_cndmask_b32_e64 v245, v245, v193, s[34:35]
	v_cndmask_b32_e64 v246, v246, v196, s[40:41]
	v_cndmask_b32_e64 v247, v247, v197, s[42:43]
	v_sub_f32_e32 v34, v244, v188
	v_sub_f32_e32 v35, v245, v189
	v_sub_f32_e32 v36, v246, v190
	v_sub_f32_e32 v37, v247, v191
	v_cvt_pk_bf16_f32 v42, v42, v43
	v_cvt_pk_bf16_f32 v43, v44, v45
	v_cvt_pk_bf16_f32 v44, v34, v35
	v_cvt_pk_bf16_f32 v45, v36, v37
	global_store_dwordx4 v[164:165], v[42:45], off offset:256
	v_lshl_add_u64 v[164:165], v[164:165], 0, s[8:9]
	v_mul_f32_e32 v244, 0xbfb8aa3b, v58
	v_mul_f32_e32 v245, 0xbfb8aa3b, v59
	v_mul_f32_e32 v246, 0xbfb8aa3b, v60
	v_mul_f32_e32 v247, 0xbfb8aa3b, v61
	v_exp_f32_e32 v244, v244
	v_exp_f32_e32 v245, v245
	v_exp_f32_e32 v246, v246
	v_exp_f32_e32 v247, v247
	v_sub_f32_e32 v248, 1.0, v172
	v_sub_f32_e32 v249, 1.0, v173
	v_sub_f32_e32 v250, 1.0, v174
	v_sub_f32_e32 v251, 1.0, v175
	v_add_f32_e32 v244, 1.0, v244
	v_add_f32_e32 v245, 1.0, v245
	v_add_f32_e32 v246, 1.0, v246
	v_add_f32_e32 v247, 1.0, v247
	v_rcp_f32_e32 v244, v244
	v_rcp_f32_e32 v245, v245
	v_rcp_f32_e32 v246, v246
	v_rcp_f32_e32 v247, v247
	v_fma_f32 v244, v244, v248, v172
	v_fma_f32 v245, v245, v249, v173
	v_fma_f32 v246, v246, v250, v174
	v_fma_f32 v247, v247, v251, v175
	v_cmp_gt_f32_e64 vcc, s74, v244
	v_cmp_gt_f32_e64 s[34:35], s74, v245
	v_cmp_gt_f32_e64 s[40:41], s74, v246
	v_cmp_gt_f32_e64 s[42:43], s74, v247
	v_cndmask_b32_e64 v192, 0, 32, vcc
	v_cndmask_b32_e64 v193, 0, 32, s[34:35]
	v_cndmask_b32_e64 v196, 0, 32, s[40:41]
	v_cndmask_b32_e64 v197, 0, 32, s[42:43]
	v_cndmask_b32_e64 v188, 0, v171, vcc
	v_cndmask_b32_e64 v189, 0, v171, s[34:35]
	v_cndmask_b32_e64 v190, 0, v171, s[40:41]
	v_cndmask_b32_e64 v191, 0, v171, s[42:43]
	v_ldexp_f32 v244, v244, v192
	v_ldexp_f32 v245, v245, v193
	v_ldexp_f32 v246, v246, v196
	v_ldexp_f32 v247, v247, v197
	v_log_f32_e32 v244, v244
	v_log_f32_e32 v245, v245
	v_log_f32_e32 v246, v246
	v_log_f32_e32 v247, v247
	v_mul_f32_e32 v248, 0x3f317217, v244
	v_mul_f32_e32 v249, 0x3f317217, v245
	v_mul_f32_e32 v250, 0x3f317217, v246
	v_mul_f32_e32 v251, 0x3f317217, v247
	v_fma_f32 v192, v244, s75, -v248
	v_fma_f32 v193, v245, s75, -v249
	v_fma_f32 v196, v246, s75, -v250
	v_fma_f32 v197, v247, s75, -v251
	v_fmac_f32_e32 v192, 0x3377d1cf, v244
	v_fmac_f32_e32 v193, 0x3377d1cf, v245
	v_fmac_f32_e32 v196, 0x3377d1cf, v246
	v_fmac_f32_e32 v197, 0x3377d1cf, v247
	v_fmac_f32_e32 v192, 0x3f317217, v244
	v_fmac_f32_e32 v193, 0x3f317217, v245
	v_fmac_f32_e32 v196, 0x3f317217, v246
	v_fmac_f32_e32 v197, 0x3f317217, v247
	v_cmp_lt_f32_e64 vcc, |v244|, s76
	v_cmp_lt_f32_e64 s[34:35], |v245|, s76
	v_cmp_lt_f32_e64 s[40:41], |v246|, s76
	v_cmp_lt_f32_e64 s[42:43], |v247|, s76
	v_cndmask_b32_e64 v244, v244, v192, vcc
	v_cndmask_b32_e64 v245, v245, v193, s[34:35]
	v_cndmask_b32_e64 v246, v246, v196, s[40:41]
	v_cndmask_b32_e64 v247, v247, v197, s[42:43]
	v_sub_f32_e32 v58, v244, v188
	v_sub_f32_e32 v59, v245, v189
	v_sub_f32_e32 v60, v246, v190
	v_sub_f32_e32 v61, v247, v191
	v_mul_f32_e32 v244, 0xbfb8aa3b, v54
	v_mul_f32_e32 v245, 0xbfb8aa3b, v55
	v_mul_f32_e32 v246, 0xbfb8aa3b, v56
	v_mul_f32_e32 v247, 0xbfb8aa3b, v57
	v_exp_f32_e32 v244, v244
	v_exp_f32_e32 v245, v245
	v_exp_f32_e32 v246, v246
	v_exp_f32_e32 v247, v247
	v_sub_f32_e32 v248, 1.0, v176
	v_sub_f32_e32 v249, 1.0, v177
	v_sub_f32_e32 v250, 1.0, v178
	v_sub_f32_e32 v251, 1.0, v179
	v_add_f32_e32 v244, 1.0, v244
	v_add_f32_e32 v245, 1.0, v245
	v_add_f32_e32 v246, 1.0, v246
	v_add_f32_e32 v247, 1.0, v247
	v_rcp_f32_e32 v244, v244
	v_rcp_f32_e32 v245, v245
	v_rcp_f32_e32 v246, v246
	v_rcp_f32_e32 v247, v247
	v_fma_f32 v244, v244, v248, v176
	v_fma_f32 v245, v245, v249, v177
	v_fma_f32 v246, v246, v250, v178
	v_fma_f32 v247, v247, v251, v179
	v_cmp_gt_f32_e64 vcc, s74, v244
	v_cmp_gt_f32_e64 s[34:35], s74, v245
	v_cmp_gt_f32_e64 s[40:41], s74, v246
	v_cmp_gt_f32_e64 s[42:43], s74, v247
	v_cndmask_b32_e64 v192, 0, 32, vcc
	v_cndmask_b32_e64 v193, 0, 32, s[34:35]
	v_cndmask_b32_e64 v196, 0, 32, s[40:41]
	v_cndmask_b32_e64 v197, 0, 32, s[42:43]
	v_cndmask_b32_e64 v188, 0, v171, vcc
	v_cndmask_b32_e64 v189, 0, v171, s[34:35]
	v_cndmask_b32_e64 v190, 0, v171, s[40:41]
	v_cndmask_b32_e64 v191, 0, v171, s[42:43]
	v_ldexp_f32 v244, v244, v192
	v_ldexp_f32 v245, v245, v193
	v_ldexp_f32 v246, v246, v196
	v_ldexp_f32 v247, v247, v197
	v_log_f32_e32 v244, v244
	v_log_f32_e32 v245, v245
	v_log_f32_e32 v246, v246
	v_log_f32_e32 v247, v247
	v_mul_f32_e32 v248, 0x3f317217, v244
	v_mul_f32_e32 v249, 0x3f317217, v245
	v_mul_f32_e32 v250, 0x3f317217, v246
	v_mul_f32_e32 v251, 0x3f317217, v247
	v_fma_f32 v192, v244, s75, -v248
	v_fma_f32 v193, v245, s75, -v249
	v_fma_f32 v196, v246, s75, -v250
	v_fma_f32 v197, v247, s75, -v251
	v_fmac_f32_e32 v192, 0x3377d1cf, v244
	v_fmac_f32_e32 v193, 0x3377d1cf, v245
	v_fmac_f32_e32 v196, 0x3377d1cf, v246
	v_fmac_f32_e32 v197, 0x3377d1cf, v247
	v_fmac_f32_e32 v192, 0x3f317217, v244
	v_fmac_f32_e32 v193, 0x3f317217, v245
	v_fmac_f32_e32 v196, 0x3f317217, v246
	v_fmac_f32_e32 v197, 0x3f317217, v247
	v_cmp_lt_f32_e64 vcc, |v244|, s76
	v_cmp_lt_f32_e64 s[34:35], |v245|, s76
	v_cmp_lt_f32_e64 s[40:41], |v246|, s76
	v_cmp_lt_f32_e64 s[42:43], |v247|, s76
	v_cndmask_b32_e64 v244, v244, v192, vcc
	v_cndmask_b32_e64 v245, v245, v193, s[34:35]
	v_cndmask_b32_e64 v246, v246, v196, s[40:41]
	v_cndmask_b32_e64 v247, v247, v197, s[42:43]
	v_sub_f32_e32 v54, v244, v188
	v_sub_f32_e32 v55, v245, v189
	v_sub_f32_e32 v56, v246, v190
	v_sub_f32_e32 v57, v247, v191
	v_cvt_pk_bf16_f32 v58, v58, v59
	v_cvt_pk_bf16_f32 v59, v60, v61
	v_cvt_pk_bf16_f32 v60, v54, v55
	v_cvt_pk_bf16_f32 v61, v56, v57
	global_store_dwordx4 v[164:165], v[58:61], off
	v_mul_f32_e32 v244, 0xbfb8aa3b, v26
	v_mul_f32_e32 v245, 0xbfb8aa3b, v27
	v_mul_f32_e32 v246, 0xbfb8aa3b, v28
	v_mul_f32_e32 v247, 0xbfb8aa3b, v29
	v_exp_f32_e32 v244, v244
	v_exp_f32_e32 v245, v245
	v_exp_f32_e32 v246, v246
	v_exp_f32_e32 v247, v247
	v_sub_f32_e32 v248, 1.0, v180
	v_sub_f32_e32 v249, 1.0, v181
	v_sub_f32_e32 v250, 1.0, v182
	v_sub_f32_e32 v251, 1.0, v183
	v_add_f32_e32 v244, 1.0, v244
	v_add_f32_e32 v245, 1.0, v245
	v_add_f32_e32 v246, 1.0, v246
	v_add_f32_e32 v247, 1.0, v247
	v_rcp_f32_e32 v244, v244
	v_rcp_f32_e32 v245, v245
	v_rcp_f32_e32 v246, v246
	v_rcp_f32_e32 v247, v247
	v_fma_f32 v244, v244, v248, v180
	v_fma_f32 v245, v245, v249, v181
	v_fma_f32 v246, v246, v250, v182
	v_fma_f32 v247, v247, v251, v183
	v_cmp_gt_f32_e64 vcc, s74, v244
	v_cmp_gt_f32_e64 s[34:35], s74, v245
	v_cmp_gt_f32_e64 s[40:41], s74, v246
	v_cmp_gt_f32_e64 s[42:43], s74, v247
	v_cndmask_b32_e64 v192, 0, 32, vcc
	v_cndmask_b32_e64 v193, 0, 32, s[34:35]
	v_cndmask_b32_e64 v196, 0, 32, s[40:41]
	v_cndmask_b32_e64 v197, 0, 32, s[42:43]
	v_cndmask_b32_e64 v188, 0, v171, vcc
	v_cndmask_b32_e64 v189, 0, v171, s[34:35]
	v_cndmask_b32_e64 v190, 0, v171, s[40:41]
	v_cndmask_b32_e64 v191, 0, v171, s[42:43]
	v_ldexp_f32 v244, v244, v192
	v_ldexp_f32 v245, v245, v193
	v_ldexp_f32 v246, v246, v196
	v_ldexp_f32 v247, v247, v197
	v_log_f32_e32 v244, v244
	v_log_f32_e32 v245, v245
	v_log_f32_e32 v246, v246
	v_log_f32_e32 v247, v247
	v_mul_f32_e32 v248, 0x3f317217, v244
	v_mul_f32_e32 v249, 0x3f317217, v245
	v_mul_f32_e32 v250, 0x3f317217, v246
	v_mul_f32_e32 v251, 0x3f317217, v247
	v_fma_f32 v192, v244, s75, -v248
	v_fma_f32 v193, v245, s75, -v249
	v_fma_f32 v196, v246, s75, -v250
	v_fma_f32 v197, v247, s75, -v251
	v_fmac_f32_e32 v192, 0x3377d1cf, v244
	v_fmac_f32_e32 v193, 0x3377d1cf, v245
	v_fmac_f32_e32 v196, 0x3377d1cf, v246
	v_fmac_f32_e32 v197, 0x3377d1cf, v247
	v_fmac_f32_e32 v192, 0x3f317217, v244
	v_fmac_f32_e32 v193, 0x3f317217, v245
	v_fmac_f32_e32 v196, 0x3f317217, v246
	v_fmac_f32_e32 v197, 0x3f317217, v247
	v_cmp_lt_f32_e64 vcc, |v244|, s76
	v_cmp_lt_f32_e64 s[34:35], |v245|, s76
	v_cmp_lt_f32_e64 s[40:41], |v246|, s76
	v_cmp_lt_f32_e64 s[42:43], |v247|, s76
	v_cndmask_b32_e64 v244, v244, v192, vcc
	v_cndmask_b32_e64 v245, v245, v193, s[34:35]
	v_cndmask_b32_e64 v246, v246, v196, s[40:41]
	v_cndmask_b32_e64 v247, v247, v197, s[42:43]
	v_sub_f32_e32 v26, v244, v188
	v_sub_f32_e32 v27, v245, v189
	v_sub_f32_e32 v28, v246, v190
	v_sub_f32_e32 v29, v247, v191
	v_mul_f32_e32 v244, 0xbfb8aa3b, v22
	v_mul_f32_e32 v245, 0xbfb8aa3b, v23
	v_mul_f32_e32 v246, 0xbfb8aa3b, v24
	v_mul_f32_e32 v247, 0xbfb8aa3b, v25
	v_exp_f32_e32 v244, v244
	v_exp_f32_e32 v245, v245
	v_exp_f32_e32 v246, v246
	v_exp_f32_e32 v247, v247
	v_sub_f32_e32 v248, 1.0, v184
	v_sub_f32_e32 v249, 1.0, v185
	v_sub_f32_e32 v250, 1.0, v186
	v_sub_f32_e32 v251, 1.0, v187
	v_add_f32_e32 v244, 1.0, v244
	v_add_f32_e32 v245, 1.0, v245
	v_add_f32_e32 v246, 1.0, v246
	v_add_f32_e32 v247, 1.0, v247
	v_rcp_f32_e32 v244, v244
	v_rcp_f32_e32 v245, v245
	v_rcp_f32_e32 v246, v246
	v_rcp_f32_e32 v247, v247
	v_fma_f32 v244, v244, v248, v184
	v_fma_f32 v245, v245, v249, v185
	v_fma_f32 v246, v246, v250, v186
	v_fma_f32 v247, v247, v251, v187
	v_cmp_gt_f32_e64 vcc, s74, v244
	v_cmp_gt_f32_e64 s[34:35], s74, v245
	v_cmp_gt_f32_e64 s[40:41], s74, v246
	v_cmp_gt_f32_e64 s[42:43], s74, v247
	v_cndmask_b32_e64 v192, 0, 32, vcc
	v_cndmask_b32_e64 v193, 0, 32, s[34:35]
	v_cndmask_b32_e64 v196, 0, 32, s[40:41]
	v_cndmask_b32_e64 v197, 0, 32, s[42:43]
	v_cndmask_b32_e64 v188, 0, v171, vcc
	v_cndmask_b32_e64 v189, 0, v171, s[34:35]
	v_cndmask_b32_e64 v190, 0, v171, s[40:41]
	v_cndmask_b32_e64 v191, 0, v171, s[42:43]
	v_ldexp_f32 v244, v244, v192
	v_ldexp_f32 v245, v245, v193
	v_ldexp_f32 v246, v246, v196
	v_ldexp_f32 v247, v247, v197
	v_log_f32_e32 v244, v244
	v_log_f32_e32 v245, v245
	v_log_f32_e32 v246, v246
	v_log_f32_e32 v247, v247
	v_mul_f32_e32 v248, 0x3f317217, v244
	v_mul_f32_e32 v249, 0x3f317217, v245
	v_mul_f32_e32 v250, 0x3f317217, v246
	v_mul_f32_e32 v251, 0x3f317217, v247
	v_fma_f32 v192, v244, s75, -v248
	v_fma_f32 v193, v245, s75, -v249
	v_fma_f32 v196, v246, s75, -v250
	v_fma_f32 v197, v247, s75, -v251
	v_fmac_f32_e32 v192, 0x3377d1cf, v244
	v_fmac_f32_e32 v193, 0x3377d1cf, v245
	v_fmac_f32_e32 v196, 0x3377d1cf, v246
	v_fmac_f32_e32 v197, 0x3377d1cf, v247
	v_fmac_f32_e32 v192, 0x3f317217, v244
	v_fmac_f32_e32 v193, 0x3f317217, v245
	v_fmac_f32_e32 v196, 0x3f317217, v246
	v_fmac_f32_e32 v197, 0x3f317217, v247
	v_cmp_lt_f32_e64 vcc, |v244|, s76
	v_cmp_lt_f32_e64 s[34:35], |v245|, s76
	v_cmp_lt_f32_e64 s[40:41], |v246|, s76
	v_cmp_lt_f32_e64 s[42:43], |v247|, s76
	v_cndmask_b32_e64 v244, v244, v192, vcc
	v_cndmask_b32_e64 v245, v245, v193, s[34:35]
	v_cndmask_b32_e64 v246, v246, v196, s[40:41]
	v_cndmask_b32_e64 v247, v247, v197, s[42:43]
	v_sub_f32_e32 v22, v244, v188
	v_sub_f32_e32 v23, v245, v189
	v_sub_f32_e32 v24, v246, v190
	v_sub_f32_e32 v25, v247, v191
	v_cvt_pk_bf16_f32 v26, v26, v27
	v_cvt_pk_bf16_f32 v27, v28, v29
	v_cvt_pk_bf16_f32 v28, v22, v23
	v_cvt_pk_bf16_f32 v29, v24, v25
	global_store_dwordx4 v[164:165], v[26:29], off offset:256
	v_lshl_add_u64 v[164:165], v[164:165], 0, s[8:9]
	v_mul_f32_e32 v244, 0xbfb8aa3b, v50
	v_mul_f32_e32 v245, 0xbfb8aa3b, v51
	v_mul_f32_e32 v246, 0xbfb8aa3b, v52
	v_mul_f32_e32 v247, 0xbfb8aa3b, v53
	v_exp_f32_e32 v244, v244
	v_exp_f32_e32 v245, v245
	v_exp_f32_e32 v246, v246
	v_exp_f32_e32 v247, v247
	v_sub_f32_e32 v248, 1.0, v172
	v_sub_f32_e32 v249, 1.0, v173
	v_sub_f32_e32 v250, 1.0, v174
	v_sub_f32_e32 v251, 1.0, v175
	v_add_f32_e32 v244, 1.0, v244
	v_add_f32_e32 v245, 1.0, v245
	v_add_f32_e32 v246, 1.0, v246
	v_add_f32_e32 v247, 1.0, v247
	v_rcp_f32_e32 v244, v244
	v_rcp_f32_e32 v245, v245
	v_rcp_f32_e32 v246, v246
	v_rcp_f32_e32 v247, v247
	v_fma_f32 v244, v244, v248, v172
	v_fma_f32 v245, v245, v249, v173
	v_fma_f32 v246, v246, v250, v174
	v_fma_f32 v247, v247, v251, v175
	v_cmp_gt_f32_e64 vcc, s74, v244
	v_cmp_gt_f32_e64 s[34:35], s74, v245
	v_cmp_gt_f32_e64 s[40:41], s74, v246
	v_cmp_gt_f32_e64 s[42:43], s74, v247
	v_cndmask_b32_e64 v192, 0, 32, vcc
	v_cndmask_b32_e64 v193, 0, 32, s[34:35]
	v_cndmask_b32_e64 v196, 0, 32, s[40:41]
	v_cndmask_b32_e64 v197, 0, 32, s[42:43]
	v_cndmask_b32_e64 v188, 0, v171, vcc
	v_cndmask_b32_e64 v189, 0, v171, s[34:35]
	v_cndmask_b32_e64 v190, 0, v171, s[40:41]
	v_cndmask_b32_e64 v191, 0, v171, s[42:43]
	v_ldexp_f32 v244, v244, v192
	v_ldexp_f32 v245, v245, v193
	v_ldexp_f32 v246, v246, v196
	v_ldexp_f32 v247, v247, v197
	v_log_f32_e32 v244, v244
	v_log_f32_e32 v245, v245
	v_log_f32_e32 v246, v246
	v_log_f32_e32 v247, v247
	v_mul_f32_e32 v248, 0x3f317217, v244
	v_mul_f32_e32 v249, 0x3f317217, v245
	v_mul_f32_e32 v250, 0x3f317217, v246
	v_mul_f32_e32 v251, 0x3f317217, v247
	v_fma_f32 v192, v244, s75, -v248
	v_fma_f32 v193, v245, s75, -v249
	v_fma_f32 v196, v246, s75, -v250
	v_fma_f32 v197, v247, s75, -v251
	v_fmac_f32_e32 v192, 0x3377d1cf, v244
	v_fmac_f32_e32 v193, 0x3377d1cf, v245
	v_fmac_f32_e32 v196, 0x3377d1cf, v246
	v_fmac_f32_e32 v197, 0x3377d1cf, v247
	v_fmac_f32_e32 v192, 0x3f317217, v244
	v_fmac_f32_e32 v193, 0x3f317217, v245
	v_fmac_f32_e32 v196, 0x3f317217, v246
	v_fmac_f32_e32 v197, 0x3f317217, v247
	v_cmp_lt_f32_e64 vcc, |v244|, s76
	v_cmp_lt_f32_e64 s[34:35], |v245|, s76
	v_cmp_lt_f32_e64 s[40:41], |v246|, s76
	v_cmp_lt_f32_e64 s[42:43], |v247|, s76
	v_cndmask_b32_e64 v244, v244, v192, vcc
	v_cndmask_b32_e64 v245, v245, v193, s[34:35]
	v_cndmask_b32_e64 v246, v246, v196, s[40:41]
	v_cndmask_b32_e64 v247, v247, v197, s[42:43]
	v_sub_f32_e32 v50, v244, v188
	v_sub_f32_e32 v51, v245, v189
	v_sub_f32_e32 v52, v246, v190
	v_sub_f32_e32 v53, v247, v191
	v_mul_f32_e32 v244, 0xbfb8aa3b, v46
	v_mul_f32_e32 v245, 0xbfb8aa3b, v47
	v_mul_f32_e32 v246, 0xbfb8aa3b, v48
	v_mul_f32_e32 v247, 0xbfb8aa3b, v49
	v_exp_f32_e32 v244, v244
	v_exp_f32_e32 v245, v245
	v_exp_f32_e32 v246, v246
	v_exp_f32_e32 v247, v247
	v_sub_f32_e32 v248, 1.0, v176
	v_sub_f32_e32 v249, 1.0, v177
	v_sub_f32_e32 v250, 1.0, v178
	v_sub_f32_e32 v251, 1.0, v179
	v_add_f32_e32 v244, 1.0, v244
	v_add_f32_e32 v245, 1.0, v245
	v_add_f32_e32 v246, 1.0, v246
	v_add_f32_e32 v247, 1.0, v247
	v_rcp_f32_e32 v244, v244
	v_rcp_f32_e32 v245, v245
	v_rcp_f32_e32 v246, v246
	v_rcp_f32_e32 v247, v247
	v_fma_f32 v244, v244, v248, v176
	v_fma_f32 v245, v245, v249, v177
	v_fma_f32 v246, v246, v250, v178
	v_fma_f32 v247, v247, v251, v179
	v_cmp_gt_f32_e64 vcc, s74, v244
	v_cmp_gt_f32_e64 s[34:35], s74, v245
	v_cmp_gt_f32_e64 s[40:41], s74, v246
	v_cmp_gt_f32_e64 s[42:43], s74, v247
	v_cndmask_b32_e64 v192, 0, 32, vcc
	v_cndmask_b32_e64 v193, 0, 32, s[34:35]
	v_cndmask_b32_e64 v196, 0, 32, s[40:41]
	v_cndmask_b32_e64 v197, 0, 32, s[42:43]
	v_cndmask_b32_e64 v188, 0, v171, vcc
	v_cndmask_b32_e64 v189, 0, v171, s[34:35]
	v_cndmask_b32_e64 v190, 0, v171, s[40:41]
	v_cndmask_b32_e64 v191, 0, v171, s[42:43]
	v_ldexp_f32 v244, v244, v192
	v_ldexp_f32 v245, v245, v193
	v_ldexp_f32 v246, v246, v196
	v_ldexp_f32 v247, v247, v197
	v_log_f32_e32 v244, v244
	v_log_f32_e32 v245, v245
	v_log_f32_e32 v246, v246
	v_log_f32_e32 v247, v247
	v_mul_f32_e32 v248, 0x3f317217, v244
	v_mul_f32_e32 v249, 0x3f317217, v245
	v_mul_f32_e32 v250, 0x3f317217, v246
	v_mul_f32_e32 v251, 0x3f317217, v247
	v_fma_f32 v192, v244, s75, -v248
	v_fma_f32 v193, v245, s75, -v249
	v_fma_f32 v196, v246, s75, -v250
	v_fma_f32 v197, v247, s75, -v251
	v_fmac_f32_e32 v192, 0x3377d1cf, v244
	v_fmac_f32_e32 v193, 0x3377d1cf, v245
	v_fmac_f32_e32 v196, 0x3377d1cf, v246
	v_fmac_f32_e32 v197, 0x3377d1cf, v247
	v_fmac_f32_e32 v192, 0x3f317217, v244
	v_fmac_f32_e32 v193, 0x3f317217, v245
	v_fmac_f32_e32 v196, 0x3f317217, v246
	v_fmac_f32_e32 v197, 0x3f317217, v247
	v_cmp_lt_f32_e64 vcc, |v244|, s76
	v_cmp_lt_f32_e64 s[34:35], |v245|, s76
	v_cmp_lt_f32_e64 s[40:41], |v246|, s76
	v_cmp_lt_f32_e64 s[42:43], |v247|, s76
	v_cndmask_b32_e64 v244, v244, v192, vcc
	v_cndmask_b32_e64 v245, v245, v193, s[34:35]
	v_cndmask_b32_e64 v246, v246, v196, s[40:41]
	v_cndmask_b32_e64 v247, v247, v197, s[42:43]
	v_sub_f32_e32 v46, v244, v188
	v_sub_f32_e32 v47, v245, v189
	v_sub_f32_e32 v48, v246, v190
	v_sub_f32_e32 v49, v247, v191
	v_cvt_pk_bf16_f32 v50, v50, v51
	v_cvt_pk_bf16_f32 v51, v52, v53
	v_cvt_pk_bf16_f32 v52, v46, v47
	v_cvt_pk_bf16_f32 v53, v48, v49
	global_store_dwordx4 v[164:165], v[50:53], off
	v_mul_f32_e32 v244, 0xbfb8aa3b, v18
	v_mul_f32_e32 v245, 0xbfb8aa3b, v19
	v_mul_f32_e32 v246, 0xbfb8aa3b, v20
	v_mul_f32_e32 v247, 0xbfb8aa3b, v21
	v_exp_f32_e32 v244, v244
	v_exp_f32_e32 v245, v245
	v_exp_f32_e32 v246, v246
	v_exp_f32_e32 v247, v247
	v_sub_f32_e32 v248, 1.0, v180
	v_sub_f32_e32 v249, 1.0, v181
	v_sub_f32_e32 v250, 1.0, v182
	v_sub_f32_e32 v251, 1.0, v183
	v_add_f32_e32 v244, 1.0, v244
	v_add_f32_e32 v245, 1.0, v245
	v_add_f32_e32 v246, 1.0, v246
	v_add_f32_e32 v247, 1.0, v247
	v_rcp_f32_e32 v244, v244
	v_rcp_f32_e32 v245, v245
	v_rcp_f32_e32 v246, v246
	v_rcp_f32_e32 v247, v247
	v_fma_f32 v244, v244, v248, v180
	v_fma_f32 v245, v245, v249, v181
	v_fma_f32 v246, v246, v250, v182
	v_fma_f32 v247, v247, v251, v183
	v_cmp_gt_f32_e64 vcc, s74, v244
	v_cmp_gt_f32_e64 s[34:35], s74, v245
	v_cmp_gt_f32_e64 s[40:41], s74, v246
	v_cmp_gt_f32_e64 s[42:43], s74, v247
	v_cndmask_b32_e64 v192, 0, 32, vcc
	v_cndmask_b32_e64 v193, 0, 32, s[34:35]
	v_cndmask_b32_e64 v196, 0, 32, s[40:41]
	v_cndmask_b32_e64 v197, 0, 32, s[42:43]
	v_cndmask_b32_e64 v188, 0, v171, vcc
	v_cndmask_b32_e64 v189, 0, v171, s[34:35]
	v_cndmask_b32_e64 v190, 0, v171, s[40:41]
	v_cndmask_b32_e64 v191, 0, v171, s[42:43]
	v_ldexp_f32 v244, v244, v192
	v_ldexp_f32 v245, v245, v193
	v_ldexp_f32 v246, v246, v196
	v_ldexp_f32 v247, v247, v197
	v_log_f32_e32 v244, v244
	v_log_f32_e32 v245, v245
	v_log_f32_e32 v246, v246
	v_log_f32_e32 v247, v247
	v_mul_f32_e32 v248, 0x3f317217, v244
	v_mul_f32_e32 v249, 0x3f317217, v245
	v_mul_f32_e32 v250, 0x3f317217, v246
	v_mul_f32_e32 v251, 0x3f317217, v247
	v_fma_f32 v192, v244, s75, -v248
	v_fma_f32 v193, v245, s75, -v249
	v_fma_f32 v196, v246, s75, -v250
	v_fma_f32 v197, v247, s75, -v251
	v_fmac_f32_e32 v192, 0x3377d1cf, v244
	v_fmac_f32_e32 v193, 0x3377d1cf, v245
	v_fmac_f32_e32 v196, 0x3377d1cf, v246
	v_fmac_f32_e32 v197, 0x3377d1cf, v247
	v_fmac_f32_e32 v192, 0x3f317217, v244
	v_fmac_f32_e32 v193, 0x3f317217, v245
	v_fmac_f32_e32 v196, 0x3f317217, v246
	v_fmac_f32_e32 v197, 0x3f317217, v247
	v_cmp_lt_f32_e64 vcc, |v244|, s76
	v_cmp_lt_f32_e64 s[34:35], |v245|, s76
	v_cmp_lt_f32_e64 s[40:41], |v246|, s76
	v_cmp_lt_f32_e64 s[42:43], |v247|, s76
	v_cndmask_b32_e64 v244, v244, v192, vcc
	v_cndmask_b32_e64 v245, v245, v193, s[34:35]
	v_cndmask_b32_e64 v246, v246, v196, s[40:41]
	v_cndmask_b32_e64 v247, v247, v197, s[42:43]
	v_sub_f32_e32 v18, v244, v188
	v_sub_f32_e32 v19, v245, v189
	v_sub_f32_e32 v20, v246, v190
	v_sub_f32_e32 v21, v247, v191
	v_mul_f32_e32 v244, 0xbfb8aa3b, v14
	v_mul_f32_e32 v245, 0xbfb8aa3b, v15
	v_mul_f32_e32 v246, 0xbfb8aa3b, v16
	v_mul_f32_e32 v247, 0xbfb8aa3b, v17
	v_exp_f32_e32 v244, v244
	v_exp_f32_e32 v245, v245
	v_exp_f32_e32 v246, v246
	v_exp_f32_e32 v247, v247
	v_sub_f32_e32 v248, 1.0, v184
	v_sub_f32_e32 v249, 1.0, v185
	v_sub_f32_e32 v250, 1.0, v186
	v_sub_f32_e32 v251, 1.0, v187
	v_add_f32_e32 v244, 1.0, v244
	v_add_f32_e32 v245, 1.0, v245
	v_add_f32_e32 v246, 1.0, v246
	v_add_f32_e32 v247, 1.0, v247
	v_rcp_f32_e32 v244, v244
	v_rcp_f32_e32 v245, v245
	v_rcp_f32_e32 v246, v246
	v_rcp_f32_e32 v247, v247
	v_fma_f32 v244, v244, v248, v184
	v_fma_f32 v245, v245, v249, v185
	v_fma_f32 v246, v246, v250, v186
	v_fma_f32 v247, v247, v251, v187
	v_cmp_gt_f32_e64 vcc, s74, v244
	v_cmp_gt_f32_e64 s[34:35], s74, v245
	v_cmp_gt_f32_e64 s[40:41], s74, v246
	v_cmp_gt_f32_e64 s[42:43], s74, v247
	v_cndmask_b32_e64 v192, 0, 32, vcc
	v_cndmask_b32_e64 v193, 0, 32, s[34:35]
	v_cndmask_b32_e64 v196, 0, 32, s[40:41]
	v_cndmask_b32_e64 v197, 0, 32, s[42:43]
	v_cndmask_b32_e64 v188, 0, v171, vcc
	v_cndmask_b32_e64 v189, 0, v171, s[34:35]
	v_cndmask_b32_e64 v190, 0, v171, s[40:41]
	v_cndmask_b32_e64 v191, 0, v171, s[42:43]
	v_ldexp_f32 v244, v244, v192
	v_ldexp_f32 v245, v245, v193
	v_ldexp_f32 v246, v246, v196
	v_ldexp_f32 v247, v247, v197
	v_log_f32_e32 v244, v244
	v_log_f32_e32 v245, v245
	v_log_f32_e32 v246, v246
	v_log_f32_e32 v247, v247
	v_mul_f32_e32 v248, 0x3f317217, v244
	v_mul_f32_e32 v249, 0x3f317217, v245
	v_mul_f32_e32 v250, 0x3f317217, v246
	v_mul_f32_e32 v251, 0x3f317217, v247
	v_fma_f32 v192, v244, s75, -v248
	v_fma_f32 v193, v245, s75, -v249
	v_fma_f32 v196, v246, s75, -v250
	v_fma_f32 v197, v247, s75, -v251
	v_fmac_f32_e32 v192, 0x3377d1cf, v244
	v_fmac_f32_e32 v193, 0x3377d1cf, v245
	v_fmac_f32_e32 v196, 0x3377d1cf, v246
	v_fmac_f32_e32 v197, 0x3377d1cf, v247
	v_fmac_f32_e32 v192, 0x3f317217, v244
	v_fmac_f32_e32 v193, 0x3f317217, v245
	v_fmac_f32_e32 v196, 0x3f317217, v246
	v_fmac_f32_e32 v197, 0x3f317217, v247
	v_cmp_lt_f32_e64 vcc, |v244|, s76
	v_cmp_lt_f32_e64 s[34:35], |v245|, s76
	v_cmp_lt_f32_e64 s[40:41], |v246|, s76
	v_cmp_lt_f32_e64 s[42:43], |v247|, s76
	v_cndmask_b32_e64 v244, v244, v192, vcc
	v_cndmask_b32_e64 v245, v245, v193, s[34:35]
	v_cndmask_b32_e64 v246, v246, v196, s[40:41]
	v_cndmask_b32_e64 v247, v247, v197, s[42:43]
	v_sub_f32_e32 v14, v244, v188
	v_sub_f32_e32 v15, v245, v189
	v_sub_f32_e32 v16, v246, v190
	v_sub_f32_e32 v17, v247, v191
	v_cvt_pk_bf16_f32 v18, v18, v19
	v_cvt_pk_bf16_f32 v19, v20, v21
	v_cvt_pk_bf16_f32 v20, v14, v15
	v_cvt_pk_bf16_f32 v21, v16, v17
	global_store_dwordx4 v[164:165], v[18:21], off offset:256
	v_lshl_add_u64 v[164:165], v[164:165], 0, s[8:9]
	v_mul_f32_e32 v244, 0xbfb8aa3b, v38
	v_mul_f32_e32 v245, 0xbfb8aa3b, v39
	v_mul_f32_e32 v246, 0xbfb8aa3b, v40
	v_mul_f32_e32 v247, 0xbfb8aa3b, v41
	v_exp_f32_e32 v244, v244
	v_exp_f32_e32 v245, v245
	v_exp_f32_e32 v246, v246
	v_exp_f32_e32 v247, v247
	v_sub_f32_e32 v248, 1.0, v172
	v_sub_f32_e32 v249, 1.0, v173
	v_sub_f32_e32 v250, 1.0, v174
	v_sub_f32_e32 v251, 1.0, v175
	v_add_f32_e32 v244, 1.0, v244
	v_add_f32_e32 v245, 1.0, v245
	v_add_f32_e32 v246, 1.0, v246
	v_add_f32_e32 v247, 1.0, v247
	v_rcp_f32_e32 v244, v244
	v_rcp_f32_e32 v245, v245
	v_rcp_f32_e32 v246, v246
	v_rcp_f32_e32 v247, v247
	v_fma_f32 v244, v244, v248, v172
	v_fma_f32 v245, v245, v249, v173
	v_fma_f32 v246, v246, v250, v174
	v_fma_f32 v247, v247, v251, v175
	v_cmp_gt_f32_e64 vcc, s74, v244
	v_cmp_gt_f32_e64 s[34:35], s74, v245
	v_cmp_gt_f32_e64 s[40:41], s74, v246
	v_cmp_gt_f32_e64 s[42:43], s74, v247
	v_cndmask_b32_e64 v192, 0, 32, vcc
	v_cndmask_b32_e64 v193, 0, 32, s[34:35]
	v_cndmask_b32_e64 v196, 0, 32, s[40:41]
	v_cndmask_b32_e64 v197, 0, 32, s[42:43]
	v_cndmask_b32_e64 v188, 0, v171, vcc
	v_cndmask_b32_e64 v189, 0, v171, s[34:35]
	v_cndmask_b32_e64 v190, 0, v171, s[40:41]
	v_cndmask_b32_e64 v191, 0, v171, s[42:43]
	v_ldexp_f32 v244, v244, v192
	v_ldexp_f32 v245, v245, v193
	v_ldexp_f32 v246, v246, v196
	v_ldexp_f32 v247, v247, v197
	v_log_f32_e32 v244, v244
	v_log_f32_e32 v245, v245
	v_log_f32_e32 v246, v246
	v_log_f32_e32 v247, v247
	v_mul_f32_e32 v248, 0x3f317217, v244
	v_mul_f32_e32 v249, 0x3f317217, v245
	v_mul_f32_e32 v250, 0x3f317217, v246
	v_mul_f32_e32 v251, 0x3f317217, v247
	v_fma_f32 v192, v244, s75, -v248
	v_fma_f32 v193, v245, s75, -v249
	v_fma_f32 v196, v246, s75, -v250
	v_fma_f32 v197, v247, s75, -v251
	v_fmac_f32_e32 v192, 0x3377d1cf, v244
	v_fmac_f32_e32 v193, 0x3377d1cf, v245
	v_fmac_f32_e32 v196, 0x3377d1cf, v246
	v_fmac_f32_e32 v197, 0x3377d1cf, v247
	v_fmac_f32_e32 v192, 0x3f317217, v244
	v_fmac_f32_e32 v193, 0x3f317217, v245
	v_fmac_f32_e32 v196, 0x3f317217, v246
	v_fmac_f32_e32 v197, 0x3f317217, v247
	v_cmp_lt_f32_e64 vcc, |v244|, s76
	v_cmp_lt_f32_e64 s[34:35], |v245|, s76
	v_cmp_lt_f32_e64 s[40:41], |v246|, s76
	v_cmp_lt_f32_e64 s[42:43], |v247|, s76
	v_cndmask_b32_e64 v244, v244, v192, vcc
	v_cndmask_b32_e64 v245, v245, v193, s[34:35]
	v_cndmask_b32_e64 v246, v246, v196, s[40:41]
	v_cndmask_b32_e64 v247, v247, v197, s[42:43]
	v_sub_f32_e32 v38, v244, v188
	v_sub_f32_e32 v39, v245, v189
	v_sub_f32_e32 v40, v246, v190
	v_sub_f32_e32 v41, v247, v191
	v_mul_f32_e32 v244, 0xbfb8aa3b, v30
	v_mul_f32_e32 v245, 0xbfb8aa3b, v31
	v_mul_f32_e32 v246, 0xbfb8aa3b, v32
	v_mul_f32_e32 v247, 0xbfb8aa3b, v33
	v_exp_f32_e32 v244, v244
	v_exp_f32_e32 v245, v245
	v_exp_f32_e32 v246, v246
	v_exp_f32_e32 v247, v247
	v_sub_f32_e32 v248, 1.0, v176
	v_sub_f32_e32 v249, 1.0, v177
	v_sub_f32_e32 v250, 1.0, v178
	v_sub_f32_e32 v251, 1.0, v179
	v_add_f32_e32 v244, 1.0, v244
	v_add_f32_e32 v245, 1.0, v245
	v_add_f32_e32 v246, 1.0, v246
	v_add_f32_e32 v247, 1.0, v247
	v_rcp_f32_e32 v244, v244
	v_rcp_f32_e32 v245, v245
	v_rcp_f32_e32 v246, v246
	v_rcp_f32_e32 v247, v247
	v_fma_f32 v244, v244, v248, v176
	v_fma_f32 v245, v245, v249, v177
	v_fma_f32 v246, v246, v250, v178
	v_fma_f32 v247, v247, v251, v179
	v_cmp_gt_f32_e64 vcc, s74, v244
	v_cmp_gt_f32_e64 s[34:35], s74, v245
	v_cmp_gt_f32_e64 s[40:41], s74, v246
	v_cmp_gt_f32_e64 s[42:43], s74, v247
	v_cndmask_b32_e64 v192, 0, 32, vcc
	v_cndmask_b32_e64 v193, 0, 32, s[34:35]
	v_cndmask_b32_e64 v196, 0, 32, s[40:41]
	v_cndmask_b32_e64 v197, 0, 32, s[42:43]
	v_cndmask_b32_e64 v188, 0, v171, vcc
	v_cndmask_b32_e64 v189, 0, v171, s[34:35]
	v_cndmask_b32_e64 v190, 0, v171, s[40:41]
	v_cndmask_b32_e64 v191, 0, v171, s[42:43]
	v_ldexp_f32 v244, v244, v192
	v_ldexp_f32 v245, v245, v193
	v_ldexp_f32 v246, v246, v196
	v_ldexp_f32 v247, v247, v197
	v_log_f32_e32 v244, v244
	v_log_f32_e32 v245, v245
	v_log_f32_e32 v246, v246
	v_log_f32_e32 v247, v247
	v_mul_f32_e32 v248, 0x3f317217, v244
	v_mul_f32_e32 v249, 0x3f317217, v245
	v_mul_f32_e32 v250, 0x3f317217, v246
	v_mul_f32_e32 v251, 0x3f317217, v247
	v_fma_f32 v192, v244, s75, -v248
	v_fma_f32 v193, v245, s75, -v249
	v_fma_f32 v196, v246, s75, -v250
	v_fma_f32 v197, v247, s75, -v251
	v_fmac_f32_e32 v192, 0x3377d1cf, v244
	v_fmac_f32_e32 v193, 0x3377d1cf, v245
	v_fmac_f32_e32 v196, 0x3377d1cf, v246
	v_fmac_f32_e32 v197, 0x3377d1cf, v247
	v_fmac_f32_e32 v192, 0x3f317217, v244
	v_fmac_f32_e32 v193, 0x3f317217, v245
	v_fmac_f32_e32 v196, 0x3f317217, v246
	v_fmac_f32_e32 v197, 0x3f317217, v247
	v_cmp_lt_f32_e64 vcc, |v244|, s76
	v_cmp_lt_f32_e64 s[34:35], |v245|, s76
	v_cmp_lt_f32_e64 s[40:41], |v246|, s76
	v_cmp_lt_f32_e64 s[42:43], |v247|, s76
	v_cndmask_b32_e64 v244, v244, v192, vcc
	v_cndmask_b32_e64 v245, v245, v193, s[34:35]
	v_cndmask_b32_e64 v246, v246, v196, s[40:41]
	v_cndmask_b32_e64 v247, v247, v197, s[42:43]
	v_sub_f32_e32 v30, v244, v188
	v_sub_f32_e32 v31, v245, v189
	v_sub_f32_e32 v32, v246, v190
	v_sub_f32_e32 v33, v247, v191
	v_cvt_pk_bf16_f32 v38, v38, v39
	v_cvt_pk_bf16_f32 v39, v40, v41
	v_cvt_pk_bf16_f32 v40, v30, v31
	v_cvt_pk_bf16_f32 v41, v32, v33
	global_store_dwordx4 v[164:165], v[38:41], off
	v_mul_f32_e32 v244, 0xbfb8aa3b, v10
	v_mul_f32_e32 v245, 0xbfb8aa3b, v11
	v_mul_f32_e32 v246, 0xbfb8aa3b, v12
	v_mul_f32_e32 v247, 0xbfb8aa3b, v13
	v_exp_f32_e32 v244, v244
	v_exp_f32_e32 v245, v245
	v_exp_f32_e32 v246, v246
	v_exp_f32_e32 v247, v247
	v_sub_f32_e32 v248, 1.0, v180
	v_sub_f32_e32 v249, 1.0, v181
	v_sub_f32_e32 v250, 1.0, v182
	v_sub_f32_e32 v251, 1.0, v183
	v_add_f32_e32 v244, 1.0, v244
	v_add_f32_e32 v245, 1.0, v245
	v_add_f32_e32 v246, 1.0, v246
	v_add_f32_e32 v247, 1.0, v247
	v_rcp_f32_e32 v244, v244
	v_rcp_f32_e32 v245, v245
	v_rcp_f32_e32 v246, v246
	v_rcp_f32_e32 v247, v247
	v_fma_f32 v244, v244, v248, v180
	v_fma_f32 v245, v245, v249, v181
	v_fma_f32 v246, v246, v250, v182
	v_fma_f32 v247, v247, v251, v183
	v_cmp_gt_f32_e64 vcc, s74, v244
	v_cmp_gt_f32_e64 s[34:35], s74, v245
	v_cmp_gt_f32_e64 s[40:41], s74, v246
	v_cmp_gt_f32_e64 s[42:43], s74, v247
	v_cndmask_b32_e64 v192, 0, 32, vcc
	v_cndmask_b32_e64 v193, 0, 32, s[34:35]
	v_cndmask_b32_e64 v196, 0, 32, s[40:41]
	v_cndmask_b32_e64 v197, 0, 32, s[42:43]
	v_cndmask_b32_e64 v188, 0, v171, vcc
	v_cndmask_b32_e64 v189, 0, v171, s[34:35]
	v_cndmask_b32_e64 v190, 0, v171, s[40:41]
	v_cndmask_b32_e64 v191, 0, v171, s[42:43]
	v_ldexp_f32 v244, v244, v192
	v_ldexp_f32 v245, v245, v193
	v_ldexp_f32 v246, v246, v196
	v_ldexp_f32 v247, v247, v197
	v_log_f32_e32 v244, v244
	v_log_f32_e32 v245, v245
	v_log_f32_e32 v246, v246
	v_log_f32_e32 v247, v247
	v_mul_f32_e32 v248, 0x3f317217, v244
	v_mul_f32_e32 v249, 0x3f317217, v245
	v_mul_f32_e32 v250, 0x3f317217, v246
	v_mul_f32_e32 v251, 0x3f317217, v247
	v_fma_f32 v192, v244, s75, -v248
	v_fma_f32 v193, v245, s75, -v249
	v_fma_f32 v196, v246, s75, -v250
	v_fma_f32 v197, v247, s75, -v251
	v_fmac_f32_e32 v192, 0x3377d1cf, v244
	v_fmac_f32_e32 v193, 0x3377d1cf, v245
	v_fmac_f32_e32 v196, 0x3377d1cf, v246
	v_fmac_f32_e32 v197, 0x3377d1cf, v247
	v_fmac_f32_e32 v192, 0x3f317217, v244
	v_fmac_f32_e32 v193, 0x3f317217, v245
	v_fmac_f32_e32 v196, 0x3f317217, v246
	v_fmac_f32_e32 v197, 0x3f317217, v247
	v_cmp_lt_f32_e64 vcc, |v244|, s76
	v_cmp_lt_f32_e64 s[34:35], |v245|, s76
	v_cmp_lt_f32_e64 s[40:41], |v246|, s76
	v_cmp_lt_f32_e64 s[42:43], |v247|, s76
	v_cndmask_b32_e64 v244, v244, v192, vcc
	v_cndmask_b32_e64 v245, v245, v193, s[34:35]
	v_cndmask_b32_e64 v246, v246, v196, s[40:41]
	v_cndmask_b32_e64 v247, v247, v197, s[42:43]
	v_sub_f32_e32 v10, v244, v188
	v_sub_f32_e32 v11, v245, v189
	v_sub_f32_e32 v12, v246, v190
	v_sub_f32_e32 v13, v247, v191
	v_mul_f32_e32 v244, 0xbfb8aa3b, v6
	v_mul_f32_e32 v245, 0xbfb8aa3b, v7
	v_mul_f32_e32 v246, 0xbfb8aa3b, v8
	v_mul_f32_e32 v247, 0xbfb8aa3b, v9
	v_exp_f32_e32 v244, v244
	v_exp_f32_e32 v245, v245
	v_exp_f32_e32 v246, v246
	v_exp_f32_e32 v247, v247
	v_sub_f32_e32 v248, 1.0, v184
	v_sub_f32_e32 v249, 1.0, v185
	v_sub_f32_e32 v250, 1.0, v186
	v_sub_f32_e32 v251, 1.0, v187
	v_add_f32_e32 v244, 1.0, v244
	v_add_f32_e32 v245, 1.0, v245
	v_add_f32_e32 v246, 1.0, v246
	v_add_f32_e32 v247, 1.0, v247
	v_rcp_f32_e32 v244, v244
	v_rcp_f32_e32 v245, v245
	v_rcp_f32_e32 v246, v246
	v_rcp_f32_e32 v247, v247
	v_fma_f32 v244, v244, v248, v184
	v_fma_f32 v245, v245, v249, v185
	v_fma_f32 v246, v246, v250, v186
	v_fma_f32 v247, v247, v251, v187
	v_cmp_gt_f32_e64 vcc, s74, v244
	v_cmp_gt_f32_e64 s[34:35], s74, v245
	v_cmp_gt_f32_e64 s[40:41], s74, v246
	v_cmp_gt_f32_e64 s[42:43], s74, v247
	v_cndmask_b32_e64 v192, 0, 32, vcc
	v_cndmask_b32_e64 v193, 0, 32, s[34:35]
	v_cndmask_b32_e64 v196, 0, 32, s[40:41]
	v_cndmask_b32_e64 v197, 0, 32, s[42:43]
	v_cndmask_b32_e64 v188, 0, v171, vcc
	v_cndmask_b32_e64 v189, 0, v171, s[34:35]
	v_cndmask_b32_e64 v190, 0, v171, s[40:41]
	v_cndmask_b32_e64 v191, 0, v171, s[42:43]
	v_ldexp_f32 v244, v244, v192
	v_ldexp_f32 v245, v245, v193
	v_ldexp_f32 v246, v246, v196
	v_ldexp_f32 v247, v247, v197
	v_log_f32_e32 v244, v244
	v_log_f32_e32 v245, v245
	v_log_f32_e32 v246, v246
	v_log_f32_e32 v247, v247
	v_mul_f32_e32 v248, 0x3f317217, v244
	v_mul_f32_e32 v249, 0x3f317217, v245
	v_mul_f32_e32 v250, 0x3f317217, v246
	v_mul_f32_e32 v251, 0x3f317217, v247
	v_fma_f32 v192, v244, s75, -v248
	v_fma_f32 v193, v245, s75, -v249
	v_fma_f32 v196, v246, s75, -v250
	v_fma_f32 v197, v247, s75, -v251
	v_fmac_f32_e32 v192, 0x3377d1cf, v244
	v_fmac_f32_e32 v193, 0x3377d1cf, v245
	v_fmac_f32_e32 v196, 0x3377d1cf, v246
	v_fmac_f32_e32 v197, 0x3377d1cf, v247
	v_fmac_f32_e32 v192, 0x3f317217, v244
	v_fmac_f32_e32 v193, 0x3f317217, v245
	v_fmac_f32_e32 v196, 0x3f317217, v246
	v_fmac_f32_e32 v197, 0x3f317217, v247
	v_cmp_lt_f32_e64 vcc, |v244|, s76
	v_cmp_lt_f32_e64 s[34:35], |v245|, s76
	v_cmp_lt_f32_e64 s[40:41], |v246|, s76
	v_cmp_lt_f32_e64 s[42:43], |v247|, s76
	v_cndmask_b32_e64 v244, v244, v192, vcc
	v_cndmask_b32_e64 v245, v245, v193, s[34:35]
	v_cndmask_b32_e64 v246, v246, v196, s[40:41]
	v_cndmask_b32_e64 v247, v247, v197, s[42:43]
	v_sub_f32_e32 v6, v244, v188
	v_sub_f32_e32 v7, v245, v189
	v_sub_f32_e32 v8, v246, v190
	v_sub_f32_e32 v9, v247, v191
	v_cvt_pk_bf16_f32 v10, v10, v11
	v_cvt_pk_bf16_f32 v11, v12, v13
	v_cvt_pk_bf16_f32 v12, v6, v7
	v_cvt_pk_bf16_f32 v13, v8, v9
	global_store_dwordx4 v[164:165], v[10:13], off offset:256
	v_lshl_add_u64 v[164:165], v[166:167], 0, s[22:23]
	v_mul_f32_e32 v244, 0xbfb8aa3b, v126
	v_mul_f32_e32 v245, 0xbfb8aa3b, v127
	v_mul_f32_e32 v246, 0xbfb8aa3b, v128
	v_mul_f32_e32 v247, 0xbfb8aa3b, v129
	v_exp_f32_e32 v244, v244
	v_exp_f32_e32 v245, v245
	v_exp_f32_e32 v246, v246
	v_exp_f32_e32 v247, v247
	v_sub_f32_e32 v248, 1.0, v172
	v_sub_f32_e32 v249, 1.0, v173
	v_sub_f32_e32 v250, 1.0, v174
	v_sub_f32_e32 v251, 1.0, v175
	v_add_f32_e32 v244, 1.0, v244
	v_add_f32_e32 v245, 1.0, v245
	v_add_f32_e32 v246, 1.0, v246
	v_add_f32_e32 v247, 1.0, v247
	v_rcp_f32_e32 v244, v244
	v_rcp_f32_e32 v245, v245
	v_rcp_f32_e32 v246, v246
	v_rcp_f32_e32 v247, v247
	v_fma_f32 v244, v244, v248, v172
	v_fma_f32 v245, v245, v249, v173
	v_fma_f32 v246, v246, v250, v174
	v_fma_f32 v247, v247, v251, v175
	v_cmp_gt_f32_e64 vcc, s74, v244
	v_cmp_gt_f32_e64 s[34:35], s74, v245
	v_cmp_gt_f32_e64 s[40:41], s74, v246
	v_cmp_gt_f32_e64 s[42:43], s74, v247
	v_cndmask_b32_e64 v192, 0, 32, vcc
	v_cndmask_b32_e64 v193, 0, 32, s[34:35]
	v_cndmask_b32_e64 v196, 0, 32, s[40:41]
	v_cndmask_b32_e64 v197, 0, 32, s[42:43]
	v_cndmask_b32_e64 v188, 0, v171, vcc
	v_cndmask_b32_e64 v189, 0, v171, s[34:35]
	v_cndmask_b32_e64 v190, 0, v171, s[40:41]
	v_cndmask_b32_e64 v191, 0, v171, s[42:43]
	v_ldexp_f32 v244, v244, v192
	v_ldexp_f32 v245, v245, v193
	v_ldexp_f32 v246, v246, v196
	v_ldexp_f32 v247, v247, v197
	v_log_f32_e32 v244, v244
	v_log_f32_e32 v245, v245
	v_log_f32_e32 v246, v246
	v_log_f32_e32 v247, v247
	v_mul_f32_e32 v248, 0x3f317217, v244
	v_mul_f32_e32 v249, 0x3f317217, v245
	v_mul_f32_e32 v250, 0x3f317217, v246
	v_mul_f32_e32 v251, 0x3f317217, v247
	v_fma_f32 v192, v244, s75, -v248
	v_fma_f32 v193, v245, s75, -v249
	v_fma_f32 v196, v246, s75, -v250
	v_fma_f32 v197, v247, s75, -v251
	v_fmac_f32_e32 v192, 0x3377d1cf, v244
	v_fmac_f32_e32 v193, 0x3377d1cf, v245
	v_fmac_f32_e32 v196, 0x3377d1cf, v246
	v_fmac_f32_e32 v197, 0x3377d1cf, v247
	v_fmac_f32_e32 v192, 0x3f317217, v244
	v_fmac_f32_e32 v193, 0x3f317217, v245
	v_fmac_f32_e32 v196, 0x3f317217, v246
	v_fmac_f32_e32 v197, 0x3f317217, v247
	v_cmp_lt_f32_e64 vcc, |v244|, s76
	v_cmp_lt_f32_e64 s[34:35], |v245|, s76
	v_cmp_lt_f32_e64 s[40:41], |v246|, s76
	v_cmp_lt_f32_e64 s[42:43], |v247|, s76
	v_cndmask_b32_e64 v244, v244, v192, vcc
	v_cndmask_b32_e64 v245, v245, v193, s[34:35]
	v_cndmask_b32_e64 v246, v246, v196, s[40:41]
	v_cndmask_b32_e64 v247, v247, v197, s[42:43]
	v_sub_f32_e32 v126, v244, v188
	v_sub_f32_e32 v127, v245, v189
	v_sub_f32_e32 v128, v246, v190
	v_sub_f32_e32 v129, v247, v191
	v_mul_f32_e32 v244, 0xbfb8aa3b, v122
	v_mul_f32_e32 v245, 0xbfb8aa3b, v123
	v_mul_f32_e32 v246, 0xbfb8aa3b, v124
	v_mul_f32_e32 v247, 0xbfb8aa3b, v125
	v_exp_f32_e32 v244, v244
	v_exp_f32_e32 v245, v245
	v_exp_f32_e32 v246, v246
	v_exp_f32_e32 v247, v247
	v_sub_f32_e32 v248, 1.0, v176
	v_sub_f32_e32 v249, 1.0, v177
	v_sub_f32_e32 v250, 1.0, v178
	v_sub_f32_e32 v251, 1.0, v179
	v_add_f32_e32 v244, 1.0, v244
	v_add_f32_e32 v245, 1.0, v245
	v_add_f32_e32 v246, 1.0, v246
	v_add_f32_e32 v247, 1.0, v247
	v_rcp_f32_e32 v244, v244
	v_rcp_f32_e32 v245, v245
	v_rcp_f32_e32 v246, v246
	v_rcp_f32_e32 v247, v247
	v_fma_f32 v244, v244, v248, v176
	v_fma_f32 v245, v245, v249, v177
	v_fma_f32 v246, v246, v250, v178
	v_fma_f32 v247, v247, v251, v179
	v_cmp_gt_f32_e64 vcc, s74, v244
	v_cmp_gt_f32_e64 s[34:35], s74, v245
	v_cmp_gt_f32_e64 s[40:41], s74, v246
	v_cmp_gt_f32_e64 s[42:43], s74, v247
	v_cndmask_b32_e64 v192, 0, 32, vcc
	v_cndmask_b32_e64 v193, 0, 32, s[34:35]
	v_cndmask_b32_e64 v196, 0, 32, s[40:41]
	v_cndmask_b32_e64 v197, 0, 32, s[42:43]
	v_cndmask_b32_e64 v188, 0, v171, vcc
	v_cndmask_b32_e64 v189, 0, v171, s[34:35]
	v_cndmask_b32_e64 v190, 0, v171, s[40:41]
	v_cndmask_b32_e64 v191, 0, v171, s[42:43]
	v_ldexp_f32 v244, v244, v192
	v_ldexp_f32 v245, v245, v193
	v_ldexp_f32 v246, v246, v196
	v_ldexp_f32 v247, v247, v197
	v_log_f32_e32 v244, v244
	v_log_f32_e32 v245, v245
	v_log_f32_e32 v246, v246
	v_log_f32_e32 v247, v247
	v_mul_f32_e32 v248, 0x3f317217, v244
	v_mul_f32_e32 v249, 0x3f317217, v245
	v_mul_f32_e32 v250, 0x3f317217, v246
	v_mul_f32_e32 v251, 0x3f317217, v247
	v_fma_f32 v192, v244, s75, -v248
	v_fma_f32 v193, v245, s75, -v249
	v_fma_f32 v196, v246, s75, -v250
	v_fma_f32 v197, v247, s75, -v251
	v_fmac_f32_e32 v192, 0x3377d1cf, v244
	v_fmac_f32_e32 v193, 0x3377d1cf, v245
	v_fmac_f32_e32 v196, 0x3377d1cf, v246
	v_fmac_f32_e32 v197, 0x3377d1cf, v247
	v_fmac_f32_e32 v192, 0x3f317217, v244
	v_fmac_f32_e32 v193, 0x3f317217, v245
	v_fmac_f32_e32 v196, 0x3f317217, v246
	v_fmac_f32_e32 v197, 0x3f317217, v247
	v_cmp_lt_f32_e64 vcc, |v244|, s76
	v_cmp_lt_f32_e64 s[34:35], |v245|, s76
	v_cmp_lt_f32_e64 s[40:41], |v246|, s76
	v_cmp_lt_f32_e64 s[42:43], |v247|, s76
	v_cndmask_b32_e64 v244, v244, v192, vcc
	v_cndmask_b32_e64 v245, v245, v193, s[34:35]
	v_cndmask_b32_e64 v246, v246, v196, s[40:41]
	v_cndmask_b32_e64 v247, v247, v197, s[42:43]
	v_sub_f32_e32 v122, v244, v188
	v_sub_f32_e32 v123, v245, v189
	v_sub_f32_e32 v124, v246, v190
	v_sub_f32_e32 v125, v247, v191
	v_cvt_pk_bf16_f32 v126, v126, v127
	v_cvt_pk_bf16_f32 v127, v128, v129
	v_cvt_pk_bf16_f32 v128, v122, v123
	v_cvt_pk_bf16_f32 v129, v124, v125
	global_store_dwordx4 v[164:165], v[126:129], off
	v_mul_f32_e32 v244, 0xbfb8aa3b, v118
	v_mul_f32_e32 v245, 0xbfb8aa3b, v119
	v_mul_f32_e32 v246, 0xbfb8aa3b, v120
	v_mul_f32_e32 v247, 0xbfb8aa3b, v121
	v_exp_f32_e32 v244, v244
	v_exp_f32_e32 v245, v245
	v_exp_f32_e32 v246, v246
	v_exp_f32_e32 v247, v247
	v_sub_f32_e32 v248, 1.0, v180
	v_sub_f32_e32 v249, 1.0, v181
	v_sub_f32_e32 v250, 1.0, v182
	v_sub_f32_e32 v251, 1.0, v183
	v_add_f32_e32 v244, 1.0, v244
	v_add_f32_e32 v245, 1.0, v245
	v_add_f32_e32 v246, 1.0, v246
	v_add_f32_e32 v247, 1.0, v247
	v_rcp_f32_e32 v244, v244
	v_rcp_f32_e32 v245, v245
	v_rcp_f32_e32 v246, v246
	v_rcp_f32_e32 v247, v247
	v_fma_f32 v244, v244, v248, v180
	v_fma_f32 v245, v245, v249, v181
	v_fma_f32 v246, v246, v250, v182
	v_fma_f32 v247, v247, v251, v183
	v_cmp_gt_f32_e64 vcc, s74, v244
	v_cmp_gt_f32_e64 s[34:35], s74, v245
	v_cmp_gt_f32_e64 s[40:41], s74, v246
	v_cmp_gt_f32_e64 s[42:43], s74, v247
	v_cndmask_b32_e64 v192, 0, 32, vcc
	v_cndmask_b32_e64 v193, 0, 32, s[34:35]
	v_cndmask_b32_e64 v196, 0, 32, s[40:41]
	v_cndmask_b32_e64 v197, 0, 32, s[42:43]
	v_cndmask_b32_e64 v188, 0, v171, vcc
	v_cndmask_b32_e64 v189, 0, v171, s[34:35]
	v_cndmask_b32_e64 v190, 0, v171, s[40:41]
	v_cndmask_b32_e64 v191, 0, v171, s[42:43]
	v_ldexp_f32 v244, v244, v192
	v_ldexp_f32 v245, v245, v193
	v_ldexp_f32 v246, v246, v196
	v_ldexp_f32 v247, v247, v197
	v_log_f32_e32 v244, v244
	v_log_f32_e32 v245, v245
	v_log_f32_e32 v246, v246
	v_log_f32_e32 v247, v247
	v_mul_f32_e32 v248, 0x3f317217, v244
	v_mul_f32_e32 v249, 0x3f317217, v245
	v_mul_f32_e32 v250, 0x3f317217, v246
	v_mul_f32_e32 v251, 0x3f317217, v247
	v_fma_f32 v192, v244, s75, -v248
	v_fma_f32 v193, v245, s75, -v249
	v_fma_f32 v196, v246, s75, -v250
	v_fma_f32 v197, v247, s75, -v251
	v_fmac_f32_e32 v192, 0x3377d1cf, v244
	v_fmac_f32_e32 v193, 0x3377d1cf, v245
	v_fmac_f32_e32 v196, 0x3377d1cf, v246
	v_fmac_f32_e32 v197, 0x3377d1cf, v247
	v_fmac_f32_e32 v192, 0x3f317217, v244
	v_fmac_f32_e32 v193, 0x3f317217, v245
	v_fmac_f32_e32 v196, 0x3f317217, v246
	v_fmac_f32_e32 v197, 0x3f317217, v247
	v_cmp_lt_f32_e64 vcc, |v244|, s76
	v_cmp_lt_f32_e64 s[34:35], |v245|, s76
	v_cmp_lt_f32_e64 s[40:41], |v246|, s76
	v_cmp_lt_f32_e64 s[42:43], |v247|, s76
	v_cndmask_b32_e64 v244, v244, v192, vcc
	v_cndmask_b32_e64 v245, v245, v193, s[34:35]
	v_cndmask_b32_e64 v246, v246, v196, s[40:41]
	v_cndmask_b32_e64 v247, v247, v197, s[42:43]
	v_sub_f32_e32 v118, v244, v188
	v_sub_f32_e32 v119, v245, v189
	v_sub_f32_e32 v120, v246, v190
	v_sub_f32_e32 v121, v247, v191
	v_mul_f32_e32 v244, 0xbfb8aa3b, v114
	v_mul_f32_e32 v245, 0xbfb8aa3b, v115
	v_mul_f32_e32 v246, 0xbfb8aa3b, v116
	v_mul_f32_e32 v247, 0xbfb8aa3b, v117
	v_exp_f32_e32 v244, v244
	v_exp_f32_e32 v245, v245
	v_exp_f32_e32 v246, v246
	v_exp_f32_e32 v247, v247
	v_sub_f32_e32 v248, 1.0, v184
	v_sub_f32_e32 v249, 1.0, v185
	v_sub_f32_e32 v250, 1.0, v186
	v_sub_f32_e32 v251, 1.0, v187
	v_add_f32_e32 v244, 1.0, v244
	v_add_f32_e32 v245, 1.0, v245
	v_add_f32_e32 v246, 1.0, v246
	v_add_f32_e32 v247, 1.0, v247
	v_rcp_f32_e32 v244, v244
	v_rcp_f32_e32 v245, v245
	v_rcp_f32_e32 v246, v246
	v_rcp_f32_e32 v247, v247
	v_fma_f32 v244, v244, v248, v184
	v_fma_f32 v245, v245, v249, v185
	v_fma_f32 v246, v246, v250, v186
	v_fma_f32 v247, v247, v251, v187
	v_cmp_gt_f32_e64 vcc, s74, v244
	v_cmp_gt_f32_e64 s[34:35], s74, v245
	v_cmp_gt_f32_e64 s[40:41], s74, v246
	v_cmp_gt_f32_e64 s[42:43], s74, v247
	v_cndmask_b32_e64 v192, 0, 32, vcc
	v_cndmask_b32_e64 v193, 0, 32, s[34:35]
	v_cndmask_b32_e64 v196, 0, 32, s[40:41]
	v_cndmask_b32_e64 v197, 0, 32, s[42:43]
	v_cndmask_b32_e64 v188, 0, v171, vcc
	v_cndmask_b32_e64 v189, 0, v171, s[34:35]
	v_cndmask_b32_e64 v190, 0, v171, s[40:41]
	v_cndmask_b32_e64 v191, 0, v171, s[42:43]
	v_ldexp_f32 v244, v244, v192
	v_ldexp_f32 v245, v245, v193
	v_ldexp_f32 v246, v246, v196
	v_ldexp_f32 v247, v247, v197
	v_log_f32_e32 v244, v244
	v_log_f32_e32 v245, v245
	v_log_f32_e32 v246, v246
	v_log_f32_e32 v247, v247
	v_mul_f32_e32 v248, 0x3f317217, v244
	v_mul_f32_e32 v249, 0x3f317217, v245
	v_mul_f32_e32 v250, 0x3f317217, v246
	v_mul_f32_e32 v251, 0x3f317217, v247
	v_fma_f32 v192, v244, s75, -v248
	v_fma_f32 v193, v245, s75, -v249
	v_fma_f32 v196, v246, s75, -v250
	v_fma_f32 v197, v247, s75, -v251
	v_fmac_f32_e32 v192, 0x3377d1cf, v244
	v_fmac_f32_e32 v193, 0x3377d1cf, v245
	v_fmac_f32_e32 v196, 0x3377d1cf, v246
	v_fmac_f32_e32 v197, 0x3377d1cf, v247
	v_fmac_f32_e32 v192, 0x3f317217, v244
	v_fmac_f32_e32 v193, 0x3f317217, v245
	v_fmac_f32_e32 v196, 0x3f317217, v246
	v_fmac_f32_e32 v197, 0x3f317217, v247
	v_cmp_lt_f32_e64 vcc, |v244|, s76
	v_cmp_lt_f32_e64 s[34:35], |v245|, s76
	v_cmp_lt_f32_e64 s[40:41], |v246|, s76
	v_cmp_lt_f32_e64 s[42:43], |v247|, s76
	v_cndmask_b32_e64 v244, v244, v192, vcc
	v_cndmask_b32_e64 v245, v245, v193, s[34:35]
	v_cndmask_b32_e64 v246, v246, v196, s[40:41]
	v_cndmask_b32_e64 v247, v247, v197, s[42:43]
	v_sub_f32_e32 v114, v244, v188
	v_sub_f32_e32 v115, v245, v189
	v_sub_f32_e32 v116, v246, v190
	v_sub_f32_e32 v117, v247, v191
	v_cvt_pk_bf16_f32 v118, v118, v119
	v_cvt_pk_bf16_f32 v119, v120, v121
	v_cvt_pk_bf16_f32 v120, v114, v115
	v_cvt_pk_bf16_f32 v121, v116, v117
	global_store_dwordx4 v[164:165], v[118:121], off offset:256
	v_lshl_add_u64 v[164:165], v[164:165], 0, s[8:9]
	v_mul_f32_e32 v244, 0xbfb8aa3b, v110
	v_mul_f32_e32 v245, 0xbfb8aa3b, v111
	v_mul_f32_e32 v246, 0xbfb8aa3b, v112
	v_mul_f32_e32 v247, 0xbfb8aa3b, v113
	v_exp_f32_e32 v244, v244
	v_exp_f32_e32 v245, v245
	v_exp_f32_e32 v246, v246
	v_exp_f32_e32 v247, v247
	v_sub_f32_e32 v248, 1.0, v172
	v_sub_f32_e32 v249, 1.0, v173
	v_sub_f32_e32 v250, 1.0, v174
	v_sub_f32_e32 v251, 1.0, v175
	v_add_f32_e32 v244, 1.0, v244
	v_add_f32_e32 v245, 1.0, v245
	v_add_f32_e32 v246, 1.0, v246
	v_add_f32_e32 v247, 1.0, v247
	v_rcp_f32_e32 v244, v244
	v_rcp_f32_e32 v245, v245
	v_rcp_f32_e32 v246, v246
	v_rcp_f32_e32 v247, v247
	v_fma_f32 v244, v244, v248, v172
	v_fma_f32 v245, v245, v249, v173
	v_fma_f32 v246, v246, v250, v174
	v_fma_f32 v247, v247, v251, v175
	v_cmp_gt_f32_e64 vcc, s74, v244
	v_cmp_gt_f32_e64 s[34:35], s74, v245
	v_cmp_gt_f32_e64 s[40:41], s74, v246
	v_cmp_gt_f32_e64 s[42:43], s74, v247
	v_cndmask_b32_e64 v192, 0, 32, vcc
	v_cndmask_b32_e64 v193, 0, 32, s[34:35]
	v_cndmask_b32_e64 v196, 0, 32, s[40:41]
	v_cndmask_b32_e64 v197, 0, 32, s[42:43]
	v_cndmask_b32_e64 v188, 0, v171, vcc
	v_cndmask_b32_e64 v189, 0, v171, s[34:35]
	v_cndmask_b32_e64 v190, 0, v171, s[40:41]
	v_cndmask_b32_e64 v191, 0, v171, s[42:43]
	v_ldexp_f32 v244, v244, v192
	v_ldexp_f32 v245, v245, v193
	v_ldexp_f32 v246, v246, v196
	v_ldexp_f32 v247, v247, v197
	v_log_f32_e32 v244, v244
	v_log_f32_e32 v245, v245
	v_log_f32_e32 v246, v246
	v_log_f32_e32 v247, v247
	v_mul_f32_e32 v248, 0x3f317217, v244
	v_mul_f32_e32 v249, 0x3f317217, v245
	v_mul_f32_e32 v250, 0x3f317217, v246
	v_mul_f32_e32 v251, 0x3f317217, v247
	v_fma_f32 v192, v244, s75, -v248
	v_fma_f32 v193, v245, s75, -v249
	v_fma_f32 v196, v246, s75, -v250
	v_fma_f32 v197, v247, s75, -v251
	v_fmac_f32_e32 v192, 0x3377d1cf, v244
	v_fmac_f32_e32 v193, 0x3377d1cf, v245
	v_fmac_f32_e32 v196, 0x3377d1cf, v246
	v_fmac_f32_e32 v197, 0x3377d1cf, v247
	v_fmac_f32_e32 v192, 0x3f317217, v244
	v_fmac_f32_e32 v193, 0x3f317217, v245
	v_fmac_f32_e32 v196, 0x3f317217, v246
	v_fmac_f32_e32 v197, 0x3f317217, v247
	v_cmp_lt_f32_e64 vcc, |v244|, s76
	v_cmp_lt_f32_e64 s[34:35], |v245|, s76
	v_cmp_lt_f32_e64 s[40:41], |v246|, s76
	v_cmp_lt_f32_e64 s[42:43], |v247|, s76
	v_cndmask_b32_e64 v244, v244, v192, vcc
	v_cndmask_b32_e64 v245, v245, v193, s[34:35]
	v_cndmask_b32_e64 v246, v246, v196, s[40:41]
	v_cndmask_b32_e64 v247, v247, v197, s[42:43]
	v_sub_f32_e32 v110, v244, v188
	v_sub_f32_e32 v111, v245, v189
	v_sub_f32_e32 v112, v246, v190
	v_sub_f32_e32 v113, v247, v191
	v_mul_f32_e32 v244, 0xbfb8aa3b, v106
	v_mul_f32_e32 v245, 0xbfb8aa3b, v107
	v_mul_f32_e32 v246, 0xbfb8aa3b, v108
	v_mul_f32_e32 v247, 0xbfb8aa3b, v109
	v_exp_f32_e32 v244, v244
	v_exp_f32_e32 v245, v245
	v_exp_f32_e32 v246, v246
	v_exp_f32_e32 v247, v247
	v_sub_f32_e32 v248, 1.0, v176
	v_sub_f32_e32 v249, 1.0, v177
	v_sub_f32_e32 v250, 1.0, v178
	v_sub_f32_e32 v251, 1.0, v179
	v_add_f32_e32 v244, 1.0, v244
	v_add_f32_e32 v245, 1.0, v245
	v_add_f32_e32 v246, 1.0, v246
	v_add_f32_e32 v247, 1.0, v247
	v_rcp_f32_e32 v244, v244
	v_rcp_f32_e32 v245, v245
	v_rcp_f32_e32 v246, v246
	v_rcp_f32_e32 v247, v247
	v_fma_f32 v244, v244, v248, v176
	v_fma_f32 v245, v245, v249, v177
	v_fma_f32 v246, v246, v250, v178
	v_fma_f32 v247, v247, v251, v179
	v_cmp_gt_f32_e64 vcc, s74, v244
	v_cmp_gt_f32_e64 s[34:35], s74, v245
	v_cmp_gt_f32_e64 s[40:41], s74, v246
	v_cmp_gt_f32_e64 s[42:43], s74, v247
	v_cndmask_b32_e64 v192, 0, 32, vcc
	v_cndmask_b32_e64 v193, 0, 32, s[34:35]
	v_cndmask_b32_e64 v196, 0, 32, s[40:41]
	v_cndmask_b32_e64 v197, 0, 32, s[42:43]
	v_cndmask_b32_e64 v188, 0, v171, vcc
	v_cndmask_b32_e64 v189, 0, v171, s[34:35]
	v_cndmask_b32_e64 v190, 0, v171, s[40:41]
	v_cndmask_b32_e64 v191, 0, v171, s[42:43]
	v_ldexp_f32 v244, v244, v192
	v_ldexp_f32 v245, v245, v193
	v_ldexp_f32 v246, v246, v196
	v_ldexp_f32 v247, v247, v197
	v_log_f32_e32 v244, v244
	v_log_f32_e32 v245, v245
	v_log_f32_e32 v246, v246
	v_log_f32_e32 v247, v247
	v_mul_f32_e32 v248, 0x3f317217, v244
	v_mul_f32_e32 v249, 0x3f317217, v245
	v_mul_f32_e32 v250, 0x3f317217, v246
	v_mul_f32_e32 v251, 0x3f317217, v247
	v_fma_f32 v192, v244, s75, -v248
	v_fma_f32 v193, v245, s75, -v249
	v_fma_f32 v196, v246, s75, -v250
	v_fma_f32 v197, v247, s75, -v251
	v_fmac_f32_e32 v192, 0x3377d1cf, v244
	v_fmac_f32_e32 v193, 0x3377d1cf, v245
	v_fmac_f32_e32 v196, 0x3377d1cf, v246
	v_fmac_f32_e32 v197, 0x3377d1cf, v247
	v_fmac_f32_e32 v192, 0x3f317217, v244
	v_fmac_f32_e32 v193, 0x3f317217, v245
	v_fmac_f32_e32 v196, 0x3f317217, v246
	v_fmac_f32_e32 v197, 0x3f317217, v247
	v_cmp_lt_f32_e64 vcc, |v244|, s76
	v_cmp_lt_f32_e64 s[34:35], |v245|, s76
	v_cmp_lt_f32_e64 s[40:41], |v246|, s76
	v_cmp_lt_f32_e64 s[42:43], |v247|, s76
	v_cndmask_b32_e64 v244, v244, v192, vcc
	v_cndmask_b32_e64 v245, v245, v193, s[34:35]
	v_cndmask_b32_e64 v246, v246, v196, s[40:41]
	v_cndmask_b32_e64 v247, v247, v197, s[42:43]
	v_sub_f32_e32 v106, v244, v188
	v_sub_f32_e32 v107, v245, v189
	v_sub_f32_e32 v108, v246, v190
	v_sub_f32_e32 v109, v247, v191
	v_cvt_pk_bf16_f32 v110, v110, v111
	v_cvt_pk_bf16_f32 v111, v112, v113
	v_cvt_pk_bf16_f32 v112, v106, v107
	v_cvt_pk_bf16_f32 v113, v108, v109
	global_store_dwordx4 v[164:165], v[110:113], off
	v_mul_f32_e32 v244, 0xbfb8aa3b, v102
	v_mul_f32_e32 v245, 0xbfb8aa3b, v103
	v_mul_f32_e32 v246, 0xbfb8aa3b, v104
	v_mul_f32_e32 v247, 0xbfb8aa3b, v105
	v_exp_f32_e32 v244, v244
	v_exp_f32_e32 v245, v245
	v_exp_f32_e32 v246, v246
	v_exp_f32_e32 v247, v247
	v_sub_f32_e32 v248, 1.0, v180
	v_sub_f32_e32 v249, 1.0, v181
	v_sub_f32_e32 v250, 1.0, v182
	v_sub_f32_e32 v251, 1.0, v183
	v_add_f32_e32 v244, 1.0, v244
	v_add_f32_e32 v245, 1.0, v245
	v_add_f32_e32 v246, 1.0, v246
	v_add_f32_e32 v247, 1.0, v247
	v_rcp_f32_e32 v244, v244
	v_rcp_f32_e32 v245, v245
	v_rcp_f32_e32 v246, v246
	v_rcp_f32_e32 v247, v247
	v_fma_f32 v244, v244, v248, v180
	v_fma_f32 v245, v245, v249, v181
	v_fma_f32 v246, v246, v250, v182
	v_fma_f32 v247, v247, v251, v183
	v_cmp_gt_f32_e64 vcc, s74, v244
	v_cmp_gt_f32_e64 s[34:35], s74, v245
	v_cmp_gt_f32_e64 s[40:41], s74, v246
	v_cmp_gt_f32_e64 s[42:43], s74, v247
	v_cndmask_b32_e64 v192, 0, 32, vcc
	v_cndmask_b32_e64 v193, 0, 32, s[34:35]
	v_cndmask_b32_e64 v196, 0, 32, s[40:41]
	v_cndmask_b32_e64 v197, 0, 32, s[42:43]
	v_cndmask_b32_e64 v188, 0, v171, vcc
	v_cndmask_b32_e64 v189, 0, v171, s[34:35]
	v_cndmask_b32_e64 v190, 0, v171, s[40:41]
	v_cndmask_b32_e64 v191, 0, v171, s[42:43]
	v_ldexp_f32 v244, v244, v192
	v_ldexp_f32 v245, v245, v193
	v_ldexp_f32 v246, v246, v196
	v_ldexp_f32 v247, v247, v197
	v_log_f32_e32 v244, v244
	v_log_f32_e32 v245, v245
	v_log_f32_e32 v246, v246
	v_log_f32_e32 v247, v247
	v_mul_f32_e32 v248, 0x3f317217, v244
	v_mul_f32_e32 v249, 0x3f317217, v245
	v_mul_f32_e32 v250, 0x3f317217, v246
	v_mul_f32_e32 v251, 0x3f317217, v247
	v_fma_f32 v192, v244, s75, -v248
	v_fma_f32 v193, v245, s75, -v249
	v_fma_f32 v196, v246, s75, -v250
	v_fma_f32 v197, v247, s75, -v251
	v_fmac_f32_e32 v192, 0x3377d1cf, v244
	v_fmac_f32_e32 v193, 0x3377d1cf, v245
	v_fmac_f32_e32 v196, 0x3377d1cf, v246
	v_fmac_f32_e32 v197, 0x3377d1cf, v247
	v_fmac_f32_e32 v192, 0x3f317217, v244
	v_fmac_f32_e32 v193, 0x3f317217, v245
	v_fmac_f32_e32 v196, 0x3f317217, v246
	v_fmac_f32_e32 v197, 0x3f317217, v247
	v_cmp_lt_f32_e64 vcc, |v244|, s76
	v_cmp_lt_f32_e64 s[34:35], |v245|, s76
	v_cmp_lt_f32_e64 s[40:41], |v246|, s76
	v_cmp_lt_f32_e64 s[42:43], |v247|, s76
	v_cndmask_b32_e64 v244, v244, v192, vcc
	v_cndmask_b32_e64 v245, v245, v193, s[34:35]
	v_cndmask_b32_e64 v246, v246, v196, s[40:41]
	v_cndmask_b32_e64 v247, v247, v197, s[42:43]
	v_sub_f32_e32 v102, v244, v188
	v_sub_f32_e32 v103, v245, v189
	v_sub_f32_e32 v104, v246, v190
	v_sub_f32_e32 v105, v247, v191
	v_mul_f32_e32 v244, 0xbfb8aa3b, v98
	v_mul_f32_e32 v245, 0xbfb8aa3b, v99
	v_mul_f32_e32 v246, 0xbfb8aa3b, v100
	v_mul_f32_e32 v247, 0xbfb8aa3b, v101
	v_exp_f32_e32 v244, v244
	v_exp_f32_e32 v245, v245
	v_exp_f32_e32 v246, v246
	v_exp_f32_e32 v247, v247
	v_sub_f32_e32 v248, 1.0, v184
	v_sub_f32_e32 v249, 1.0, v185
	v_sub_f32_e32 v250, 1.0, v186
	v_sub_f32_e32 v251, 1.0, v187
	v_add_f32_e32 v244, 1.0, v244
	v_add_f32_e32 v245, 1.0, v245
	v_add_f32_e32 v246, 1.0, v246
	v_add_f32_e32 v247, 1.0, v247
	v_rcp_f32_e32 v244, v244
	v_rcp_f32_e32 v245, v245
	v_rcp_f32_e32 v246, v246
	v_rcp_f32_e32 v247, v247
	v_fma_f32 v244, v244, v248, v184
	v_fma_f32 v245, v245, v249, v185
	v_fma_f32 v246, v246, v250, v186
	v_fma_f32 v247, v247, v251, v187
	v_cmp_gt_f32_e64 vcc, s74, v244
	v_cmp_gt_f32_e64 s[34:35], s74, v245
	v_cmp_gt_f32_e64 s[40:41], s74, v246
	v_cmp_gt_f32_e64 s[42:43], s74, v247
	v_cndmask_b32_e64 v192, 0, 32, vcc
	v_cndmask_b32_e64 v193, 0, 32, s[34:35]
	v_cndmask_b32_e64 v196, 0, 32, s[40:41]
	v_cndmask_b32_e64 v197, 0, 32, s[42:43]
	v_cndmask_b32_e64 v188, 0, v171, vcc
	v_cndmask_b32_e64 v189, 0, v171, s[34:35]
	v_cndmask_b32_e64 v190, 0, v171, s[40:41]
	v_cndmask_b32_e64 v191, 0, v171, s[42:43]
	v_ldexp_f32 v244, v244, v192
	v_ldexp_f32 v245, v245, v193
	v_ldexp_f32 v246, v246, v196
	v_ldexp_f32 v247, v247, v197
	v_log_f32_e32 v244, v244
	v_log_f32_e32 v245, v245
	v_log_f32_e32 v246, v246
	v_log_f32_e32 v247, v247
	v_mul_f32_e32 v248, 0x3f317217, v244
	v_mul_f32_e32 v249, 0x3f317217, v245
	v_mul_f32_e32 v250, 0x3f317217, v246
	v_mul_f32_e32 v251, 0x3f317217, v247
	v_fma_f32 v192, v244, s75, -v248
	v_fma_f32 v193, v245, s75, -v249
	v_fma_f32 v196, v246, s75, -v250
	v_fma_f32 v197, v247, s75, -v251
	v_fmac_f32_e32 v192, 0x3377d1cf, v244
	v_fmac_f32_e32 v193, 0x3377d1cf, v245
	v_fmac_f32_e32 v196, 0x3377d1cf, v246
	v_fmac_f32_e32 v197, 0x3377d1cf, v247
	v_fmac_f32_e32 v192, 0x3f317217, v244
	v_fmac_f32_e32 v193, 0x3f317217, v245
	v_fmac_f32_e32 v196, 0x3f317217, v246
	v_fmac_f32_e32 v197, 0x3f317217, v247
	v_cmp_lt_f32_e64 vcc, |v244|, s76
	v_cmp_lt_f32_e64 s[34:35], |v245|, s76
	v_cmp_lt_f32_e64 s[40:41], |v246|, s76
	v_cmp_lt_f32_e64 s[42:43], |v247|, s76
	v_cndmask_b32_e64 v244, v244, v192, vcc
	v_cndmask_b32_e64 v245, v245, v193, s[34:35]
	v_cndmask_b32_e64 v246, v246, v196, s[40:41]
	v_cndmask_b32_e64 v247, v247, v197, s[42:43]
	v_sub_f32_e32 v98, v244, v188
	v_sub_f32_e32 v99, v245, v189
	v_sub_f32_e32 v100, v246, v190
	v_sub_f32_e32 v101, v247, v191
	v_cvt_pk_bf16_f32 v102, v102, v103
	v_cvt_pk_bf16_f32 v103, v104, v105
	v_cvt_pk_bf16_f32 v104, v98, v99
	v_cvt_pk_bf16_f32 v105, v100, v101
	global_store_dwordx4 v[164:165], v[102:105], off offset:256
	v_lshl_add_u64 v[164:165], v[164:165], 0, s[8:9]
	v_mul_f32_e32 v244, 0xbfb8aa3b, v94
	v_mul_f32_e32 v245, 0xbfb8aa3b, v95
	v_mul_f32_e32 v246, 0xbfb8aa3b, v96
	v_mul_f32_e32 v247, 0xbfb8aa3b, v97
	v_exp_f32_e32 v244, v244
	v_exp_f32_e32 v245, v245
	v_exp_f32_e32 v246, v246
	v_exp_f32_e32 v247, v247
	v_sub_f32_e32 v248, 1.0, v172
	v_sub_f32_e32 v249, 1.0, v173
	v_sub_f32_e32 v250, 1.0, v174
	v_sub_f32_e32 v251, 1.0, v175
	v_add_f32_e32 v244, 1.0, v244
	v_add_f32_e32 v245, 1.0, v245
	v_add_f32_e32 v246, 1.0, v246
	v_add_f32_e32 v247, 1.0, v247
	v_rcp_f32_e32 v244, v244
	v_rcp_f32_e32 v245, v245
	v_rcp_f32_e32 v246, v246
	v_rcp_f32_e32 v247, v247
	v_fma_f32 v244, v244, v248, v172
	v_fma_f32 v245, v245, v249, v173
	v_fma_f32 v246, v246, v250, v174
	v_fma_f32 v247, v247, v251, v175
	v_cmp_gt_f32_e64 vcc, s74, v244
	v_cmp_gt_f32_e64 s[34:35], s74, v245
	v_cmp_gt_f32_e64 s[40:41], s74, v246
	v_cmp_gt_f32_e64 s[42:43], s74, v247
	v_cndmask_b32_e64 v192, 0, 32, vcc
	v_cndmask_b32_e64 v193, 0, 32, s[34:35]
	v_cndmask_b32_e64 v196, 0, 32, s[40:41]
	v_cndmask_b32_e64 v197, 0, 32, s[42:43]
	v_cndmask_b32_e64 v188, 0, v171, vcc
	v_cndmask_b32_e64 v189, 0, v171, s[34:35]
	v_cndmask_b32_e64 v190, 0, v171, s[40:41]
	v_cndmask_b32_e64 v191, 0, v171, s[42:43]
	v_ldexp_f32 v244, v244, v192
	v_ldexp_f32 v245, v245, v193
	v_ldexp_f32 v246, v246, v196
	v_ldexp_f32 v247, v247, v197
	v_log_f32_e32 v244, v244
	v_log_f32_e32 v245, v245
	v_log_f32_e32 v246, v246
	v_log_f32_e32 v247, v247
	v_mul_f32_e32 v248, 0x3f317217, v244
	v_mul_f32_e32 v249, 0x3f317217, v245
	v_mul_f32_e32 v250, 0x3f317217, v246
	v_mul_f32_e32 v251, 0x3f317217, v247
	v_fma_f32 v192, v244, s75, -v248
	v_fma_f32 v193, v245, s75, -v249
	v_fma_f32 v196, v246, s75, -v250
	v_fma_f32 v197, v247, s75, -v251
	v_fmac_f32_e32 v192, 0x3377d1cf, v244
	v_fmac_f32_e32 v193, 0x3377d1cf, v245
	v_fmac_f32_e32 v196, 0x3377d1cf, v246
	v_fmac_f32_e32 v197, 0x3377d1cf, v247
	v_fmac_f32_e32 v192, 0x3f317217, v244
	v_fmac_f32_e32 v193, 0x3f317217, v245
	v_fmac_f32_e32 v196, 0x3f317217, v246
	v_fmac_f32_e32 v197, 0x3f317217, v247
	v_cmp_lt_f32_e64 vcc, |v244|, s76
	v_cmp_lt_f32_e64 s[34:35], |v245|, s76
	v_cmp_lt_f32_e64 s[40:41], |v246|, s76
	v_cmp_lt_f32_e64 s[42:43], |v247|, s76
	v_cndmask_b32_e64 v244, v244, v192, vcc
	v_cndmask_b32_e64 v245, v245, v193, s[34:35]
	v_cndmask_b32_e64 v246, v246, v196, s[40:41]
	v_cndmask_b32_e64 v247, v247, v197, s[42:43]
	v_sub_f32_e32 v94, v244, v188
	v_sub_f32_e32 v95, v245, v189
	v_sub_f32_e32 v96, v246, v190
	v_sub_f32_e32 v97, v247, v191
	v_mul_f32_e32 v244, 0xbfb8aa3b, v90
	v_mul_f32_e32 v245, 0xbfb8aa3b, v91
	v_mul_f32_e32 v246, 0xbfb8aa3b, v92
	v_mul_f32_e32 v247, 0xbfb8aa3b, v93
	v_exp_f32_e32 v244, v244
	v_exp_f32_e32 v245, v245
	v_exp_f32_e32 v246, v246
	v_exp_f32_e32 v247, v247
	v_sub_f32_e32 v248, 1.0, v176
	v_sub_f32_e32 v249, 1.0, v177
	v_sub_f32_e32 v250, 1.0, v178
	v_sub_f32_e32 v251, 1.0, v179
	v_add_f32_e32 v244, 1.0, v244
	v_add_f32_e32 v245, 1.0, v245
	v_add_f32_e32 v246, 1.0, v246
	v_add_f32_e32 v247, 1.0, v247
	v_rcp_f32_e32 v244, v244
	v_rcp_f32_e32 v245, v245
	v_rcp_f32_e32 v246, v246
	v_rcp_f32_e32 v247, v247
	v_fma_f32 v244, v244, v248, v176
	v_fma_f32 v245, v245, v249, v177
	v_fma_f32 v246, v246, v250, v178
	v_fma_f32 v247, v247, v251, v179
	v_cmp_gt_f32_e64 vcc, s74, v244
	v_cmp_gt_f32_e64 s[34:35], s74, v245
	v_cmp_gt_f32_e64 s[40:41], s74, v246
	v_cmp_gt_f32_e64 s[42:43], s74, v247
	v_cndmask_b32_e64 v192, 0, 32, vcc
	v_cndmask_b32_e64 v193, 0, 32, s[34:35]
	v_cndmask_b32_e64 v196, 0, 32, s[40:41]
	v_cndmask_b32_e64 v197, 0, 32, s[42:43]
	v_cndmask_b32_e64 v188, 0, v171, vcc
	v_cndmask_b32_e64 v189, 0, v171, s[34:35]
	v_cndmask_b32_e64 v190, 0, v171, s[40:41]
	v_cndmask_b32_e64 v191, 0, v171, s[42:43]
	v_ldexp_f32 v244, v244, v192
	v_ldexp_f32 v245, v245, v193
	v_ldexp_f32 v246, v246, v196
	v_ldexp_f32 v247, v247, v197
	v_log_f32_e32 v244, v244
	v_log_f32_e32 v245, v245
	v_log_f32_e32 v246, v246
	v_log_f32_e32 v247, v247
	v_mul_f32_e32 v248, 0x3f317217, v244
	v_mul_f32_e32 v249, 0x3f317217, v245
	v_mul_f32_e32 v250, 0x3f317217, v246
	v_mul_f32_e32 v251, 0x3f317217, v247
	v_fma_f32 v192, v244, s75, -v248
	v_fma_f32 v193, v245, s75, -v249
	v_fma_f32 v196, v246, s75, -v250
	v_fma_f32 v197, v247, s75, -v251
	v_fmac_f32_e32 v192, 0x3377d1cf, v244
	v_fmac_f32_e32 v193, 0x3377d1cf, v245
	v_fmac_f32_e32 v196, 0x3377d1cf, v246
	v_fmac_f32_e32 v197, 0x3377d1cf, v247
	v_fmac_f32_e32 v192, 0x3f317217, v244
	v_fmac_f32_e32 v193, 0x3f317217, v245
	v_fmac_f32_e32 v196, 0x3f317217, v246
	v_fmac_f32_e32 v197, 0x3f317217, v247
	v_cmp_lt_f32_e64 vcc, |v244|, s76
	v_cmp_lt_f32_e64 s[34:35], |v245|, s76
	v_cmp_lt_f32_e64 s[40:41], |v246|, s76
	v_cmp_lt_f32_e64 s[42:43], |v247|, s76
	v_cndmask_b32_e64 v244, v244, v192, vcc
	v_cndmask_b32_e64 v245, v245, v193, s[34:35]
	v_cndmask_b32_e64 v246, v246, v196, s[40:41]
	v_cndmask_b32_e64 v247, v247, v197, s[42:43]
	v_sub_f32_e32 v90, v244, v188
	v_sub_f32_e32 v91, v245, v189
	v_sub_f32_e32 v92, v246, v190
	v_sub_f32_e32 v93, v247, v191
	v_cvt_pk_bf16_f32 v94, v94, v95
	v_cvt_pk_bf16_f32 v95, v96, v97
	v_cvt_pk_bf16_f32 v96, v90, v91
	v_cvt_pk_bf16_f32 v97, v92, v93
	global_store_dwordx4 v[164:165], v[94:97], off
	v_mul_f32_e32 v244, 0xbfb8aa3b, v86
	v_mul_f32_e32 v245, 0xbfb8aa3b, v87
	v_mul_f32_e32 v246, 0xbfb8aa3b, v88
	v_mul_f32_e32 v247, 0xbfb8aa3b, v89
	v_exp_f32_e32 v244, v244
	v_exp_f32_e32 v245, v245
	v_exp_f32_e32 v246, v246
	v_exp_f32_e32 v247, v247
	v_sub_f32_e32 v248, 1.0, v180
	v_sub_f32_e32 v249, 1.0, v181
	v_sub_f32_e32 v250, 1.0, v182
	v_sub_f32_e32 v251, 1.0, v183
	v_add_f32_e32 v244, 1.0, v244
	v_add_f32_e32 v245, 1.0, v245
	v_add_f32_e32 v246, 1.0, v246
	v_add_f32_e32 v247, 1.0, v247
	v_rcp_f32_e32 v244, v244
	v_rcp_f32_e32 v245, v245
	v_rcp_f32_e32 v246, v246
	v_rcp_f32_e32 v247, v247
	v_fma_f32 v244, v244, v248, v180
	v_fma_f32 v245, v245, v249, v181
	v_fma_f32 v246, v246, v250, v182
	v_fma_f32 v247, v247, v251, v183
	v_cmp_gt_f32_e64 vcc, s74, v244
	v_cmp_gt_f32_e64 s[34:35], s74, v245
	v_cmp_gt_f32_e64 s[40:41], s74, v246
	v_cmp_gt_f32_e64 s[42:43], s74, v247
	v_cndmask_b32_e64 v192, 0, 32, vcc
	v_cndmask_b32_e64 v193, 0, 32, s[34:35]
	v_cndmask_b32_e64 v196, 0, 32, s[40:41]
	v_cndmask_b32_e64 v197, 0, 32, s[42:43]
	v_cndmask_b32_e64 v188, 0, v171, vcc
	v_cndmask_b32_e64 v189, 0, v171, s[34:35]
	v_cndmask_b32_e64 v190, 0, v171, s[40:41]
	v_cndmask_b32_e64 v191, 0, v171, s[42:43]
	v_ldexp_f32 v244, v244, v192
	v_ldexp_f32 v245, v245, v193
	v_ldexp_f32 v246, v246, v196
	v_ldexp_f32 v247, v247, v197
	v_log_f32_e32 v244, v244
	v_log_f32_e32 v245, v245
	v_log_f32_e32 v246, v246
	v_log_f32_e32 v247, v247
	v_mul_f32_e32 v248, 0x3f317217, v244
	v_mul_f32_e32 v249, 0x3f317217, v245
	v_mul_f32_e32 v250, 0x3f317217, v246
	v_mul_f32_e32 v251, 0x3f317217, v247
	v_fma_f32 v192, v244, s75, -v248
	v_fma_f32 v193, v245, s75, -v249
	v_fma_f32 v196, v246, s75, -v250
	v_fma_f32 v197, v247, s75, -v251
	v_fmac_f32_e32 v192, 0x3377d1cf, v244
	v_fmac_f32_e32 v193, 0x3377d1cf, v245
	v_fmac_f32_e32 v196, 0x3377d1cf, v246
	v_fmac_f32_e32 v197, 0x3377d1cf, v247
	v_fmac_f32_e32 v192, 0x3f317217, v244
	v_fmac_f32_e32 v193, 0x3f317217, v245
	v_fmac_f32_e32 v196, 0x3f317217, v246
	v_fmac_f32_e32 v197, 0x3f317217, v247
	v_cmp_lt_f32_e64 vcc, |v244|, s76
	v_cmp_lt_f32_e64 s[34:35], |v245|, s76
	v_cmp_lt_f32_e64 s[40:41], |v246|, s76
	v_cmp_lt_f32_e64 s[42:43], |v247|, s76
	v_cndmask_b32_e64 v244, v244, v192, vcc
	v_cndmask_b32_e64 v245, v245, v193, s[34:35]
	v_cndmask_b32_e64 v246, v246, v196, s[40:41]
	v_cndmask_b32_e64 v247, v247, v197, s[42:43]
	v_sub_f32_e32 v86, v244, v188
	v_sub_f32_e32 v87, v245, v189
	v_sub_f32_e32 v88, v246, v190
	v_sub_f32_e32 v89, v247, v191
	v_mul_f32_e32 v244, 0xbfb8aa3b, v82
	v_mul_f32_e32 v245, 0xbfb8aa3b, v83
	v_mul_f32_e32 v246, 0xbfb8aa3b, v84
	v_mul_f32_e32 v247, 0xbfb8aa3b, v85
	v_exp_f32_e32 v244, v244
	v_exp_f32_e32 v245, v245
	v_exp_f32_e32 v246, v246
	v_exp_f32_e32 v247, v247
	v_sub_f32_e32 v248, 1.0, v184
	v_sub_f32_e32 v249, 1.0, v185
	v_sub_f32_e32 v250, 1.0, v186
	v_sub_f32_e32 v251, 1.0, v187
	v_add_f32_e32 v244, 1.0, v244
	v_add_f32_e32 v245, 1.0, v245
	v_add_f32_e32 v246, 1.0, v246
	v_add_f32_e32 v247, 1.0, v247
	v_rcp_f32_e32 v244, v244
	v_rcp_f32_e32 v245, v245
	v_rcp_f32_e32 v246, v246
	v_rcp_f32_e32 v247, v247
	v_fma_f32 v244, v244, v248, v184
	v_fma_f32 v245, v245, v249, v185
	v_fma_f32 v246, v246, v250, v186
	v_fma_f32 v247, v247, v251, v187
	v_cmp_gt_f32_e64 vcc, s74, v244
	v_cmp_gt_f32_e64 s[34:35], s74, v245
	v_cmp_gt_f32_e64 s[40:41], s74, v246
	v_cmp_gt_f32_e64 s[42:43], s74, v247
	v_cndmask_b32_e64 v192, 0, 32, vcc
	v_cndmask_b32_e64 v193, 0, 32, s[34:35]
	v_cndmask_b32_e64 v196, 0, 32, s[40:41]
	v_cndmask_b32_e64 v197, 0, 32, s[42:43]
	v_cndmask_b32_e64 v188, 0, v171, vcc
	v_cndmask_b32_e64 v189, 0, v171, s[34:35]
	v_cndmask_b32_e64 v190, 0, v171, s[40:41]
	v_cndmask_b32_e64 v191, 0, v171, s[42:43]
	v_ldexp_f32 v244, v244, v192
	v_ldexp_f32 v245, v245, v193
	v_ldexp_f32 v246, v246, v196
	v_ldexp_f32 v247, v247, v197
	v_log_f32_e32 v244, v244
	v_log_f32_e32 v245, v245
	v_log_f32_e32 v246, v246
	v_log_f32_e32 v247, v247
	v_mul_f32_e32 v248, 0x3f317217, v244
	v_mul_f32_e32 v249, 0x3f317217, v245
	v_mul_f32_e32 v250, 0x3f317217, v246
	v_mul_f32_e32 v251, 0x3f317217, v247
	v_fma_f32 v192, v244, s75, -v248
	v_fma_f32 v193, v245, s75, -v249
	v_fma_f32 v196, v246, s75, -v250
	v_fma_f32 v197, v247, s75, -v251
	v_fmac_f32_e32 v192, 0x3377d1cf, v244
	v_fmac_f32_e32 v193, 0x3377d1cf, v245
	v_fmac_f32_e32 v196, 0x3377d1cf, v246
	v_fmac_f32_e32 v197, 0x3377d1cf, v247
	v_fmac_f32_e32 v192, 0x3f317217, v244
	v_fmac_f32_e32 v193, 0x3f317217, v245
	v_fmac_f32_e32 v196, 0x3f317217, v246
	v_fmac_f32_e32 v197, 0x3f317217, v247
	v_cmp_lt_f32_e64 vcc, |v244|, s76
	v_cmp_lt_f32_e64 s[34:35], |v245|, s76
	v_cmp_lt_f32_e64 s[40:41], |v246|, s76
	v_cmp_lt_f32_e64 s[42:43], |v247|, s76
	v_cndmask_b32_e64 v244, v244, v192, vcc
	v_cndmask_b32_e64 v245, v245, v193, s[34:35]
	v_cndmask_b32_e64 v246, v246, v196, s[40:41]
	v_cndmask_b32_e64 v247, v247, v197, s[42:43]
	v_sub_f32_e32 v82, v244, v188
	v_sub_f32_e32 v83, v245, v189
	v_sub_f32_e32 v84, v246, v190
	v_sub_f32_e32 v85, v247, v191
	v_cvt_pk_bf16_f32 v86, v86, v87
	v_cvt_pk_bf16_f32 v87, v88, v89
	v_cvt_pk_bf16_f32 v88, v82, v83
	v_cvt_pk_bf16_f32 v89, v84, v85
	global_store_dwordx4 v[164:165], v[86:89], off offset:256
	v_lshl_add_u64 v[164:165], v[164:165], 0, s[8:9]
	v_mul_f32_e32 v244, 0xbfb8aa3b, v78
	v_mul_f32_e32 v245, 0xbfb8aa3b, v79
	v_mul_f32_e32 v246, 0xbfb8aa3b, v80
	v_mul_f32_e32 v247, 0xbfb8aa3b, v81
	v_exp_f32_e32 v244, v244
	v_exp_f32_e32 v245, v245
	v_exp_f32_e32 v246, v246
	v_exp_f32_e32 v247, v247
	v_sub_f32_e32 v248, 1.0, v172
	v_sub_f32_e32 v249, 1.0, v173
	v_sub_f32_e32 v250, 1.0, v174
	v_sub_f32_e32 v251, 1.0, v175
	v_add_f32_e32 v244, 1.0, v244
	v_add_f32_e32 v245, 1.0, v245
	v_add_f32_e32 v246, 1.0, v246
	v_add_f32_e32 v247, 1.0, v247
	v_rcp_f32_e32 v244, v244
	v_rcp_f32_e32 v245, v245
	v_rcp_f32_e32 v246, v246
	v_rcp_f32_e32 v247, v247
	v_fma_f32 v244, v244, v248, v172
	v_fma_f32 v245, v245, v249, v173
	v_fma_f32 v246, v246, v250, v174
	v_fma_f32 v247, v247, v251, v175
	v_cmp_gt_f32_e64 vcc, s74, v244
	v_cmp_gt_f32_e64 s[34:35], s74, v245
	v_cmp_gt_f32_e64 s[40:41], s74, v246
	v_cmp_gt_f32_e64 s[42:43], s74, v247
	v_cndmask_b32_e64 v192, 0, 32, vcc
	v_cndmask_b32_e64 v193, 0, 32, s[34:35]
	v_cndmask_b32_e64 v196, 0, 32, s[40:41]
	v_cndmask_b32_e64 v197, 0, 32, s[42:43]
	v_cndmask_b32_e64 v188, 0, v171, vcc
	v_cndmask_b32_e64 v189, 0, v171, s[34:35]
	v_cndmask_b32_e64 v190, 0, v171, s[40:41]
	v_cndmask_b32_e64 v191, 0, v171, s[42:43]
	v_ldexp_f32 v244, v244, v192
	v_ldexp_f32 v245, v245, v193
	v_ldexp_f32 v246, v246, v196
	v_ldexp_f32 v247, v247, v197
	v_log_f32_e32 v244, v244
	v_log_f32_e32 v245, v245
	v_log_f32_e32 v246, v246
	v_log_f32_e32 v247, v247
	v_mul_f32_e32 v248, 0x3f317217, v244
	v_mul_f32_e32 v249, 0x3f317217, v245
	v_mul_f32_e32 v250, 0x3f317217, v246
	v_mul_f32_e32 v251, 0x3f317217, v247
	v_fma_f32 v192, v244, s75, -v248
	v_fma_f32 v193, v245, s75, -v249
	v_fma_f32 v196, v246, s75, -v250
	v_fma_f32 v197, v247, s75, -v251
	v_fmac_f32_e32 v192, 0x3377d1cf, v244
	v_fmac_f32_e32 v193, 0x3377d1cf, v245
	v_fmac_f32_e32 v196, 0x3377d1cf, v246
	v_fmac_f32_e32 v197, 0x3377d1cf, v247
	v_fmac_f32_e32 v192, 0x3f317217, v244
	v_fmac_f32_e32 v193, 0x3f317217, v245
	v_fmac_f32_e32 v196, 0x3f317217, v246
	v_fmac_f32_e32 v197, 0x3f317217, v247
	v_cmp_lt_f32_e64 vcc, |v244|, s76
	v_cmp_lt_f32_e64 s[34:35], |v245|, s76
	v_cmp_lt_f32_e64 s[40:41], |v246|, s76
	v_cmp_lt_f32_e64 s[42:43], |v247|, s76
	v_cndmask_b32_e64 v244, v244, v192, vcc
	v_cndmask_b32_e64 v245, v245, v193, s[34:35]
	v_cndmask_b32_e64 v246, v246, v196, s[40:41]
	v_cndmask_b32_e64 v247, v247, v197, s[42:43]
	v_sub_f32_e32 v78, v244, v188
	v_sub_f32_e32 v79, v245, v189
	v_sub_f32_e32 v80, v246, v190
	v_sub_f32_e32 v81, v247, v191
	v_mul_f32_e32 v244, 0xbfb8aa3b, v74
	v_mul_f32_e32 v245, 0xbfb8aa3b, v75
	v_mul_f32_e32 v246, 0xbfb8aa3b, v76
	v_mul_f32_e32 v247, 0xbfb8aa3b, v77
	v_exp_f32_e32 v244, v244
	v_exp_f32_e32 v245, v245
	v_exp_f32_e32 v246, v246
	v_exp_f32_e32 v247, v247
	v_sub_f32_e32 v248, 1.0, v176
	v_sub_f32_e32 v249, 1.0, v177
	v_sub_f32_e32 v250, 1.0, v178
	v_sub_f32_e32 v251, 1.0, v179
	v_add_f32_e32 v244, 1.0, v244
	v_add_f32_e32 v245, 1.0, v245
	v_add_f32_e32 v246, 1.0, v246
	v_add_f32_e32 v247, 1.0, v247
	v_rcp_f32_e32 v244, v244
	v_rcp_f32_e32 v245, v245
	v_rcp_f32_e32 v246, v246
	v_rcp_f32_e32 v247, v247
	v_fma_f32 v244, v244, v248, v176
	v_fma_f32 v245, v245, v249, v177
	v_fma_f32 v246, v246, v250, v178
	v_fma_f32 v247, v247, v251, v179
	v_cmp_gt_f32_e64 vcc, s74, v244
	v_cmp_gt_f32_e64 s[34:35], s74, v245
	v_cmp_gt_f32_e64 s[40:41], s74, v246
	v_cmp_gt_f32_e64 s[42:43], s74, v247
	v_cndmask_b32_e64 v192, 0, 32, vcc
	v_cndmask_b32_e64 v193, 0, 32, s[34:35]
	v_cndmask_b32_e64 v196, 0, 32, s[40:41]
	v_cndmask_b32_e64 v197, 0, 32, s[42:43]
	v_cndmask_b32_e64 v188, 0, v171, vcc
	v_cndmask_b32_e64 v189, 0, v171, s[34:35]
	v_cndmask_b32_e64 v190, 0, v171, s[40:41]
	v_cndmask_b32_e64 v191, 0, v171, s[42:43]
	v_ldexp_f32 v244, v244, v192
	v_ldexp_f32 v245, v245, v193
	v_ldexp_f32 v246, v246, v196
	v_ldexp_f32 v247, v247, v197
	v_log_f32_e32 v244, v244
	v_log_f32_e32 v245, v245
	v_log_f32_e32 v246, v246
	v_log_f32_e32 v247, v247
	v_mul_f32_e32 v248, 0x3f317217, v244
	v_mul_f32_e32 v249, 0x3f317217, v245
	v_mul_f32_e32 v250, 0x3f317217, v246
	v_mul_f32_e32 v251, 0x3f317217, v247
	v_fma_f32 v192, v244, s75, -v248
	v_fma_f32 v193, v245, s75, -v249
	v_fma_f32 v196, v246, s75, -v250
	v_fma_f32 v197, v247, s75, -v251
	v_fmac_f32_e32 v192, 0x3377d1cf, v244
	v_fmac_f32_e32 v193, 0x3377d1cf, v245
	v_fmac_f32_e32 v196, 0x3377d1cf, v246
	v_fmac_f32_e32 v197, 0x3377d1cf, v247
	v_fmac_f32_e32 v192, 0x3f317217, v244
	v_fmac_f32_e32 v193, 0x3f317217, v245
	v_fmac_f32_e32 v196, 0x3f317217, v246
	v_fmac_f32_e32 v197, 0x3f317217, v247
	v_cmp_lt_f32_e64 vcc, |v244|, s76
	v_cmp_lt_f32_e64 s[34:35], |v245|, s76
	v_cmp_lt_f32_e64 s[40:41], |v246|, s76
	v_cmp_lt_f32_e64 s[42:43], |v247|, s76
	v_cndmask_b32_e64 v244, v244, v192, vcc
	v_cndmask_b32_e64 v245, v245, v193, s[34:35]
	v_cndmask_b32_e64 v246, v246, v196, s[40:41]
	v_cndmask_b32_e64 v247, v247, v197, s[42:43]
	v_sub_f32_e32 v74, v244, v188
	v_sub_f32_e32 v75, v245, v189
	v_sub_f32_e32 v76, v246, v190
	v_sub_f32_e32 v77, v247, v191
	v_cvt_pk_bf16_f32 v78, v78, v79
	v_cvt_pk_bf16_f32 v79, v80, v81
	v_cvt_pk_bf16_f32 v80, v74, v75
	v_cvt_pk_bf16_f32 v81, v76, v77
	global_store_dwordx4 v[164:165], v[78:81], off
	v_mul_f32_e32 v244, 0xbfb8aa3b, v70
	v_mul_f32_e32 v245, 0xbfb8aa3b, v71
	v_mul_f32_e32 v246, 0xbfb8aa3b, v72
	v_mul_f32_e32 v247, 0xbfb8aa3b, v73
	v_exp_f32_e32 v244, v244
	v_exp_f32_e32 v245, v245
	v_exp_f32_e32 v246, v246
	v_exp_f32_e32 v247, v247
	v_sub_f32_e32 v248, 1.0, v180
	v_sub_f32_e32 v249, 1.0, v181
	v_sub_f32_e32 v250, 1.0, v182
	v_sub_f32_e32 v251, 1.0, v183
	v_add_f32_e32 v244, 1.0, v244
	v_add_f32_e32 v245, 1.0, v245
	v_add_f32_e32 v246, 1.0, v246
	v_add_f32_e32 v247, 1.0, v247
	v_rcp_f32_e32 v244, v244
	v_rcp_f32_e32 v245, v245
	v_rcp_f32_e32 v246, v246
	v_rcp_f32_e32 v247, v247
	v_fma_f32 v244, v244, v248, v180
	v_fma_f32 v245, v245, v249, v181
	v_fma_f32 v246, v246, v250, v182
	v_fma_f32 v247, v247, v251, v183
	v_cmp_gt_f32_e64 vcc, s74, v244
	v_cmp_gt_f32_e64 s[34:35], s74, v245
	v_cmp_gt_f32_e64 s[40:41], s74, v246
	v_cmp_gt_f32_e64 s[42:43], s74, v247
	v_cndmask_b32_e64 v192, 0, 32, vcc
	v_cndmask_b32_e64 v193, 0, 32, s[34:35]
	v_cndmask_b32_e64 v196, 0, 32, s[40:41]
	v_cndmask_b32_e64 v197, 0, 32, s[42:43]
	v_cndmask_b32_e64 v188, 0, v171, vcc
	v_cndmask_b32_e64 v189, 0, v171, s[34:35]
	v_cndmask_b32_e64 v190, 0, v171, s[40:41]
	v_cndmask_b32_e64 v191, 0, v171, s[42:43]
	v_ldexp_f32 v244, v244, v192
	v_ldexp_f32 v245, v245, v193
	v_ldexp_f32 v246, v246, v196
	v_ldexp_f32 v247, v247, v197
	v_log_f32_e32 v244, v244
	v_log_f32_e32 v245, v245
	v_log_f32_e32 v246, v246
	v_log_f32_e32 v247, v247
	v_mul_f32_e32 v248, 0x3f317217, v244
	v_mul_f32_e32 v249, 0x3f317217, v245
	v_mul_f32_e32 v250, 0x3f317217, v246
	v_mul_f32_e32 v251, 0x3f317217, v247
	v_fma_f32 v192, v244, s75, -v248
	v_fma_f32 v193, v245, s75, -v249
	v_fma_f32 v196, v246, s75, -v250
	v_fma_f32 v197, v247, s75, -v251
	v_fmac_f32_e32 v192, 0x3377d1cf, v244
	v_fmac_f32_e32 v193, 0x3377d1cf, v245
	v_fmac_f32_e32 v196, 0x3377d1cf, v246
	v_fmac_f32_e32 v197, 0x3377d1cf, v247
	v_fmac_f32_e32 v192, 0x3f317217, v244
	v_fmac_f32_e32 v193, 0x3f317217, v245
	v_fmac_f32_e32 v196, 0x3f317217, v246
	v_fmac_f32_e32 v197, 0x3f317217, v247
	v_cmp_lt_f32_e64 vcc, |v244|, s76
	v_cmp_lt_f32_e64 s[34:35], |v245|, s76
	v_cmp_lt_f32_e64 s[40:41], |v246|, s76
	v_cmp_lt_f32_e64 s[42:43], |v247|, s76
	v_cndmask_b32_e64 v244, v244, v192, vcc
	v_cndmask_b32_e64 v245, v245, v193, s[34:35]
	v_cndmask_b32_e64 v246, v246, v196, s[40:41]
	v_cndmask_b32_e64 v247, v247, v197, s[42:43]
	v_sub_f32_e32 v70, v244, v188
	v_sub_f32_e32 v71, v245, v189
	v_sub_f32_e32 v72, v246, v190
	v_sub_f32_e32 v73, v247, v191
	v_mul_f32_e32 v244, 0xbfb8aa3b, v2
	v_mul_f32_e32 v245, 0xbfb8aa3b, v3
	v_mul_f32_e32 v246, 0xbfb8aa3b, v4
	v_mul_f32_e32 v247, 0xbfb8aa3b, v5
	v_exp_f32_e32 v244, v244
	v_exp_f32_e32 v245, v245
	v_exp_f32_e32 v246, v246
	v_exp_f32_e32 v247, v247
	v_sub_f32_e32 v248, 1.0, v184
	v_sub_f32_e32 v249, 1.0, v185
	v_sub_f32_e32 v250, 1.0, v186
	v_sub_f32_e32 v251, 1.0, v187
	v_add_f32_e32 v244, 1.0, v244
	v_add_f32_e32 v245, 1.0, v245
	v_add_f32_e32 v246, 1.0, v246
	v_add_f32_e32 v247, 1.0, v247
	v_rcp_f32_e32 v244, v244
	v_rcp_f32_e32 v245, v245
	v_rcp_f32_e32 v246, v246
	v_rcp_f32_e32 v247, v247
	v_fma_f32 v244, v244, v248, v184
	v_fma_f32 v245, v245, v249, v185
	v_fma_f32 v246, v246, v250, v186
	v_fma_f32 v247, v247, v251, v187
	v_cmp_gt_f32_e64 vcc, s74, v244
	v_cmp_gt_f32_e64 s[34:35], s74, v245
	v_cmp_gt_f32_e64 s[40:41], s74, v246
	v_cmp_gt_f32_e64 s[42:43], s74, v247
	v_cndmask_b32_e64 v192, 0, 32, vcc
	v_cndmask_b32_e64 v193, 0, 32, s[34:35]
	v_cndmask_b32_e64 v196, 0, 32, s[40:41]
	v_cndmask_b32_e64 v197, 0, 32, s[42:43]
	v_cndmask_b32_e64 v188, 0, v171, vcc
	v_cndmask_b32_e64 v189, 0, v171, s[34:35]
	v_cndmask_b32_e64 v190, 0, v171, s[40:41]
	v_cndmask_b32_e64 v191, 0, v171, s[42:43]
	v_ldexp_f32 v244, v244, v192
	v_ldexp_f32 v245, v245, v193
	v_ldexp_f32 v246, v246, v196
	v_ldexp_f32 v247, v247, v197
	v_log_f32_e32 v244, v244
	v_log_f32_e32 v245, v245
	v_log_f32_e32 v246, v246
	v_log_f32_e32 v247, v247
	v_mul_f32_e32 v248, 0x3f317217, v244
	v_mul_f32_e32 v249, 0x3f317217, v245
	v_mul_f32_e32 v250, 0x3f317217, v246
	v_mul_f32_e32 v251, 0x3f317217, v247
	v_fma_f32 v192, v244, s75, -v248
	v_fma_f32 v193, v245, s75, -v249
	v_fma_f32 v196, v246, s75, -v250
	v_fma_f32 v197, v247, s75, -v251
	v_fmac_f32_e32 v192, 0x3377d1cf, v244
	v_fmac_f32_e32 v193, 0x3377d1cf, v245
	v_fmac_f32_e32 v196, 0x3377d1cf, v246
	v_fmac_f32_e32 v197, 0x3377d1cf, v247
	v_fmac_f32_e32 v192, 0x3f317217, v244
	v_fmac_f32_e32 v193, 0x3f317217, v245
	v_fmac_f32_e32 v196, 0x3f317217, v246
	v_fmac_f32_e32 v197, 0x3f317217, v247
	v_cmp_lt_f32_e64 vcc, |v244|, s76
	v_cmp_lt_f32_e64 s[34:35], |v245|, s76
	v_cmp_lt_f32_e64 s[40:41], |v246|, s76
	v_cmp_lt_f32_e64 s[42:43], |v247|, s76
	v_cndmask_b32_e64 v244, v244, v192, vcc
	v_cndmask_b32_e64 v245, v245, v193, s[34:35]
	v_cndmask_b32_e64 v246, v246, v196, s[40:41]
	v_cndmask_b32_e64 v247, v247, v197, s[42:43]
	v_sub_f32_e32 v2, v244, v188
	v_sub_f32_e32 v3, v245, v189
	v_sub_f32_e32 v4, v246, v190
	v_sub_f32_e32 v5, v247, v191
	v_cvt_pk_bf16_f32 v70, v70, v71
	v_cvt_pk_bf16_f32 v71, v72, v73
	v_cvt_pk_bf16_f32 v72, v2, v3
	v_cvt_pk_bf16_f32 v73, v4, v5
	global_store_dwordx4 v[164:165], v[70:73], off offset:256
.Lodd_done:
.LBB0_3444:
	s_andn2_b64 vcc, exec, s[6:7]
	s_mov_b64 s[6:7], -1
	s_cbranch_vccnz .LBB0_1858
